# sync trims: duplicate lgkmcnt(0) waits dropped from the GEMM K-loop MFMA segments; unit-closing barrier dropped in the GLA summary and GLA output loops
# speedup vs baseline: 1.0045x; 1.0045x over previous
; #define LDA(dst, b, h) for (int m = 0; m < 4; ++m) for (int k = 0; k < 2; ++k) \
;     dst[m][k] = *reinterpret_cast<const bf16x8*>((char*)SA(b, h) + lds_byte(wr * 64 + m * 16 + fr, k * 32 + fq * 8))
; #define LDB(dst, b, h) for (int n = 0; n < 2; ++n) for (int k = 0; k < 2; ++k) \
;     dst[n][k] = *reinterpret_cast<const bf16x8*>((char*)SB(b, h) + lds_byte(wc * 32 + n * 16 + fr, k * 32 + fq * 8))
; #define MMA(ai, bj, At, Bq) do { __builtin_amdgcn_s_setprio(1); \
;     for (int m = 0; m < 4; ++m) for (int n = 0; n < 2; ++n) for (int k = 0; k < 2; ++k) \
;       acc[ai][bj][m][n] = __builtin_amdgcn_mfma_f32_16x16x32_bf16(At[m][k], Bq[n][k], acc[ai][bj][m][n], 0, 0, 0); \
;     __builtin_amdgcn_s_setprio(0); } while (0)
; #define WAIT_L(n) asm volatile("s_waitcnt lgkmcnt(" #n ")" ::: "memory")
; #define BAR __builtin_amdgcn_s_barrier()
; #define SCHED __builtin_amdgcn_sched_barrier(0)
; template <class Epi>
; __device__ __forceinline__ void gemm_tile(const u16* __restrict__ A, const u16* __restrict__ Bt, int K,
;                                           int brow, int bcol, bool first, bool has_next, int nbrow, int nbcol, Epi epi) {
;     ...
;     LDB(B0, 0, 0); SCHED; LDA(At, 0, 0); STAGE(SA(1, 1), A, brow + HALF, t + 1);
;     WAIT_L(8); BAR; WAIT_L(0); MMA(0, 0, At, B0); BAR; SCHED;
;     LDB(B1, 0, 1); STAGE(SB(0, 0), Bt, bcol, t + 2);
;     BAR; WAIT_L(0); MMA(0, 1, At, B1); BAR;
;     LDA(At, 0, 1); STAGE(SA(0, 0), A, brow, t + 2);
;     BAR; WAIT_L(0); MMA(1, 0, At, B0); BAR; SCHED;
.LBB0_143:
	ds_read_b128 v[166:169], v150
	ds_read_b128 v[174:177], v150 offset:1024
	ds_read_b128 v[178:181], v150 offset:2048
	ds_read_b128 v[182:185], v150 offset:3072
	v_add_u32_e32 v151, 0xc000, v157
	v_lshl_add_u64 v[170:171], s[6:7], 0, v[142:143]
	v_readfirstlane_b32 s8, v151
	v_lshl_add_u64 v[172:173], v[170:171], 0, s[20:21]
	s_mov_b32 m0, s8
	ds_read_b128 v[186:189], v162
	ds_read_b128 v[190:193], v162 offset:1024
	ds_read_b128 v[194:197], v161
	ds_read_b128 v[198:201], v161 offset:1024
	ds_read_b128 v[202:205], v160
	ds_read_b128 v[206:209], v160 offset:1024
	ds_read_b128 v[210:213], v159
	ds_read_b128 v[214:217], v159 offset:1024
	global_load_lds_dwordx4 v[172:173], off
	v_add_u32_e32 v173, 0xe000, v157
	v_lshl_add_u64 v[222:223], s[6:7], 0, v[144:145]
	v_readfirstlane_b32 s8, v173
	v_lshl_add_u64 v[218:219], v[222:223], 0, s[20:21]
	s_mov_b32 m0, s8
	s_nop 0
	global_load_lds_dwordx4 v[218:219], off
	s_waitcnt lgkmcnt(8)
	s_barrier
	s_waitcnt lgkmcnt(0)
	s_setprio 1
	v_mfma_f32_16x16x32_bf16 v[124:127], v[186:189], v[166:169], v[124:127]
	v_mfma_f32_16x16x32_bf16 v[120:123], v[186:189], v[178:181], v[120:123]
	v_mfma_f32_16x16x32_bf16 v[116:119], v[194:197], v[166:169], v[116:119]
	v_mfma_f32_16x16x32_bf16 v[112:115], v[194:197], v[178:181], v[112:115]
	v_mfma_f32_16x16x32_bf16 v[108:111], v[202:205], v[166:169], v[108:111]
	v_mfma_f32_16x16x32_bf16 v[104:107], v[202:205], v[178:181], v[104:107]
	v_mfma_f32_16x16x32_bf16 v[100:103], v[210:213], v[166:169], v[100:103]
	v_mfma_f32_16x16x32_bf16 v[96:99], v[210:213], v[178:181], v[96:99]
	v_mfma_f32_16x16x32_bf16 v[124:127], v[190:193], v[174:177], v[124:127]
	v_mfma_f32_16x16x32_bf16 v[120:123], v[190:193], v[182:185], v[120:123]
	v_mfma_f32_16x16x32_bf16 v[116:119], v[198:201], v[174:177], v[116:119]
	v_mfma_f32_16x16x32_bf16 v[112:115], v[198:201], v[182:185], v[112:115]
	v_mfma_f32_16x16x32_bf16 v[108:111], v[206:209], v[174:177], v[108:111]
	v_mfma_f32_16x16x32_bf16 v[104:107], v[206:209], v[182:185], v[104:107]
	v_mfma_f32_16x16x32_bf16 v[100:103], v[214:217], v[174:177], v[100:103]
	v_mfma_f32_16x16x32_bf16 v[96:99], v[214:217], v[182:185], v[96:99]
	s_setprio 0
	s_barrier
	v_lshl_add_u64 v[246:247], s[6:7], 0, v[128:129]
	v_readfirstlane_b32 s8, v158
	v_add_u32_e32 v163, 0x2000, v158
	v_lshl_add_u64 v[242:243], v[246:247], 0, s[22:23]
	s_mov_b32 m0, s8
	v_lshl_add_u64 v[248:249], s[6:7], 0, v[130:131]
	v_readfirstlane_b32 s8, v163
	ds_read_b128 v[218:221], v149
	ds_read_b128 v[230:233], v149 offset:1024
	ds_read_b128 v[234:237], v149 offset:2048
	ds_read_b128 v[238:241], v149 offset:3072
	global_load_lds_dwordx4 v[242:243], off
	v_lshl_add_u64 v[242:243], v[248:249], 0, s[22:23]
	s_mov_b32 m0, s8
	s_nop 0
	global_load_lds_dwordx4 v[242:243], off
	s_barrier
	s_waitcnt lgkmcnt(0)
	s_setprio 1
	v_mfma_f32_16x16x32_bf16 v[92:95], v[186:189], v[218:221], v[92:95]
	v_mfma_f32_16x16x32_bf16 v[88:91], v[186:189], v[234:237], v[88:91]
	v_mfma_f32_16x16x32_bf16 v[84:87], v[194:197], v[218:221], v[84:87]
	v_mfma_f32_16x16x32_bf16 v[80:83], v[194:197], v[234:237], v[80:83]
	v_mfma_f32_16x16x32_bf16 v[76:79], v[202:205], v[218:221], v[76:79]
	v_mfma_f32_16x16x32_bf16 v[72:75], v[202:205], v[234:237], v[72:75]
	v_mfma_f32_16x16x32_bf16 v[68:71], v[210:213], v[218:221], v[68:71]
	v_mfma_f32_16x16x32_bf16 v[64:67], v[210:213], v[234:237], v[64:67]
	v_mfma_f32_16x16x32_bf16 v[92:95], v[190:193], v[230:233], v[92:95]
	v_mfma_f32_16x16x32_bf16 v[88:91], v[190:193], v[238:241], v[88:91]
	v_mfma_f32_16x16x32_bf16 v[84:87], v[198:201], v[230:233], v[84:87]
	v_mfma_f32_16x16x32_bf16 v[80:83], v[198:201], v[238:241], v[80:83]
	v_mfma_f32_16x16x32_bf16 v[76:79], v[206:209], v[230:233], v[76:79]
	v_mfma_f32_16x16x32_bf16 v[72:75], v[206:209], v[238:241], v[72:75]
	v_mfma_f32_16x16x32_bf16 v[68:71], v[214:217], v[230:233], v[68:71]
	v_mfma_f32_16x16x32_bf16 v[64:67], v[214:217], v[238:241], v[64:67]
	s_setprio 0
	v_lshl_add_u64 v[250:251], s[6:7], 0, v[134:135]
	v_readfirstlane_b32 s8, v157
	v_lshl_add_u64 v[242:243], v[250:251], 0, s[24:25]
	s_mov_b32 m0, s8
	v_lshl_add_u64 v[252:253], s[6:7], 0, v[136:137]
	v_readfirstlane_b32 s8, v156
	s_barrier
	ds_read_b128 v[186:189], v162 offset:16384
	ds_read_b128 v[190:193], v162 offset:17408
	ds_read_b128 v[194:197], v161 offset:16384
	ds_read_b128 v[198:201], v161 offset:17408
	ds_read_b128 v[202:205], v160 offset:16384
	ds_read_b128 v[206:209], v160 offset:17408
	ds_read_b128 v[210:213], v159 offset:16384
	ds_read_b128 v[214:217], v159 offset:17408
	global_load_lds_dwordx4 v[242:243], off
	v_lshl_add_u64 v[242:243], v[252:253], 0, s[24:25]
	s_mov_b32 m0, s8
	s_nop 0
	global_load_lds_dwordx4 v[242:243], off
	s_barrier
	s_waitcnt lgkmcnt(0)
	s_setprio 1
	v_mfma_f32_16x16x32_bf16 v[60:63], v[186:189], v[166:169], v[60:63]
	v_mfma_f32_16x16x32_bf16 v[56:59], v[186:189], v[178:181], v[56:59]
	v_mfma_f32_16x16x32_bf16 v[52:55], v[194:197], v[166:169], v[52:55]
	v_mfma_f32_16x16x32_bf16 v[48:51], v[194:197], v[178:181], v[48:51]
	v_mfma_f32_16x16x32_bf16 v[44:47], v[202:205], v[166:169], v[44:47]
	v_mfma_f32_16x16x32_bf16 v[40:43], v[202:205], v[178:181], v[40:43]
	v_mfma_f32_16x16x32_bf16 v[36:39], v[210:213], v[166:169], v[36:39]
	v_mfma_f32_16x16x32_bf16 v[32:35], v[210:213], v[178:181], v[32:35]
	v_mfma_f32_16x16x32_bf16 v[60:63], v[190:193], v[174:177], v[60:63]
	v_mfma_f32_16x16x32_bf16 v[56:59], v[190:193], v[182:185], v[56:59]
	v_mfma_f32_16x16x32_bf16 v[52:55], v[198:201], v[174:177], v[52:55]
	v_mfma_f32_16x16x32_bf16 v[48:51], v[198:201], v[182:185], v[48:51]
	v_mfma_f32_16x16x32_bf16 v[44:47], v[206:209], v[174:177], v[44:47]
	v_mfma_f32_16x16x32_bf16 v[40:43], v[206:209], v[182:185], v[40:43]
	v_mfma_f32_16x16x32_bf16 v[36:39], v[214:217], v[174:177], v[36:39]
	v_mfma_f32_16x16x32_bf16 v[32:35], v[214:217], v[182:185], v[32:35]
	s_setprio 0
	s_barrier
; #define LDA(dst, b, h) for (int m = 0; m < 4; ++m) for (int k = 0; k < 2; ++k) \
;     dst[m][k] = *reinterpret_cast<const bf16x8*>((char*)SA(b, h) + lds_byte(wr * 64 + m * 16 + fr, k * 32 + fq * 8))
; #define LDB(dst, b, h) for (int n = 0; n < 2; ++n) for (int k = 0; k < 2; ++k) \
;     dst[n][k] = *reinterpret_cast<const bf16x8*>((char*)SB(b, h) + lds_byte(wc * 32 + n * 16 + fr, k * 32 + fq * 8))
; #define MMA(ai, bj, At, Bq) do { __builtin_amdgcn_s_setprio(1); \
;     for (int m = 0; m < 4; ++m) for (int n = 0; n < 2; ++n) for (int k = 0; k < 2; ++k) \
;       acc[ai][bj][m][n] = __builtin_amdgcn_mfma_f32_16x16x32_bf16(At[m][k], Bq[n][k], acc[ai][bj][m][n], 0, 0, 0); \
;     __builtin_amdgcn_s_setprio(0); } while (0)
; #define WAIT_V(n) asm volatile("s_waitcnt vmcnt(" #n ")" ::: "memory")
; #define WAIT_L(n) asm volatile("s_waitcnt lgkmcnt(" #n ")" ::: "memory")
; #define BAR __builtin_amdgcn_s_barrier()
; #define SCHED __builtin_amdgcn_sched_barrier(0)
; template <class Epi>
; __device__ __forceinline__ void gemm_tile(const u16* __restrict__ A, const u16* __restrict__ Bt, int K,
;                                           int brow, int bcol, bool first, bool has_next, int nbrow, int nbcol, Epi epi) {
;     ...
;     STAGE(SB(0, 1), Bt, bcol + HALF, t + 2);
;     WAIT_V(6); BAR; MMA(1, 1, At, B1); BAR;
;     LDB(B0, 1, 0); SCHED; LDA(At, 1, 0); STAGE(SA(0, 1), A, brow + HALF, t + 2);
;     WAIT_L(8); BAR; WAIT_L(0); MMA(0, 0, At, B0); BAR; SCHED;
;     LDB(B1, 1, 1); STAGE(SB(1, 0), Bt, bcol, t + 3);
;     BAR; WAIT_L(0); MMA(0, 1, At, B1); BAR;
	v_lshl_add_u64 v[228:229], s[6:7], 0, v[138:139]
	v_readfirstlane_b32 s8, v155
	v_lshl_add_u64 v[166:167], v[228:229], 0, s[22:23]
	s_mov_b32 m0, s8
	v_lshl_add_u64 v[224:225], s[6:7], 0, v[140:141]
	global_load_lds_dwordx4 v[166:167], off
	v_add_u32_e32 v166, 0x2000, v155
	v_lshl_add_u64 v[168:169], v[224:225], 0, s[22:23]
	v_readfirstlane_b32 s8, v166
	s_mov_b32 m0, s8
	s_nop 0
	global_load_lds_dwordx4 v[168:169], off
	s_waitcnt vmcnt(6)
	s_barrier
	s_setprio 1
	v_mfma_f32_16x16x32_bf16 v[28:31], v[186:189], v[218:221], v[28:31]
	v_mfma_f32_16x16x32_bf16 v[24:27], v[186:189], v[234:237], v[24:27]
	v_mfma_f32_16x16x32_bf16 v[20:23], v[194:197], v[218:221], v[20:23]
	v_mfma_f32_16x16x32_bf16 v[16:19], v[194:197], v[234:237], v[16:19]
	v_mfma_f32_16x16x32_bf16 v[12:15], v[202:205], v[218:221], v[12:15]
	v_mfma_f32_16x16x32_bf16 v[8:11], v[202:205], v[234:237], v[8:11]
	v_mfma_f32_16x16x32_bf16 v[4:7], v[210:213], v[218:221], v[4:7]
	v_mfma_f32_16x16x32_bf16 v[0:3], v[210:213], v[234:237], v[0:3]
	v_mfma_f32_16x16x32_bf16 v[28:31], v[190:193], v[230:233], v[28:31]
	v_mfma_f32_16x16x32_bf16 v[24:27], v[190:193], v[238:241], v[24:27]
	v_mfma_f32_16x16x32_bf16 v[20:23], v[198:201], v[230:233], v[20:23]
	v_mfma_f32_16x16x32_bf16 v[16:19], v[198:201], v[238:241], v[16:19]
	v_mfma_f32_16x16x32_bf16 v[12:15], v[206:209], v[230:233], v[12:15]
	v_mfma_f32_16x16x32_bf16 v[8:11], v[206:209], v[238:241], v[8:11]
	v_mfma_f32_16x16x32_bf16 v[4:7], v[214:217], v[230:233], v[4:7]
	v_mfma_f32_16x16x32_bf16 v[0:3], v[214:217], v[238:241], v[0:3]
	s_setprio 0
	s_barrier
	ds_read_b128 v[174:177], v148
	ds_read_b128 v[178:181], v148 offset:1024
	ds_read_b128 v[182:185], v148 offset:2048
	ds_read_b128 v[186:189], v148 offset:3072
	v_readfirstlane_b32 s8, v154
	v_lshl_add_u64 v[168:169], v[170:171], 0, s[24:25]
	s_mov_b32 m0, s8
	v_readfirstlane_b32 s8, v153
	ds_read_b128 v[190:193], v162 offset:32768
	ds_read_b128 v[194:197], v162 offset:33792
	ds_read_b128 v[198:201], v161 offset:32768
	ds_read_b128 v[202:205], v161 offset:33792
	ds_read_b128 v[206:209], v160 offset:32768
	ds_read_b128 v[210:213], v160 offset:33792
	ds_read_b128 v[214:217], v159 offset:32768
	ds_read_b128 v[218:221], v159 offset:33792
	global_load_lds_dwordx4 v[168:169], off
	v_lshl_add_u64 v[168:169], v[222:223], 0, s[24:25]
	s_mov_b32 m0, s8
	s_nop 0
	global_load_lds_dwordx4 v[168:169], off
	s_waitcnt lgkmcnt(8)
	s_barrier
	s_waitcnt lgkmcnt(0)
	s_setprio 1
	v_mfma_f32_16x16x32_bf16 v[124:127], v[190:193], v[174:177], v[124:127]
	v_mfma_f32_16x16x32_bf16 v[120:123], v[190:193], v[182:185], v[120:123]
	v_mfma_f32_16x16x32_bf16 v[116:119], v[198:201], v[174:177], v[116:119]
	v_mfma_f32_16x16x32_bf16 v[112:115], v[198:201], v[182:185], v[112:115]
	v_mfma_f32_16x16x32_bf16 v[108:111], v[206:209], v[174:177], v[108:111]
	v_mfma_f32_16x16x32_bf16 v[104:107], v[206:209], v[182:185], v[104:107]
	v_mfma_f32_16x16x32_bf16 v[100:103], v[214:217], v[174:177], v[100:103]
	v_mfma_f32_16x16x32_bf16 v[96:99], v[214:217], v[182:185], v[96:99]
	v_mfma_f32_16x16x32_bf16 v[124:127], v[194:197], v[178:181], v[124:127]
	v_mfma_f32_16x16x32_bf16 v[120:123], v[194:197], v[186:189], v[120:123]
	v_mfma_f32_16x16x32_bf16 v[116:119], v[202:205], v[178:181], v[116:119]
	v_mfma_f32_16x16x32_bf16 v[112:115], v[202:205], v[186:189], v[112:115]
	v_mfma_f32_16x16x32_bf16 v[108:111], v[210:213], v[178:181], v[108:111]
	v_mfma_f32_16x16x32_bf16 v[104:107], v[210:213], v[186:189], v[104:107]
	v_mfma_f32_16x16x32_bf16 v[100:103], v[218:221], v[178:181], v[100:103]
	v_mfma_f32_16x16x32_bf16 v[96:99], v[218:221], v[186:189], v[96:99]
	s_setprio 0
	s_barrier
	v_add_u32_e32 v167, s84, v146
	v_lshl_add_u64 v[168:169], v[246:247], 0, s[26:27]
	v_readfirstlane_b32 s8, v167
	s_mov_b32 m0, s8
	ds_read_b128 v[230:233], v147
	ds_read_b128 v[234:237], v147 offset:1024
	ds_read_b128 v[238:241], v147 offset:2048
	ds_read_b128 v[242:245], v147 offset:3072
	global_load_lds_dwordx4 v[168:169], off
	v_add_u32_e32 v168, 0x2000, v167
	v_lshl_add_u64 v[170:171], v[248:249], 0, s[26:27]
	v_readfirstlane_b32 s8, v168
	s_mov_b32 m0, s8
	s_nop 0
	global_load_lds_dwordx4 v[170:171], off
	s_barrier
	s_waitcnt lgkmcnt(0)
	s_setprio 1
	v_mfma_f32_16x16x32_bf16 v[92:95], v[190:193], v[230:233], v[92:95]
	v_mfma_f32_16x16x32_bf16 v[88:91], v[190:193], v[238:241], v[88:91]
	v_mfma_f32_16x16x32_bf16 v[84:87], v[198:201], v[230:233], v[84:87]
	v_mfma_f32_16x16x32_bf16 v[80:83], v[198:201], v[238:241], v[80:83]
	v_mfma_f32_16x16x32_bf16 v[76:79], v[206:209], v[230:233], v[76:79]
	v_mfma_f32_16x16x32_bf16 v[72:75], v[206:209], v[238:241], v[72:75]
	v_mfma_f32_16x16x32_bf16 v[68:71], v[214:217], v[230:233], v[68:71]
	v_mfma_f32_16x16x32_bf16 v[64:67], v[214:217], v[238:241], v[64:67]
	v_mfma_f32_16x16x32_bf16 v[92:95], v[194:197], v[234:237], v[92:95]
	v_mfma_f32_16x16x32_bf16 v[88:91], v[194:197], v[242:245], v[88:91]
	v_mfma_f32_16x16x32_bf16 v[84:87], v[202:205], v[234:237], v[84:87]
	v_mfma_f32_16x16x32_bf16 v[80:83], v[202:205], v[242:245], v[80:83]
	v_mfma_f32_16x16x32_bf16 v[76:79], v[210:213], v[234:237], v[76:79]
	v_mfma_f32_16x16x32_bf16 v[72:75], v[210:213], v[242:245], v[72:75]
	v_mfma_f32_16x16x32_bf16 v[68:71], v[218:221], v[234:237], v[68:71]
	v_mfma_f32_16x16x32_bf16 v[64:67], v[218:221], v[242:245], v[64:67]
	s_setprio 0
	v_add_u32_e32 v169, 0x8000, v157
	v_lshl_add_u64 v[170:171], v[250:251], 0, s[28:29]
	v_readfirstlane_b32 s8, v169
	s_mov_b32 m0, s8
	s_barrier
; #define LDA(dst, b, h) for (int m = 0; m < 4; ++m) for (int k = 0; k < 2; ++k) \
;     dst[m][k] = *reinterpret_cast<const bf16x8*>((char*)SA(b, h) + lds_byte(wr * 64 + m * 16 + fr, k * 32 + fq * 8))
; #define LDB(dst, b, h) for (int n = 0; n < 2; ++n) for (int k = 0; k < 2; ++k) \
;     dst[n][k] = *reinterpret_cast<const bf16x8*>((char*)SB(b, h) + lds_byte(wc * 32 + n * 16 + fr, k * 32 + fq * 8))
; #define MMA(ai, bj, At, Bq) do { __builtin_amdgcn_s_setprio(1); \
;     for (int m = 0; m < 4; ++m) for (int n = 0; n < 2; ++n) for (int k = 0; k < 2; ++k) \
;       acc[ai][bj][m][n] = __builtin_amdgcn_mfma_f32_16x16x32_bf16(At[m][k], Bq[n][k], acc[ai][bj][m][n], 0, 0, 0); \
;     __builtin_amdgcn_s_setprio(0); } while (0)
; #define WAIT_V(n) asm volatile("s_waitcnt vmcnt(" #n ")" ::: "memory")
; #define WAIT_L(n) asm volatile("s_waitcnt lgkmcnt(" #n ")" ::: "memory")
; #define BAR __builtin_amdgcn_s_barrier()
; #define SCHED __builtin_amdgcn_sched_barrier(0)
; template <class Epi>
; __device__ __forceinline__ void gemm_tile(const u16* __restrict__ A, const u16* __restrict__ Bt, int K,
;                                           int brow, int bcol, bool first, bool has_next, int nbrow, int nbcol, Epi epi) {
;     ...
;     LDA(At, 1, 1); STAGE(SA(1, 0), A, brow, t + 3);
;     BAR; WAIT_L(0); MMA(1, 0, At, B0); BAR; SCHED;
;     STAGE(SB(1, 1), Bt, bcol + HALF, t + 3);
;     WAIT_V(6); BAR; MMA(1, 1, At, B1); BAR;
;   }
;   { LDB(B0, 0, 0); LDA(At, 0, 0); STAGE(SA(1, 1), A, brow + HALF, nt - 1);
;     BAR; WAIT_L(0); MMA(0, 0, At, B0); BAR;
;     LDB(B1, 0, 1); BAR; WAIT_L(0); MMA(0, 1, At, B1); BAR;
;     LDA(At, 0, 1); WAIT_V(4); BAR; WAIT_L(0); MMA(1, 0, At, B0); MMA(1, 1, At, B1); BAR; }
	ds_read_b128 v[190:193], v162 offset:49152
	ds_read_b128 v[194:197], v162 offset:50176
	ds_read_b128 v[198:201], v161 offset:49152
	ds_read_b128 v[202:205], v161 offset:50176
	ds_read_b128 v[206:209], v160 offset:49152
	ds_read_b128 v[210:213], v160 offset:50176
	ds_read_b128 v[214:217], v159 offset:49152
	ds_read_b128 v[218:221], v159 offset:50176
	global_load_lds_dwordx4 v[170:171], off
	v_add_u32_e32 v170, 0xa000, v157
	v_lshl_add_u64 v[222:223], v[252:253], 0, s[28:29]
	v_readfirstlane_b32 s8, v170
	s_mov_b32 m0, s8
	s_nop 0
	global_load_lds_dwordx4 v[222:223], off
	s_barrier
	s_waitcnt lgkmcnt(0)
	s_setprio 1
	v_mfma_f32_16x16x32_bf16 v[60:63], v[190:193], v[174:177], v[60:63]
	v_mfma_f32_16x16x32_bf16 v[56:59], v[190:193], v[182:185], v[56:59]
	v_mfma_f32_16x16x32_bf16 v[52:55], v[198:201], v[174:177], v[52:55]
	v_mfma_f32_16x16x32_bf16 v[48:51], v[198:201], v[182:185], v[48:51]
	v_mfma_f32_16x16x32_bf16 v[44:47], v[206:209], v[174:177], v[44:47]
	v_mfma_f32_16x16x32_bf16 v[40:43], v[206:209], v[182:185], v[40:43]
	v_mfma_f32_16x16x32_bf16 v[36:39], v[214:217], v[174:177], v[36:39]
	v_mfma_f32_16x16x32_bf16 v[32:35], v[214:217], v[182:185], v[32:35]
	v_mfma_f32_16x16x32_bf16 v[60:63], v[194:197], v[178:181], v[60:63]
	v_mfma_f32_16x16x32_bf16 v[56:59], v[194:197], v[186:189], v[56:59]
	v_mfma_f32_16x16x32_bf16 v[52:55], v[202:205], v[178:181], v[52:55]
	v_mfma_f32_16x16x32_bf16 v[48:51], v[202:205], v[186:189], v[48:51]
	v_mfma_f32_16x16x32_bf16 v[44:47], v[210:213], v[178:181], v[44:47]
	v_mfma_f32_16x16x32_bf16 v[40:43], v[210:213], v[186:189], v[40:43]
	v_mfma_f32_16x16x32_bf16 v[36:39], v[218:221], v[178:181], v[36:39]
	v_mfma_f32_16x16x32_bf16 v[32:35], v[218:221], v[186:189], v[32:35]
	s_setprio 0
	s_barrier
	v_add_u32_e32 v171, s85, v146
	v_add_u32_e32 v172, 0x2000, v171
	v_readfirstlane_b32 s8, v171
	v_lshl_add_u64 v[174:175], v[228:229], 0, s[26:27]
	s_mov_b32 m0, s8
	v_readfirstlane_b32 s8, v172
	global_load_lds_dwordx4 v[174:175], off
	v_lshl_add_u64 v[174:175], v[224:225], 0, s[26:27]
	s_mov_b32 m0, s8
	s_nop 0
	global_load_lds_dwordx4 v[174:175], off
	s_waitcnt vmcnt(6)
	s_barrier
	s_setprio 1
	v_mfma_f32_16x16x32_bf16 v[28:31], v[190:193], v[230:233], v[28:31]
	v_mfma_f32_16x16x32_bf16 v[24:27], v[190:193], v[238:241], v[24:27]
	v_mfma_f32_16x16x32_bf16 v[20:23], v[198:201], v[230:233], v[20:23]
	v_mfma_f32_16x16x32_bf16 v[16:19], v[198:201], v[238:241], v[16:19]
	v_mfma_f32_16x16x32_bf16 v[12:15], v[206:209], v[230:233], v[12:15]
	v_mfma_f32_16x16x32_bf16 v[8:11], v[206:209], v[238:241], v[8:11]
	v_mfma_f32_16x16x32_bf16 v[4:7], v[214:217], v[230:233], v[4:7]
	v_mfma_f32_16x16x32_bf16 v[0:3], v[214:217], v[238:241], v[0:3]
	v_mfma_f32_16x16x32_bf16 v[28:31], v[194:197], v[234:237], v[28:31]
	v_mfma_f32_16x16x32_bf16 v[24:27], v[194:197], v[242:245], v[24:27]
	v_mfma_f32_16x16x32_bf16 v[20:23], v[202:205], v[234:237], v[20:23]
	v_mfma_f32_16x16x32_bf16 v[16:19], v[202:205], v[242:245], v[16:19]
	v_mfma_f32_16x16x32_bf16 v[12:15], v[210:213], v[234:237], v[12:15]
	v_mfma_f32_16x16x32_bf16 v[8:11], v[210:213], v[242:245], v[8:11]
	v_mfma_f32_16x16x32_bf16 v[4:7], v[218:221], v[234:237], v[4:7]
	v_mfma_f32_16x16x32_bf16 v[0:3], v[218:221], v[242:245], v[0:3]
	s_setprio 0
	s_add_i32 s44, s44, 2
	s_add_u32 s6, s6, 0x100
	s_addc_u32 s7, s7, 0
	s_cmp_lt_u32 s44, 12
	s_barrier
	s_cbranch_scc1 .LBB0_143
	s_add_u32 s4, s34, s4
	s_addc_u32 s5, s35, s5
	v_lshl_add_u64 v[206:207], s[4:5], 0, v[164:165]
	v_readfirstlane_b32 s6, v151
	ds_read_b128 v[128:131], v150
	ds_read_b128 v[134:137], v150 offset:1024
	ds_read_b128 v[138:141], v150 offset:2048
	ds_read_b128 v[142:145], v150 offset:3072
	ds_read_b128 v[174:177], v162
	ds_read_b128 v[178:181], v162 offset:1024
	ds_read_b128 v[182:185], v161
	ds_read_b128 v[186:189], v161 offset:1024
	ds_read_b128 v[190:193], v160
	ds_read_b128 v[194:197], v160 offset:1024
	ds_read_b128 v[198:201], v159
	ds_read_b128 v[202:205], v159 offset:1024
	v_lshl_add_u64 v[206:207], v[206:207], 0, s[30:31]
	s_mov_b32 m0, s6
	v_lshl_add_u64 v[150:151], s[4:5], 0, v[132:133]
	v_readfirstlane_b32 s4, v173
	global_load_lds_dwordx4 v[206:207], off
	v_lshl_add_u64 v[150:151], v[150:151], 0, s[30:31]
	s_mov_b32 m0, s4
	s_nop 0
	global_load_lds_dwordx4 v[150:151], off
	s_barrier
	s_waitcnt lgkmcnt(0)
	s_setprio 1
	s_waitcnt lgkmcnt(0)
	v_mfma_f32_16x16x32_bf16 v[124:127], v[174:177], v[128:131], v[124:127]
	v_mfma_f32_16x16x32_bf16 v[120:123], v[174:177], v[138:141], v[120:123]
	v_mfma_f32_16x16x32_bf16 v[116:119], v[182:185], v[128:131], v[116:119]
	v_mfma_f32_16x16x32_bf16 v[108:111], v[190:193], v[128:131], v[108:111]
	v_mfma_f32_16x16x32_bf16 v[104:107], v[190:193], v[138:141], v[104:107]
	v_mfma_f32_16x16x32_bf16 v[124:127], v[178:181], v[134:137], v[124:127]
	v_mfma_f32_16x16x32_bf16 v[120:123], v[178:181], v[142:145], v[120:123]
	v_mfma_f32_16x16x32_bf16 v[116:119], v[186:189], v[134:137], v[116:119]
	v_mfma_f32_16x16x32_bf16 v[112:115], v[182:185], v[138:141], v[112:115]
	v_mfma_f32_16x16x32_bf16 v[108:111], v[194:197], v[134:137], v[108:111]
	v_mfma_f32_16x16x32_bf16 v[104:107], v[194:197], v[142:145], v[104:107]
	v_mfma_f32_16x16x32_bf16 v[100:103], v[198:201], v[128:131], v[100:103]
	v_mfma_f32_16x16x32_bf16 v[96:99], v[198:201], v[138:141], v[96:99]
	v_mfma_f32_16x16x32_bf16 v[112:115], v[186:189], v[142:145], v[112:115]
	v_mfma_f32_16x16x32_bf16 v[206:209], v[202:205], v[134:137], v[100:103]
	v_mfma_f32_16x16x32_bf16 v[210:213], v[202:205], v[142:145], v[96:99]
	s_setprio 0
	s_barrier
	s_nop 2
	ds_read_b128 v[96:99], v149
	ds_read_b128 v[100:103], v149 offset:1024
	ds_read_b128 v[214:217], v149 offset:2048
	ds_read_b128 v[218:221], v149 offset:3072
	s_barrier
; #define LDA(dst, b, h) for (int m = 0; m < 4; ++m) for (int k = 0; k < 2; ++k) \
;     dst[m][k] = *reinterpret_cast<const bf16x8*>((char*)SA(b, h) + lds_byte(wr * 64 + m * 16 + fr, k * 32 + fq * 8))
; #define LDB(dst, b, h) for (int n = 0; n < 2; ++n) for (int k = 0; k < 2; ++k) \
;     dst[n][k] = *reinterpret_cast<const bf16x8*>((char*)SB(b, h) + lds_byte(wc * 32 + n * 16 + fr, k * 32 + fq * 8))
; #define MMA(ai, bj, At, Bq) do { __builtin_amdgcn_s_setprio(1); \
;     for (int m = 0; m < 4; ++m) for (int n = 0; n < 2; ++n) for (int k = 0; k < 2; ++k) \
;       acc[ai][bj][m][n] = __builtin_amdgcn_mfma_f32_16x16x32_bf16(At[m][k], Bq[n][k], acc[ai][bj][m][n], 0, 0, 0); \
;     __builtin_amdgcn_s_setprio(0); } while (0)
; #define WAIT_V(n) asm volatile("s_waitcnt vmcnt(" #n ")" ::: "memory")
; #define WAIT_L(n) asm volatile("s_waitcnt lgkmcnt(" #n ")" ::: "memory")
; #define BAR __builtin_amdgcn_s_barrier()
; template <class Epi>
; __device__ __forceinline__ void gemm_tile(const u16* __restrict__ A, const u16* __restrict__ Bt, int K,
;                                           int brow, int bcol, bool first, bool has_next, int nbrow, int nbcol, Epi epi) {
;     ...
;     BAR; WAIT_L(0); MMA(0, 0, At, B0); BAR;
;     LDB(B1, 0, 1); BAR; WAIT_L(0); MMA(0, 1, At, B1); BAR;
;     LDA(At, 0, 1); WAIT_V(4); BAR; WAIT_L(0); MMA(1, 0, At, B0); MMA(1, 1, At, B1); BAR; }
;   { LDB(B0, 1, 0); LDA(At, 1, 0); WAIT_V(2); BAR; WAIT_L(0); MMA(0, 0, At, B0); BAR;
	s_waitcnt lgkmcnt(0)
	s_setprio 1
	s_waitcnt lgkmcnt(0)
	v_mfma_f32_16x16x32_bf16 v[88:91], v[174:177], v[214:217], v[88:91]
	v_mfma_f32_16x16x32_bf16 v[84:87], v[182:185], v[96:99], v[84:87]
	v_mfma_f32_16x16x32_bf16 v[68:71], v[198:201], v[96:99], v[68:71]
	v_mfma_f32_16x16x32_bf16 v[64:67], v[198:201], v[214:217], v[64:67]
	v_mfma_f32_16x16x32_bf16 v[92:95], v[174:177], v[96:99], v[92:95]
	v_mfma_f32_16x16x32_bf16 v[88:91], v[178:181], v[218:221], v[88:91]
	v_mfma_f32_16x16x32_bf16 v[84:87], v[186:189], v[100:103], v[84:87]
	v_mfma_f32_16x16x32_bf16 v[80:83], v[182:185], v[214:217], v[80:83]
	v_mfma_f32_16x16x32_bf16 v[76:79], v[190:193], v[96:99], v[76:79]
	v_mfma_f32_16x16x32_bf16 v[72:75], v[190:193], v[214:217], v[72:75]
	v_mfma_f32_16x16x32_bf16 v[68:71], v[202:205], v[100:103], v[68:71]
	v_mfma_f32_16x16x32_bf16 v[64:67], v[202:205], v[218:221], v[64:67]
	v_mfma_f32_16x16x32_bf16 v[92:95], v[178:181], v[100:103], v[92:95]
	v_mfma_f32_16x16x32_bf16 v[174:177], v[186:189], v[218:221], v[80:83]
	v_mfma_f32_16x16x32_bf16 v[178:181], v[194:197], v[100:103], v[76:79]
	v_mfma_f32_16x16x32_bf16 v[72:75], v[194:197], v[218:221], v[72:75]
	s_setprio 0
	s_barrier
	ds_read_b128 v[76:79], v162 offset:16384
	ds_read_b128 v[80:83], v162 offset:17408
	ds_read_b128 v[182:185], v161 offset:16384
	ds_read_b128 v[186:189], v161 offset:17408
	ds_read_b128 v[190:193], v160 offset:16384
	ds_read_b128 v[194:197], v160 offset:17408
	ds_read_b128 v[198:201], v159 offset:16384
	ds_read_b128 v[202:205], v159 offset:17408
	s_waitcnt vmcnt(4)
	s_barrier
	s_waitcnt lgkmcnt(0)
	s_setprio 1
	s_waitcnt lgkmcnt(0)
	v_mfma_f32_16x16x32_bf16 v[60:63], v[76:79], v[128:131], v[60:63]
	v_mfma_f32_16x16x32_bf16 v[48:51], v[182:185], v[138:141], v[48:51]
	v_mfma_f32_16x16x32_bf16 v[44:47], v[190:193], v[128:131], v[44:47]
	v_mfma_f32_16x16x32_bf16 v[60:63], v[80:83], v[134:137], v[60:63]
	v_mfma_f32_16x16x32_bf16 v[56:59], v[76:79], v[138:141], v[56:59]
	v_mfma_f32_16x16x32_bf16 v[52:55], v[182:185], v[128:131], v[52:55]
	v_mfma_f32_16x16x32_bf16 v[48:51], v[186:189], v[142:145], v[48:51]
	v_mfma_f32_16x16x32_bf16 v[44:47], v[194:197], v[134:137], v[44:47]
	v_mfma_f32_16x16x32_bf16 v[40:43], v[190:193], v[138:141], v[40:43]
	v_mfma_f32_16x16x32_bf16 v[36:39], v[198:201], v[128:131], v[36:39]
	v_mfma_f32_16x16x32_bf16 v[32:35], v[198:201], v[138:141], v[32:35]
	v_mfma_f32_16x16x32_bf16 v[230:233], v[80:83], v[142:145], v[56:59]
	v_mfma_f32_16x16x32_bf16 v[52:55], v[186:189], v[134:137], v[52:55]
	v_mfma_f32_16x16x32_bf16 v[234:237], v[194:197], v[142:145], v[40:43]
	v_mfma_f32_16x16x32_bf16 v[238:241], v[202:205], v[134:137], v[36:39]
	v_mfma_f32_16x16x32_bf16 v[32:35], v[202:205], v[142:145], v[32:35]
	s_setprio 0
	s_setprio 1
	v_mfma_f32_16x16x32_bf16 v[28:31], v[76:79], v[96:99], v[28:31]
	v_mfma_f32_16x16x32_bf16 v[24:27], v[76:79], v[214:217], v[24:27]
	v_mfma_f32_16x16x32_bf16 v[12:15], v[190:193], v[96:99], v[12:15]
	v_mfma_f32_16x16x32_bf16 v[8:11], v[190:193], v[214:217], v[8:11]
	v_mfma_f32_16x16x32_bf16 v[28:31], v[80:83], v[100:103], v[28:31]
	v_mfma_f32_16x16x32_bf16 v[24:27], v[80:83], v[218:221], v[24:27]
	v_mfma_f32_16x16x32_bf16 v[20:23], v[182:185], v[96:99], v[20:23]
	v_mfma_f32_16x16x32_bf16 v[16:19], v[182:185], v[214:217], v[16:19]
	v_mfma_f32_16x16x32_bf16 v[12:15], v[194:197], v[100:103], v[12:15]
	v_mfma_f32_16x16x32_bf16 v[8:11], v[194:197], v[218:221], v[8:11]
	v_mfma_f32_16x16x32_bf16 v[4:7], v[198:201], v[96:99], v[4:7]
	v_mfma_f32_16x16x32_bf16 v[0:3], v[198:201], v[214:217], v[0:3]
	v_mfma_f32_16x16x32_bf16 v[242:245], v[186:189], v[100:103], v[20:23]
	v_mfma_f32_16x16x32_bf16 v[182:185], v[186:189], v[218:221], v[16:19]
	v_mfma_f32_16x16x32_bf16 v[186:189], v[202:205], v[100:103], v[4:7]
	v_mfma_f32_16x16x32_bf16 v[190:193], v[202:205], v[218:221], v[0:3]
	s_setprio 0
	s_barrier
	s_nop 1
	ds_read_b128 v[0:3], v148
	ds_read_b128 v[4:7], v148 offset:1024
	ds_read_b128 v[194:197], v148 offset:2048
	ds_read_b128 v[198:201], v148 offset:3072
	ds_read_b128 v[16:19], v162 offset:32768
	ds_read_b128 v[20:23], v162 offset:33792
	ds_read_b128 v[36:39], v161 offset:32768
	ds_read_b128 v[40:43], v161 offset:33792
	ds_read_b128 v[56:59], v160 offset:32768
	ds_read_b128 v[202:205], v160 offset:33792
	ds_read_b128 v[214:217], v159 offset:32768
	ds_read_b128 v[218:221], v159 offset:33792
	s_waitcnt vmcnt(2)
	s_barrier
; #define LDA(dst, b, h) for (int m = 0; m < 4; ++m) for (int k = 0; k < 2; ++k) \
;     dst[m][k] = *reinterpret_cast<const bf16x8*>((char*)SA(b, h) + lds_byte(wr * 64 + m * 16 + fr, k * 32 + fq * 8))
; #define LDB(dst, b, h) for (int n = 0; n < 2; ++n) for (int k = 0; k < 2; ++k) \
;     dst[n][k] = *reinterpret_cast<const bf16x8*>((char*)SB(b, h) + lds_byte(wc * 32 + n * 16 + fr, k * 32 + fq * 8))
; #define MMA(ai, bj, At, Bq) do { __builtin_amdgcn_s_setprio(1); \
;     for (int m = 0; m < 4; ++m) for (int n = 0; n < 2; ++n) for (int k = 0; k < 2; ++k) \
;       acc[ai][bj][m][n] = __builtin_amdgcn_mfma_f32_16x16x32_bf16(At[m][k], Bq[n][k], acc[ai][bj][m][n], 0, 0, 0); \
;     __builtin_amdgcn_s_setprio(0); } while (0)
; #define WAIT_V(n) asm volatile("s_waitcnt vmcnt(" #n ")" ::: "memory")
; #define WAIT_L(n) asm volatile("s_waitcnt lgkmcnt(" #n ")" ::: "memory")
; #define BAR __builtin_amdgcn_s_barrier()
; template <class Epi>
; __device__ __forceinline__ void gemm_tile(const u16* __restrict__ A, const u16* __restrict__ Bt, int K,
;                                           int brow, int bcol, bool first, bool has_next, int nbrow, int nbcol, Epi epi) {
;     ...
;   { LDB(B0, 1, 0); LDA(At, 1, 0); WAIT_V(2); BAR; WAIT_L(0); MMA(0, 0, At, B0); BAR;
;     LDB(B1, 1, 1); WAIT_V(0); BAR; WAIT_L(0); MMA(0, 1, At, B1); BAR;
;     LDA(At, 1, 1); BAR; WAIT_L(0); MMA(1, 0, At, B0); MMA(1, 1, At, B1); BAR; }
;   if (wr == 0) BAR;
	s_waitcnt lgkmcnt(0)
	s_setprio 1
	s_waitcnt lgkmcnt(0)
	v_mfma_f32_16x16x32_bf16 v[76:79], v[16:19], v[0:3], v[124:127]
	v_mfma_f32_16x16x32_bf16 v[136:139], v[20:23], v[4:7], v[76:79]
	v_mfma_f32_16x16x32_bf16 v[76:79], v[16:19], v[194:197], v[120:123]
	v_mfma_f32_16x16x32_bf16 v[140:143], v[20:23], v[198:201], v[76:79]
	v_mfma_f32_16x16x32_bf16 v[76:79], v[36:39], v[0:3], v[116:119]
	v_mfma_f32_16x16x32_bf16 v[116:119], v[40:43], v[4:7], v[76:79]
	v_mfma_f32_16x16x32_bf16 v[76:79], v[36:39], v[194:197], v[112:115]
	v_mfma_f32_16x16x32_bf16 v[120:123], v[40:43], v[198:201], v[76:79]
	v_mfma_f32_16x16x32_bf16 v[76:79], v[56:59], v[0:3], v[108:111]
	v_mfma_f32_16x16x32_bf16 v[96:99], v[202:205], v[4:7], v[76:79]
	v_mfma_f32_16x16x32_bf16 v[76:79], v[56:59], v[194:197], v[104:107]
	v_mfma_f32_16x16x32_bf16 v[100:103], v[202:205], v[198:201], v[76:79]
	v_mfma_f32_16x16x32_bf16 v[76:79], v[214:217], v[0:3], v[206:209]
	v_mfma_f32_16x16x32_bf16 v[80:83], v[214:217], v[194:197], v[210:213]
	v_mfma_f32_16x16x32_bf16 v[76:79], v[218:221], v[4:7], v[76:79]
	v_mfma_f32_16x16x32_bf16 v[80:83], v[218:221], v[198:201], v[80:83]
	s_setprio 0
	s_barrier
	ds_read_b128 v[112:115], v147
	ds_read_b128 v[206:209], v147 offset:1024
	ds_read_b128 v[210:213], v147 offset:2048
	ds_read_b128 v[246:249], v147 offset:3072
	s_waitcnt vmcnt(0)
	s_barrier
	s_waitcnt lgkmcnt(0)
	s_setprio 1
	s_waitcnt lgkmcnt(0)
	v_mfma_f32_16x16x32_bf16 v[92:95], v[16:19], v[112:115], v[92:95]
	v_mfma_f32_16x16x32_bf16 v[16:19], v[16:19], v[210:213], v[88:91]
	v_mfma_f32_16x16x32_bf16 v[148:151], v[20:23], v[246:249], v[16:19]
	v_mfma_f32_16x16x32_bf16 v[16:19], v[36:39], v[112:115], v[84:87]
	v_mfma_f32_16x16x32_bf16 v[124:127], v[40:43], v[206:209], v[16:19]
	v_mfma_f32_16x16x32_bf16 v[16:19], v[36:39], v[210:213], v[174:177]
	v_mfma_f32_16x16x32_bf16 v[128:131], v[40:43], v[246:249], v[16:19]
	v_mfma_f32_16x16x32_bf16 v[16:19], v[56:59], v[112:115], v[178:181]
	v_mfma_f32_16x16x32_bf16 v[104:107], v[202:205], v[206:209], v[16:19]
	v_mfma_f32_16x16x32_bf16 v[16:19], v[56:59], v[210:213], v[72:75]
	v_mfma_f32_16x16x32_bf16 v[108:111], v[202:205], v[246:249], v[16:19]
	v_mfma_f32_16x16x32_bf16 v[16:19], v[214:217], v[112:115], v[68:71]
	v_mfma_f32_16x16x32_bf16 v[84:87], v[218:221], v[206:209], v[16:19]
	v_mfma_f32_16x16x32_bf16 v[16:19], v[214:217], v[210:213], v[64:67]
	v_mfma_f32_16x16x32_bf16 v[144:147], v[20:23], v[206:209], v[92:95]
	v_mfma_f32_16x16x32_bf16 v[88:91], v[218:221], v[246:249], v[16:19]
	s_setprio 0
	s_barrier
	ds_read_b128 v[68:71], v162 offset:49152
	ds_read_b128 v[72:75], v162 offset:50176
	ds_read_b128 v[92:95], v161 offset:49152
	ds_read_b128 v[174:177], v161 offset:50176
	ds_read_b128 v[178:181], v160 offset:49152
	ds_read_b128 v[202:205], v160 offset:50176
	ds_read_b128 v[214:217], v159 offset:49152
	ds_read_b128 v[218:221], v159 offset:50176
	s_barrier
	s_waitcnt lgkmcnt(0)
	s_setprio 1
	s_waitcnt lgkmcnt(0)
	v_mfma_f32_16x16x32_bf16 v[16:19], v[68:71], v[0:3], v[60:63]
	v_mfma_f32_16x16x32_bf16 v[56:59], v[72:75], v[4:7], v[16:19]
	v_mfma_f32_16x16x32_bf16 v[16:19], v[68:71], v[194:197], v[230:233]
	v_mfma_f32_16x16x32_bf16 v[60:63], v[72:75], v[198:201], v[16:19]
	v_mfma_f32_16x16x32_bf16 v[16:19], v[92:95], v[0:3], v[52:55]
	v_mfma_f32_16x16x32_bf16 v[36:39], v[174:177], v[4:7], v[16:19]
	v_mfma_f32_16x16x32_bf16 v[16:19], v[92:95], v[194:197], v[48:51]
	v_mfma_f32_16x16x32_bf16 v[40:43], v[174:177], v[198:201], v[16:19]
	v_mfma_f32_16x16x32_bf16 v[16:19], v[178:181], v[0:3], v[44:47]
	v_mfma_f32_16x16x32_bf16 v[0:3], v[214:217], v[0:3], v[238:241]
	v_mfma_f32_16x16x32_bf16 v[16:19], v[202:205], v[4:7], v[16:19]
	v_mfma_f32_16x16x32_bf16 v[20:23], v[178:181], v[194:197], v[234:237]
	v_mfma_f32_16x16x32_bf16 v[0:3], v[218:221], v[4:7], v[0:3]
	v_mfma_f32_16x16x32_bf16 v[4:7], v[214:217], v[194:197], v[32:35]
	v_mfma_f32_16x16x32_bf16 v[20:23], v[202:205], v[198:201], v[20:23]
	v_mfma_f32_16x16x32_bf16 v[4:7], v[218:221], v[198:201], v[4:7]
	s_setprio 0
	s_setprio 1
	v_mfma_f32_16x16x32_bf16 v[24:27], v[68:71], v[210:213], v[24:27]
	v_mfma_f32_16x16x32_bf16 v[28:31], v[68:71], v[112:115], v[28:31]
	v_mfma_f32_16x16x32_bf16 v[68:71], v[72:75], v[246:249], v[24:27]
	v_mfma_f32_16x16x32_bf16 v[24:27], v[92:95], v[112:115], v[242:245]
	v_mfma_f32_16x16x32_bf16 v[44:47], v[174:177], v[206:209], v[24:27]
	v_mfma_f32_16x16x32_bf16 v[24:27], v[92:95], v[210:213], v[182:185]
	v_mfma_f32_16x16x32_bf16 v[12:15], v[178:181], v[112:115], v[12:15]
	v_mfma_f32_16x16x32_bf16 v[8:11], v[178:181], v[210:213], v[8:11]
	v_mfma_f32_16x16x32_bf16 v[64:67], v[72:75], v[206:209], v[28:31]
	v_mfma_f32_16x16x32_bf16 v[48:51], v[174:177], v[246:249], v[24:27]
	v_mfma_f32_16x16x32_bf16 v[24:27], v[202:205], v[206:209], v[12:15]
	v_mfma_f32_16x16x32_bf16 v[28:31], v[202:205], v[246:249], v[8:11]
	v_mfma_f32_16x16x32_bf16 v[8:11], v[214:217], v[112:115], v[186:189]
	v_mfma_f32_16x16x32_bf16 v[12:15], v[214:217], v[210:213], v[190:193]
	v_mfma_f32_16x16x32_bf16 v[8:11], v[218:221], v[206:209], v[8:11]
	v_mfma_f32_16x16x32_bf16 v[12:15], v[218:221], v[246:249], v[12:15]
	s_setprio 0
	s_movk_i32 s4, 0x100
	v_cmp_gt_u32_e32 vcc, s4, v152
	s_barrier
	s_and_saveexec_b64 s[4:5], vcc
	s_cbranch_execz .LBB0_146
	s_barrier

; #define LBAR do { asm volatile("s_waitcnt lgkmcnt(0)" ::: "memory"); __builtin_amdgcn_s_barrier(); } while (0)
; __device__ __forceinline__ void gla_summ_unit(const P& p, int unit, const SummRaw& raw) {
;     ...
; #pragma unroll 1
;   for (int tI = 0; tI < 8; ++tI) {
;     int tile = wid * 8 + tI;
;     int dir = tile >> 5, dkt = (tile >> 3) & 3, dvt = tile & 7;
;     const u16* Asrc = (dir ? kdbT : kdfT) + (dkt * 16 + fr) * LP + fq * 8;
;     const u16* Bsrc = vT + (dvt * 16 + fr) * LP + fq * 8;
;     f32x4 d = {0.f, 0.f, 0.f, 0.f};
; #pragma unroll
;     for (int ks = 0; ks < 2; ++ks) {
;       bf16x8 a = *(const bf16x8*)(Asrc + ks * 32);
;       bf16x8 b = *(const bf16x8*)(Bsrc + ks * 32);
;       d = __builtin_amdgcn_mfma_f32_16x16x32_bf16(a, b, d, 0, 0, 0);
;     }
;     uint2 w; w.x = pack2(d[0], d[1]); w.y = pack2(d[2], d[3]);
;     *(uint2*)(kvout + (size_t)(unit * 2 + dir) * 8192 + (dvt * 16 + fr) * 64 + dkt * 16 + fq * 4) = w;
;   }
;   LBAR;
; }
; __device__ void phase_gla_summ(const P& p) {
;     ...
;   for (; u < 4096; u += gridDim.x) {
;     int un = u + gridDim.x;
;     SummRaw nxt = gla_summ_load(p, un < 4096 ? un : u, tid);
;     gla_summ_unit(p, u, cur);
;     cur = nxt;
;   }
.LBB0_227:
	v_add_u32_e32 v31, s0, v30
	v_add_u32_e32 v34, 0x11200, v31
	s_nop 0
	ds_read_b128 v[42:45], v34
	v_add_u32_e32 v31, 0x11240, v31
	ds_read_b128 v[52:55], v31
	s_addk_i32 s0, 0x900
	s_cmpk_lg_i32 s0, 0x4800
	s_waitcnt lgkmcnt(1)
	v_mfma_f32_16x16x32_bf16 v[42:45], v[8:11], v[42:45], 0
	s_waitcnt lgkmcnt(0)
	v_mfma_f32_16x16x32_bf16 v[42:45], v[12:15], v[52:55], v[42:45]
	s_nop 7
	v_cvt_pk_bf16_f32 v42, v42, v43
	v_cvt_pk_bf16_f32 v43, v44, v45
	global_store_dwordx2 v[28:29], v[42:43], off offset:-4
	v_lshl_add_u64 v[28:29], v[28:29], 0, s[22:23]
	s_cbranch_scc1 .LBB0_227
	s_waitcnt lgkmcnt(0)
	s_add_i32 s20, s20, s3
	s_andn2_b64 vcc, exec, s[24:25]
	s_mov_b32 s21, s46
	s_waitcnt vmcnt(3)
	v_mov_b64_e32 v[12:13], v[20:21]
	v_mov_b64_e32 v[14:15], v[22:23]
	s_waitcnt vmcnt(1)
	v_mov_b64_e32 v[8:9], v[24:25]
	v_mov_b64_e32 v[10:11], v[26:27]
	v_mov_b64_e32 v[28:29], v[16:17]
	v_mov_b64_e32 v[30:31], v[18:19]
	s_cbranch_vccnz .LBB0_224

; #define LBAR do { asm volatile("s_waitcnt lgkmcnt(0)" ::: "memory"); __builtin_amdgcn_s_barrier(); } while (0)
; __device__ __forceinline__ void gla_out_unit(const P& p, int unit, const OutRaw& raw) {
;     ...
;   LBAR;
;   u16* omix = (u16*)(p.ws + OFF_OMIX);
;   {
;     float rsj[4];
; #pragma unroll
;     for (int j = 0; j < 4; ++j) {
;       int t = tt * 16 + fq * 4 + j;
;       float tot = ssq[t * 2] + ssq[t * 2 + 1];
;       rsj[j] = rsqrtf(tot * (1.f / 128.f) + 1e-6f);
;     }
;     int row0 = chunk * 64 + tt * 16 + fq * 4;
; #pragma unroll
;     for (int i = 0; i < 4; ++i) {
;       int dv = (dvh * 4 + i) * 16 + fr;
;       float g = p.g_gla[dv];
;       float s0 = __uint_as_float(rav[i].x << 16), s1 = __uint_as_float(rav[i].x & 0xffff0000u);
;       float s2 = __uint_as_float(rav[i].y << 16), s3 = __uint_as_float(rav[i].y & 0xffff0000u);
;       store_rm4(omix, 1024, row0, 512 + h * 128 + dv, o[i][0] * rsj[0] * g * s0, o[i][1] * rsj[1] * g * s1,
;                 o[i][2] * rsj[2] * g * s2, o[i][3] * rsj[3] * g * s3, fr & 1);
;     }
;   }
;   LBAR;
; }
.LBB0_384:
	s_or_b64 exec, exec, s[0:1]
	v_lshlrev_b32_e32 v50, 2, v112
	s_waitcnt lgkmcnt(0)
	s_barrier
	global_load_dword v56, v50, s[36:37]
	v_add_u32_e32 v29, s56, v29
	v_add_u32_e32 v44, s56, v28
	ds_read2_b64 v[28:31], v29 offset1:1
	ds_read2_b64 v[44:47], v44 offset1:1
	global_load_dword v62, v50, s[36:37] offset:64
	global_load_dword v63, v50, s[36:37] offset:128
	global_load_dword v64, v50, s[36:37] offset:192
	s_lshl_b32 s1, s30, 7
	s_and_b32 s0, s30, 0xffffffc
	s_and_b32 s8, s1, 0x180
	v_and_b32_e32 v57, 1, v137
	v_add_lshl_u32 v51, v136, s0, 4
	s_or_b32 s0, s8, 0x200
	v_sub_u32_e32 v54, s0, v57
	v_add_lshl_u32 v98, v54, v112, 1
	s_waitcnt lgkmcnt(1)
	v_mov_b32_e32 v54, v30
	v_mov_b32_e32 v55, v28
	v_mov_b32_e32 v28, v31
	v_mov_b64_e32 v[48:49], s[26:27]
	v_pk_add_f32 v[28:29], v[54:55], v[28:29]
	s_waitcnt lgkmcnt(0)
	v_mov_b32_e32 v30, v46
	v_mov_b32_e32 v31, v44
	v_mov_b32_e32 v44, v47
	v_pk_fma_f32 v[28:29], v[28:29], s[24:25], v[48:49] op_sel_hi:[1,0,0]
	v_pk_add_f32 v[30:31], v[30:31], v[44:45]
	v_mul_f32_e32 v44, 0x4b800000, v29
	v_mul_f32_e32 v45, 0x4b800000, v28
	v_cmp_gt_f32_e32 vcc, s57, v29
	v_cmp_gt_f32_e64 s[0:1], s57, v28
	v_pk_fma_f32 v[30:31], v[30:31], s[24:25], v[48:49] op_sel_hi:[1,0,0]
	v_cndmask_b32_e32 v29, v29, v44, vcc
	v_cndmask_b32_e64 v28, v28, v45, s[0:1]
	v_mul_f32_e32 v48, 0x4b800000, v31
	v_mul_f32_e32 v49, 0x4b800000, v30
	v_cmp_gt_f32_e64 s[4:5], s57, v31
	v_cmp_gt_f32_e64 s[6:7], s57, v30
	v_rsq_f32_e32 v29, v29
	v_rsq_f32_e32 v28, v28
	v_cndmask_b32_e64 v31, v31, v48, s[4:5]
	v_cndmask_b32_e64 v30, v30, v49, s[6:7]
	v_rsq_f32_e32 v31, v31
	v_rsq_f32_e32 v30, v30
	v_mul_f32_e32 v44, 0x45800000, v29
	v_mul_f32_e32 v45, 0x45800000, v28
	v_cndmask_b32_e32 v44, v29, v44, vcc
	v_cndmask_b32_e64 v45, v28, v45, s[0:1]
	v_mul_f32_e32 v48, 0x45800000, v31
	v_mul_f32_e32 v49, 0x45800000, v30
	v_mul_f32_e32 v28, v40, v44
	v_mul_f32_e32 v29, v41, v45
	v_lshlrev_b32_e32 v58, 16, v110
	v_and_b32_e32 v59, 0xffff0000, v110
	v_cndmask_b32_e64 v48, v31, v48, s[4:5]
	v_cndmask_b32_e64 v49, v30, v49, s[6:7]
	v_or3_b32 v50, v51, v113, v57
	v_mul_f32_e32 v30, v42, v48
	v_mul_f32_e32 v31, v43, v49
	v_cmp_eq_u32_e32 vcc, 0, v57
	v_lshlrev_b32_e32 v60, 16, v111
	v_and_b32_e32 v61, 0xffff0000, v111
	v_ashrrev_i32_e32 v51, 31, v50
	v_or_b32_e32 v52, 2, v50
	v_lshlrev_b64 v[50:51], 11, v[50:51]
	v_ashrrev_i32_e32 v53, 31, v52
	v_lshl_add_u64 v[50:51], s[34:35], 0, v[50:51]
	v_lshlrev_b64 v[52:53], 11, v[52:53]
	v_lshl_add_u64 v[46:47], s[34:35], 0, v[52:53]
	v_lshl_add_u64 v[52:53], v[50:51], 0, v[98:99]
	v_mul_f32_e32 v36, v36, v44
	v_mul_f32_e32 v32, v32, v44
	v_mul_f32_e32 v33, v33, v45
	v_mul_f32_e32 v34, v34, v48
	v_mul_f32_e32 v35, v35, v49
	v_mul_f32_e32 v24, v24, v44
	v_mul_f32_e32 v25, v25, v45
	v_mul_f32_e32 v26, v26, v48
	v_mul_f32_e32 v27, v27, v49
	v_mov_b64_e32 v[42:43], v[22:23]
	s_waitcnt vmcnt(3)
	v_mul_f32_e32 v28, v56, v28
	v_mul_f32_e32 v29, v56, v29
	v_mul_f32_e32 v28, v28, v58
	v_mul_f32_e32 v29, v29, v59
	v_mul_f32_e32 v30, v56, v30
	v_mul_f32_e32 v31, v56, v31
	v_cndmask_b32_e32 v40, v28, v29, vcc
	v_mul_f32_e32 v30, v30, v60
	v_mul_f32_e32 v31, v31, v61
	v_mov_b32_dpp v40, v40 quad_perm:[1,0,3,2] row_mask:0xf bank_mask:0xf bound_ctrl:1
	v_cndmask_b32_e32 v41, v30, v31, vcc
	v_cndmask_b32_e32 v28, v40, v28, vcc
	v_cndmask_b32_e32 v29, v29, v40, vcc
	v_mov_b32_dpp v41, v41 quad_perm:[1,0,3,2] row_mask:0xf bank_mask:0xf bound_ctrl:1
	v_cvt_pk_bf16_f32 v28, v28, v29
	global_store_dword v[52:53], v28, off
	v_cndmask_b32_e32 v28, v41, v30, vcc
	v_cndmask_b32_e32 v29, v31, v41, vcc
	v_cvt_pk_bf16_f32 v30, v28, v29
	v_lshl_add_u64 v[28:29], v[46:47], 0, v[98:99]
	global_store_dword v[28:29], v30, off
	v_lshlrev_b32_e32 v28, 16, v108
	s_waitcnt vmcnt(4)
	v_mul_f32_e32 v36, v36, v62
	v_mul_f32_e32 v28, v36, v28
	v_mul_f32_e32 v36, v37, v45
	v_and_b32_e32 v29, 0xffff0000, v108
	v_mul_f32_e32 v36, v36, v62
	v_mul_f32_e32 v29, v36, v29
	v_mul_f32_e32 v36, v38, v48
	v_lshlrev_b32_e32 v30, 16, v109
	v_mul_f32_e32 v36, v62, v36
	v_mul_f32_e32 v36, v36, v30
	v_mul_f32_e32 v30, v39, v49
	v_and_b32_e32 v31, 0xffff0000, v109
	v_mul_f32_e32 v30, v62, v30
	v_mul_f32_e32 v37, v30, v31
	v_cndmask_b32_e32 v30, v28, v29, vcc
	s_waitcnt vmcnt(3)
	v_mul_f32_e32 v32, v32, v63
	v_mul_f32_e32 v33, v33, v63
	v_mov_b32_dpp v30, v30 quad_perm:[1,0,3,2] row_mask:0xf bank_mask:0xf bound_ctrl:1
	v_cndmask_b32_e32 v28, v30, v28, vcc
	v_cndmask_b32_e32 v29, v29, v30, vcc
	v_cvt_pk_bf16_f32 v38, v28, v29
	v_sub_u32_e32 v28, s8, v57
	v_add3_u32 v98, v28, v112, s43
	v_lshlrev_b64 v[28:29], 1, v[98:99]
	v_lshl_add_u64 v[30:31], v[50:51], 0, v[28:29]
	global_store_dword v[30:31], v38, off offset:32
	v_cndmask_b32_e32 v38, v36, v37, vcc
	v_lshl_add_u64 v[28:29], v[46:47], 0, v[28:29]
	v_and_b32_e32 v39, 0xffff0000, v107
	v_mov_b32_dpp v38, v38 quad_perm:[1,0,3,2] row_mask:0xf bank_mask:0xf bound_ctrl:1
	v_cndmask_b32_e32 v36, v38, v36, vcc
	v_cndmask_b32_e32 v37, v37, v38, vcc
	v_cvt_pk_bf16_f32 v36, v36, v37
	global_store_dword v[28:29], v36, off offset:32
	v_lshlrev_b32_e32 v36, 16, v106
	v_and_b32_e32 v37, 0xffff0000, v106
	v_mul_f32_e32 v32, v32, v36
	v_mul_f32_e32 v33, v33, v37
	v_cndmask_b32_e32 v36, v32, v33, vcc
	v_lshlrev_b32_e32 v38, 16, v107
	v_mul_f32_e32 v34, v34, v63
	v_mov_b32_dpp v36, v36 quad_perm:[1,0,3,2] row_mask:0xf bank_mask:0xf bound_ctrl:1
	v_mul_f32_e32 v35, v35, v63
	v_cndmask_b32_e32 v32, v36, v32, vcc
	v_cndmask_b32_e32 v33, v33, v36, vcc
	v_mul_f32_e32 v34, v34, v38
	v_mul_f32_e32 v35, v35, v39
	v_cvt_pk_bf16_f32 v32, v32, v33
	global_store_dword v[30:31], v32, off offset:64
	v_cndmask_b32_e32 v32, v34, v35, vcc
	s_waitcnt vmcnt(5)
	v_mul_f32_e32 v24, v24, v64
	v_mul_f32_e32 v25, v25, v64
	v_mov_b32_dpp v32, v32 quad_perm:[1,0,3,2] row_mask:0xf bank_mask:0xf bound_ctrl:1
	v_cndmask_b32_e32 v33, v32, v34, vcc
	v_cndmask_b32_e32 v32, v35, v32, vcc
	v_cvt_pk_bf16_f32 v32, v33, v32
	global_store_dword v[28:29], v32, off offset:64
	v_lshlrev_b32_e32 v32, 16, v104
	v_and_b32_e32 v33, 0xffff0000, v104
	v_mul_f32_e32 v24, v24, v32
	v_mul_f32_e32 v25, v25, v33
	v_cndmask_b32_e32 v32, v24, v25, vcc
	v_lshlrev_b32_e32 v34, 16, v105
	v_and_b32_e32 v35, 0xffff0000, v105
	v_mov_b32_dpp v32, v32 quad_perm:[1,0,3,2] row_mask:0xf bank_mask:0xf bound_ctrl:1
	v_mul_f32_e32 v26, v26, v64
	v_mul_f32_e32 v27, v27, v64
	v_cndmask_b32_e32 v24, v32, v24, vcc
	v_cndmask_b32_e32 v25, v25, v32, vcc
	v_mul_f32_e32 v26, v26, v34
	v_mul_f32_e32 v27, v27, v35
	v_cvt_pk_bf16_f32 v24, v24, v25
	global_store_dword v[30:31], v24, off offset:96
	v_cndmask_b32_e32 v24, v26, v27, vcc
	s_nop 1
	v_mov_b32_dpp v24, v24 quad_perm:[1,0,3,2] row_mask:0xf bank_mask:0xf bound_ctrl:1
	v_cndmask_b32_e32 v25, v24, v26, vcc
	v_cndmask_b32_e32 v24, v27, v24, vcc
	v_cvt_pk_bf16_f32 v24, v25, v24
	global_store_dword v[28:29], v24, off offset:96
	s_waitcnt lgkmcnt(0)
	s_andn2_b64 vcc, exec, s[28:29]
	s_cbranch_vccz .LBB0_391

; #define LDA(dst, b, h) for (int m = 0; m < 4; ++m) for (int k = 0; k < 2; ++k) \
;     dst[m][k] = *reinterpret_cast<const bf16x8*>((char*)SA(b, h) + lds_byte(wr * 64 + m * 16 + fr, k * 32 + fq * 8))
; #define LDB(dst, b, h) for (int n = 0; n < 2; ++n) for (int k = 0; k < 2; ++k) \
;     dst[n][k] = *reinterpret_cast<const bf16x8*>((char*)SB(b, h) + lds_byte(wc * 32 + n * 16 + fr, k * 32 + fq * 8))
; #define MMA(ai, bj, At, Bq) do { __builtin_amdgcn_s_setprio(1); \
;     for (int m = 0; m < 4; ++m) for (int n = 0; n < 2; ++n) for (int k = 0; k < 2; ++k) \
;       acc[ai][bj][m][n] = __builtin_amdgcn_mfma_f32_16x16x32_bf16(At[m][k], Bq[n][k], acc[ai][bj][m][n], 0, 0, 0); \
;     __builtin_amdgcn_s_setprio(0); } while (0)
; #define WAIT_L(n) asm volatile("s_waitcnt lgkmcnt(" #n ")" ::: "memory")
; #define BAR __builtin_amdgcn_s_barrier()
; #define SCHED __builtin_amdgcn_sched_barrier(0)
; template <class Epi>
; __device__ __forceinline__ void gemm_tile(const u16* __restrict__ A, const u16* __restrict__ Bt, int K,
;                                           int brow, int bcol, bool first, bool has_next, int nbrow, int nbcol, Epi epi) {
;     ...
;     LDB(B0, 0, 0); SCHED; LDA(At, 0, 0); STAGE(SA(1, 1), A, brow + HALF, t + 1);
;     WAIT_L(8); BAR; WAIT_L(0); MMA(0, 0, At, B0); BAR; SCHED;
;     LDB(B1, 0, 1); STAGE(SB(0, 0), Bt, bcol, t + 2);
;     BAR; WAIT_L(0); MMA(0, 1, At, B1); BAR;
;     LDA(At, 0, 1); STAGE(SA(0, 0), A, brow, t + 2);
;     BAR; WAIT_L(0); MMA(1, 0, At, B0); BAR; SCHED;
.LBB0_457:
	ds_read_b128 v[166:169], v164
	ds_read_b128 v[176:179], v164 offset:1024
	ds_read_b128 v[180:183], v164 offset:2048
	ds_read_b128 v[184:187], v164 offset:3072
	v_add_u32_e32 v173, 0xc000, v153
	v_lshl_add_u64 v[170:171], s[28:29], 0, v[144:145]
	v_readfirstlane_b32 s3, v173
	v_lshl_add_u64 v[174:175], v[170:171], 0, s[4:5]
	s_mov_b32 m0, s3
	ds_read_b128 v[188:191], v159
	ds_read_b128 v[192:195], v159 offset:1024
	ds_read_b128 v[196:199], v158
	ds_read_b128 v[200:203], v158 offset:1024
	ds_read_b128 v[204:207], v157
	ds_read_b128 v[208:211], v157 offset:1024
	ds_read_b128 v[212:215], v156
	ds_read_b128 v[216:219], v156 offset:1024
	global_load_lds_dwordx4 v[174:175], off
	v_add_u32_e32 v174, 0xe000, v153
	v_lshl_add_u64 v[236:237], s[28:29], 0, v[146:147]
	v_readfirstlane_b32 s3, v174
	v_lshl_add_u64 v[220:221], v[236:237], 0, s[4:5]
	s_mov_b32 m0, s3
	s_nop 0
	global_load_lds_dwordx4 v[220:221], off
	s_waitcnt lgkmcnt(8)
	s_barrier
	s_waitcnt lgkmcnt(0)
	s_setprio 1
	v_mfma_f32_16x16x32_bf16 v[124:127], v[188:191], v[166:169], v[124:127]
	v_mfma_f32_16x16x32_bf16 v[120:123], v[188:191], v[180:183], v[120:123]
	v_mfma_f32_16x16x32_bf16 v[116:119], v[196:199], v[166:169], v[116:119]
	v_mfma_f32_16x16x32_bf16 v[112:115], v[196:199], v[180:183], v[112:115]
	v_mfma_f32_16x16x32_bf16 v[108:111], v[204:207], v[166:169], v[108:111]
	v_mfma_f32_16x16x32_bf16 v[104:107], v[204:207], v[180:183], v[104:107]
	v_mfma_f32_16x16x32_bf16 v[100:103], v[212:215], v[166:169], v[100:103]
	v_mfma_f32_16x16x32_bf16 v[96:99], v[212:215], v[180:183], v[96:99]
	v_mfma_f32_16x16x32_bf16 v[124:127], v[192:195], v[176:179], v[124:127]
	v_mfma_f32_16x16x32_bf16 v[120:123], v[192:195], v[184:187], v[120:123]
	v_mfma_f32_16x16x32_bf16 v[116:119], v[200:203], v[176:179], v[116:119]
	v_mfma_f32_16x16x32_bf16 v[112:115], v[200:203], v[184:187], v[112:115]
	v_mfma_f32_16x16x32_bf16 v[108:111], v[208:211], v[176:179], v[108:111]
	v_mfma_f32_16x16x32_bf16 v[104:107], v[208:211], v[184:187], v[104:107]
	v_mfma_f32_16x16x32_bf16 v[100:103], v[216:219], v[176:179], v[100:103]
	v_mfma_f32_16x16x32_bf16 v[96:99], v[216:219], v[184:187], v[96:99]
	s_setprio 0
	s_barrier
	v_lshl_add_u64 v[240:241], s[28:29], 0, v[132:133]
	v_readfirstlane_b32 s3, v154
	v_add_u32_e32 v165, 0x2000, v154
	v_lshl_add_u64 v[238:239], v[240:241], 0, s[10:11]
	s_mov_b32 m0, s3
	v_lshl_add_u64 v[242:243], s[28:29], 0, v[134:135]
	v_readfirstlane_b32 s3, v165
	ds_read_b128 v[220:223], v163
	ds_read_b128 v[224:227], v163 offset:1024
	ds_read_b128 v[228:231], v163 offset:2048
	ds_read_b128 v[232:235], v163 offset:3072
	global_load_lds_dwordx4 v[238:239], off
	v_lshl_add_u64 v[238:239], v[242:243], 0, s[10:11]
	s_mov_b32 m0, s3
	s_nop 0
	global_load_lds_dwordx4 v[238:239], off
	s_barrier
	s_waitcnt lgkmcnt(0)
	s_setprio 1
	v_mfma_f32_16x16x32_bf16 v[92:95], v[188:191], v[220:223], v[92:95]
	v_mfma_f32_16x16x32_bf16 v[88:91], v[188:191], v[228:231], v[88:91]
	v_mfma_f32_16x16x32_bf16 v[84:87], v[196:199], v[220:223], v[84:87]
	v_mfma_f32_16x16x32_bf16 v[80:83], v[196:199], v[228:231], v[80:83]
	v_mfma_f32_16x16x32_bf16 v[76:79], v[204:207], v[220:223], v[76:79]
	v_mfma_f32_16x16x32_bf16 v[72:75], v[204:207], v[228:231], v[72:75]
	v_mfma_f32_16x16x32_bf16 v[68:71], v[212:215], v[220:223], v[68:71]
	v_mfma_f32_16x16x32_bf16 v[64:67], v[212:215], v[228:231], v[64:67]
	v_mfma_f32_16x16x32_bf16 v[92:95], v[192:195], v[224:227], v[92:95]
	v_mfma_f32_16x16x32_bf16 v[88:91], v[192:195], v[232:235], v[88:91]
	v_mfma_f32_16x16x32_bf16 v[84:87], v[200:203], v[224:227], v[84:87]
	v_mfma_f32_16x16x32_bf16 v[80:83], v[200:203], v[232:235], v[80:83]
	v_mfma_f32_16x16x32_bf16 v[76:79], v[208:211], v[224:227], v[76:79]
	v_mfma_f32_16x16x32_bf16 v[72:75], v[208:211], v[232:235], v[72:75]
	v_mfma_f32_16x16x32_bf16 v[68:71], v[216:219], v[224:227], v[68:71]
	v_mfma_f32_16x16x32_bf16 v[64:67], v[216:219], v[232:235], v[64:67]
	s_setprio 0
	v_lshl_add_u64 v[244:245], s[28:29], 0, v[136:137]
	v_readfirstlane_b32 s3, v153
	v_lshl_add_u64 v[238:239], v[244:245], 0, s[12:13]
	s_mov_b32 m0, s3
	v_lshl_add_u64 v[246:247], s[28:29], 0, v[138:139]
	v_readfirstlane_b32 s3, v152
	s_barrier
	ds_read_b128 v[188:191], v159 offset:16384
	ds_read_b128 v[192:195], v159 offset:17408
	ds_read_b128 v[196:199], v158 offset:16384
	ds_read_b128 v[200:203], v158 offset:17408
	ds_read_b128 v[204:207], v157 offset:16384
	ds_read_b128 v[208:211], v157 offset:17408
	ds_read_b128 v[212:215], v156 offset:16384
	ds_read_b128 v[216:219], v156 offset:17408
	global_load_lds_dwordx4 v[238:239], off
	v_lshl_add_u64 v[238:239], v[246:247], 0, s[12:13]
	s_mov_b32 m0, s3
	s_nop 0
	global_load_lds_dwordx4 v[238:239], off
	s_barrier
	s_waitcnt lgkmcnt(0)
	s_setprio 1
	v_mfma_f32_16x16x32_bf16 v[60:63], v[188:191], v[166:169], v[60:63]
	v_mfma_f32_16x16x32_bf16 v[56:59], v[188:191], v[180:183], v[56:59]
	v_mfma_f32_16x16x32_bf16 v[52:55], v[196:199], v[166:169], v[52:55]
	v_mfma_f32_16x16x32_bf16 v[48:51], v[196:199], v[180:183], v[48:51]
	v_mfma_f32_16x16x32_bf16 v[44:47], v[204:207], v[166:169], v[44:47]
	v_mfma_f32_16x16x32_bf16 v[40:43], v[204:207], v[180:183], v[40:43]
	v_mfma_f32_16x16x32_bf16 v[36:39], v[212:215], v[166:169], v[36:39]
	v_mfma_f32_16x16x32_bf16 v[32:35], v[212:215], v[180:183], v[32:35]
	v_mfma_f32_16x16x32_bf16 v[60:63], v[192:195], v[176:179], v[60:63]
	v_mfma_f32_16x16x32_bf16 v[56:59], v[192:195], v[184:187], v[56:59]
	v_mfma_f32_16x16x32_bf16 v[52:55], v[200:203], v[176:179], v[52:55]
	v_mfma_f32_16x16x32_bf16 v[48:51], v[200:203], v[184:187], v[48:51]
	v_mfma_f32_16x16x32_bf16 v[44:47], v[208:211], v[176:179], v[44:47]
	v_mfma_f32_16x16x32_bf16 v[40:43], v[208:211], v[184:187], v[40:43]
	v_mfma_f32_16x16x32_bf16 v[36:39], v[216:219], v[176:179], v[36:39]
	v_mfma_f32_16x16x32_bf16 v[32:35], v[216:219], v[184:187], v[32:35]
	s_setprio 0
	s_barrier
; #define LDA(dst, b, h) for (int m = 0; m < 4; ++m) for (int k = 0; k < 2; ++k) \
;     dst[m][k] = *reinterpret_cast<const bf16x8*>((char*)SA(b, h) + lds_byte(wr * 64 + m * 16 + fr, k * 32 + fq * 8))
; #define LDB(dst, b, h) for (int n = 0; n < 2; ++n) for (int k = 0; k < 2; ++k) \
;     dst[n][k] = *reinterpret_cast<const bf16x8*>((char*)SB(b, h) + lds_byte(wc * 32 + n * 16 + fr, k * 32 + fq * 8))
; #define MMA(ai, bj, At, Bq) do { __builtin_amdgcn_s_setprio(1); \
;     for (int m = 0; m < 4; ++m) for (int n = 0; n < 2; ++n) for (int k = 0; k < 2; ++k) \
;       acc[ai][bj][m][n] = __builtin_amdgcn_mfma_f32_16x16x32_bf16(At[m][k], Bq[n][k], acc[ai][bj][m][n], 0, 0, 0); \
;     __builtin_amdgcn_s_setprio(0); } while (0)
; #define WAIT_V(n) asm volatile("s_waitcnt vmcnt(" #n ")" ::: "memory")
; #define WAIT_L(n) asm volatile("s_waitcnt lgkmcnt(" #n ")" ::: "memory")
; #define BAR __builtin_amdgcn_s_barrier()
; #define SCHED __builtin_amdgcn_sched_barrier(0)
; template <class Epi>
; __device__ __forceinline__ void gemm_tile(const u16* __restrict__ A, const u16* __restrict__ Bt, int K,
;                                           int brow, int bcol, bool first, bool has_next, int nbrow, int nbcol, Epi epi) {
;     ...
;     STAGE(SB(0, 1), Bt, bcol + HALF, t + 2);
;     WAIT_V(6); BAR; MMA(1, 1, At, B1); BAR;
;     LDB(B0, 1, 0); SCHED; LDA(At, 1, 0); STAGE(SA(0, 1), A, brow + HALF, t + 2);
;     WAIT_L(8); BAR; WAIT_L(0); MMA(0, 0, At, B0); BAR; SCHED;
;     LDB(B1, 1, 1); STAGE(SB(1, 0), Bt, bcol, t + 3);
;     BAR; WAIT_L(0); MMA(0, 1, At, B1); BAR;
	v_lshl_add_u64 v[248:249], s[28:29], 0, v[140:141]
	v_readfirstlane_b32 s3, v151
	v_lshl_add_u64 v[166:167], v[248:249], 0, s[10:11]
	s_mov_b32 m0, s3
	v_lshl_add_u64 v[250:251], s[28:29], 0, v[142:143]
	global_load_lds_dwordx4 v[166:167], off
	v_add_u32_e32 v166, 0x2000, v151
	v_lshl_add_u64 v[168:169], v[250:251], 0, s[10:11]
	v_readfirstlane_b32 s3, v166
	s_mov_b32 m0, s3
	s_nop 0
	global_load_lds_dwordx4 v[168:169], off
	s_waitcnt vmcnt(6)
	s_barrier
	s_setprio 1
	v_mfma_f32_16x16x32_bf16 v[28:31], v[188:191], v[220:223], v[28:31]
	v_mfma_f32_16x16x32_bf16 v[24:27], v[188:191], v[228:231], v[24:27]
	v_mfma_f32_16x16x32_bf16 v[20:23], v[196:199], v[220:223], v[20:23]
	v_mfma_f32_16x16x32_bf16 v[16:19], v[196:199], v[228:231], v[16:19]
	v_mfma_f32_16x16x32_bf16 v[12:15], v[204:207], v[220:223], v[12:15]
	v_mfma_f32_16x16x32_bf16 v[8:11], v[204:207], v[228:231], v[8:11]
	v_mfma_f32_16x16x32_bf16 v[4:7], v[212:215], v[220:223], v[4:7]
	v_mfma_f32_16x16x32_bf16 v[0:3], v[212:215], v[228:231], v[0:3]
	v_mfma_f32_16x16x32_bf16 v[28:31], v[192:195], v[224:227], v[28:31]
	v_mfma_f32_16x16x32_bf16 v[24:27], v[192:195], v[232:235], v[24:27]
	v_mfma_f32_16x16x32_bf16 v[20:23], v[200:203], v[224:227], v[20:23]
	v_mfma_f32_16x16x32_bf16 v[16:19], v[200:203], v[232:235], v[16:19]
	v_mfma_f32_16x16x32_bf16 v[12:15], v[208:211], v[224:227], v[12:15]
	v_mfma_f32_16x16x32_bf16 v[8:11], v[208:211], v[232:235], v[8:11]
	v_mfma_f32_16x16x32_bf16 v[4:7], v[216:219], v[224:227], v[4:7]
	v_mfma_f32_16x16x32_bf16 v[0:3], v[216:219], v[232:235], v[0:3]
	s_setprio 0
	s_barrier
	ds_read_b128 v[176:179], v162
	ds_read_b128 v[180:183], v162 offset:1024
	ds_read_b128 v[184:187], v162 offset:2048
	ds_read_b128 v[188:191], v162 offset:3072
	v_readfirstlane_b32 s3, v150
	v_lshl_add_u64 v[168:169], v[170:171], 0, s[12:13]
	s_mov_b32 m0, s3
	v_readfirstlane_b32 s3, v149
	ds_read_b128 v[192:195], v159 offset:32768
	ds_read_b128 v[196:199], v159 offset:33792
	ds_read_b128 v[200:203], v158 offset:32768
	ds_read_b128 v[204:207], v158 offset:33792
	ds_read_b128 v[208:211], v157 offset:32768
	ds_read_b128 v[212:215], v157 offset:33792
	ds_read_b128 v[216:219], v156 offset:32768
	ds_read_b128 v[220:223], v156 offset:33792
	global_load_lds_dwordx4 v[168:169], off
	v_lshl_add_u64 v[168:169], v[236:237], 0, s[12:13]
	s_mov_b32 m0, s3
	s_nop 0
	global_load_lds_dwordx4 v[168:169], off
	s_waitcnt lgkmcnt(8)
	s_barrier
	s_waitcnt lgkmcnt(0)
	s_setprio 1
	v_mfma_f32_16x16x32_bf16 v[124:127], v[192:195], v[176:179], v[124:127]
	v_mfma_f32_16x16x32_bf16 v[120:123], v[192:195], v[184:187], v[120:123]
	v_mfma_f32_16x16x32_bf16 v[116:119], v[200:203], v[176:179], v[116:119]
	v_mfma_f32_16x16x32_bf16 v[112:115], v[200:203], v[184:187], v[112:115]
	v_mfma_f32_16x16x32_bf16 v[108:111], v[208:211], v[176:179], v[108:111]
	v_mfma_f32_16x16x32_bf16 v[104:107], v[208:211], v[184:187], v[104:107]
	v_mfma_f32_16x16x32_bf16 v[100:103], v[216:219], v[176:179], v[100:103]
	v_mfma_f32_16x16x32_bf16 v[96:99], v[216:219], v[184:187], v[96:99]
	v_mfma_f32_16x16x32_bf16 v[124:127], v[196:199], v[180:183], v[124:127]
	v_mfma_f32_16x16x32_bf16 v[120:123], v[196:199], v[188:191], v[120:123]
	v_mfma_f32_16x16x32_bf16 v[116:119], v[204:207], v[180:183], v[116:119]
	v_mfma_f32_16x16x32_bf16 v[112:115], v[204:207], v[188:191], v[112:115]
	v_mfma_f32_16x16x32_bf16 v[108:111], v[212:215], v[180:183], v[108:111]
	v_mfma_f32_16x16x32_bf16 v[104:107], v[212:215], v[188:191], v[104:107]
	v_mfma_f32_16x16x32_bf16 v[100:103], v[220:223], v[180:183], v[100:103]
	v_mfma_f32_16x16x32_bf16 v[96:99], v[220:223], v[188:191], v[96:99]
	s_setprio 0
	s_barrier
	v_add_u32_e32 v167, s84, v155
	v_lshl_add_u64 v[168:169], v[240:241], 0, s[14:15]
	v_readfirstlane_b32 s3, v167
	s_mov_b32 m0, s3
	ds_read_b128 v[224:227], v161
	ds_read_b128 v[228:231], v161 offset:1024
	ds_read_b128 v[232:235], v161 offset:2048
	ds_read_b128 v[236:239], v161 offset:3072
	global_load_lds_dwordx4 v[168:169], off
	v_add_u32_e32 v168, 0x2000, v167
	v_lshl_add_u64 v[170:171], v[242:243], 0, s[14:15]
	v_readfirstlane_b32 s3, v168
	s_mov_b32 m0, s3
	s_nop 0
	global_load_lds_dwordx4 v[170:171], off
	s_barrier
	s_waitcnt lgkmcnt(0)
	s_setprio 1
	v_mfma_f32_16x16x32_bf16 v[92:95], v[192:195], v[224:227], v[92:95]
	v_mfma_f32_16x16x32_bf16 v[88:91], v[192:195], v[232:235], v[88:91]
	v_mfma_f32_16x16x32_bf16 v[84:87], v[200:203], v[224:227], v[84:87]
	v_mfma_f32_16x16x32_bf16 v[80:83], v[200:203], v[232:235], v[80:83]
	v_mfma_f32_16x16x32_bf16 v[76:79], v[208:211], v[224:227], v[76:79]
	v_mfma_f32_16x16x32_bf16 v[72:75], v[208:211], v[232:235], v[72:75]
	v_mfma_f32_16x16x32_bf16 v[68:71], v[216:219], v[224:227], v[68:71]
	v_mfma_f32_16x16x32_bf16 v[64:67], v[216:219], v[232:235], v[64:67]
	v_mfma_f32_16x16x32_bf16 v[92:95], v[196:199], v[228:231], v[92:95]
	v_mfma_f32_16x16x32_bf16 v[88:91], v[196:199], v[236:239], v[88:91]
	v_mfma_f32_16x16x32_bf16 v[84:87], v[204:207], v[228:231], v[84:87]
	v_mfma_f32_16x16x32_bf16 v[80:83], v[204:207], v[236:239], v[80:83]
	v_mfma_f32_16x16x32_bf16 v[76:79], v[212:215], v[228:231], v[76:79]
	v_mfma_f32_16x16x32_bf16 v[72:75], v[212:215], v[236:239], v[72:75]
	v_mfma_f32_16x16x32_bf16 v[68:71], v[220:223], v[228:231], v[68:71]
	v_mfma_f32_16x16x32_bf16 v[64:67], v[220:223], v[236:239], v[64:67]
	s_setprio 0
	v_add_u32_e32 v169, 0x8000, v153
	v_lshl_add_u64 v[170:171], v[244:245], 0, s[16:17]
	v_readfirstlane_b32 s3, v169
	s_mov_b32 m0, s3
	s_barrier
; #define LDA(dst, b, h) for (int m = 0; m < 4; ++m) for (int k = 0; k < 2; ++k) \
;     dst[m][k] = *reinterpret_cast<const bf16x8*>((char*)SA(b, h) + lds_byte(wr * 64 + m * 16 + fr, k * 32 + fq * 8))
; #define LDB(dst, b, h) for (int n = 0; n < 2; ++n) for (int k = 0; k < 2; ++k) \
;     dst[n][k] = *reinterpret_cast<const bf16x8*>((char*)SB(b, h) + lds_byte(wc * 32 + n * 16 + fr, k * 32 + fq * 8))
; #define MMA(ai, bj, At, Bq) do { __builtin_amdgcn_s_setprio(1); \
;     for (int m = 0; m < 4; ++m) for (int n = 0; n < 2; ++n) for (int k = 0; k < 2; ++k) \
;       acc[ai][bj][m][n] = __builtin_amdgcn_mfma_f32_16x16x32_bf16(At[m][k], Bq[n][k], acc[ai][bj][m][n], 0, 0, 0); \
;     __builtin_amdgcn_s_setprio(0); } while (0)
; #define WAIT_V(n) asm volatile("s_waitcnt vmcnt(" #n ")" ::: "memory")
; #define WAIT_L(n) asm volatile("s_waitcnt lgkmcnt(" #n ")" ::: "memory")
; #define BAR __builtin_amdgcn_s_barrier()
; #define SCHED __builtin_amdgcn_sched_barrier(0)
; template <class Epi>
; __device__ __forceinline__ void gemm_tile(const u16* __restrict__ A, const u16* __restrict__ Bt, int K,
;                                           int brow, int bcol, bool first, bool has_next, int nbrow, int nbcol, Epi epi) {
;     ...
;     LDA(At, 1, 1); STAGE(SA(1, 0), A, brow, t + 3);
;     BAR; WAIT_L(0); MMA(1, 0, At, B0); BAR; SCHED;
;     STAGE(SB(1, 1), Bt, bcol + HALF, t + 3);
;     WAIT_V(6); BAR; MMA(1, 1, At, B1); BAR;
;   }
;   { LDB(B0, 0, 0); LDA(At, 0, 0); STAGE(SA(1, 1), A, brow + HALF, nt - 1);
;     BAR; WAIT_L(0); MMA(0, 0, At, B0); BAR;
;     LDB(B1, 0, 1); BAR; WAIT_L(0); MMA(0, 1, At, B1); BAR;
;     LDA(At, 0, 1); WAIT_V(4); BAR; WAIT_L(0); MMA(1, 0, At, B0); MMA(1, 1, At, B1); BAR; }
	ds_read_b128 v[192:195], v159 offset:49152
	ds_read_b128 v[196:199], v159 offset:50176
	ds_read_b128 v[200:203], v158 offset:49152
	ds_read_b128 v[204:207], v158 offset:50176
	ds_read_b128 v[208:211], v157 offset:49152
	ds_read_b128 v[212:215], v157 offset:50176
	ds_read_b128 v[216:219], v156 offset:49152
	ds_read_b128 v[220:223], v156 offset:50176
	global_load_lds_dwordx4 v[170:171], off
	v_add_u32_e32 v170, 0xa000, v153
	v_lshl_add_u64 v[240:241], v[246:247], 0, s[16:17]
	v_readfirstlane_b32 s3, v170
	s_mov_b32 m0, s3
	s_nop 0
	global_load_lds_dwordx4 v[240:241], off
	s_barrier
	s_waitcnt lgkmcnt(0)
	s_setprio 1
	v_mfma_f32_16x16x32_bf16 v[60:63], v[192:195], v[176:179], v[60:63]
	v_mfma_f32_16x16x32_bf16 v[56:59], v[192:195], v[184:187], v[56:59]
	v_mfma_f32_16x16x32_bf16 v[52:55], v[200:203], v[176:179], v[52:55]
	v_mfma_f32_16x16x32_bf16 v[48:51], v[200:203], v[184:187], v[48:51]
	v_mfma_f32_16x16x32_bf16 v[44:47], v[208:211], v[176:179], v[44:47]
	v_mfma_f32_16x16x32_bf16 v[40:43], v[208:211], v[184:187], v[40:43]
	v_mfma_f32_16x16x32_bf16 v[36:39], v[216:219], v[176:179], v[36:39]
	v_mfma_f32_16x16x32_bf16 v[32:35], v[216:219], v[184:187], v[32:35]
	v_mfma_f32_16x16x32_bf16 v[60:63], v[196:199], v[180:183], v[60:63]
	v_mfma_f32_16x16x32_bf16 v[56:59], v[196:199], v[188:191], v[56:59]
	v_mfma_f32_16x16x32_bf16 v[52:55], v[204:207], v[180:183], v[52:55]
	v_mfma_f32_16x16x32_bf16 v[48:51], v[204:207], v[188:191], v[48:51]
	v_mfma_f32_16x16x32_bf16 v[44:47], v[212:215], v[180:183], v[44:47]
	v_mfma_f32_16x16x32_bf16 v[40:43], v[212:215], v[188:191], v[40:43]
	v_mfma_f32_16x16x32_bf16 v[36:39], v[220:223], v[180:183], v[36:39]
	v_mfma_f32_16x16x32_bf16 v[32:35], v[220:223], v[188:191], v[32:35]
	s_setprio 0
	s_barrier
	v_add_u32_e32 v171, s85, v155
	v_add_u32_e32 v172, 0x2000, v171
	v_readfirstlane_b32 s3, v171
	v_lshl_add_u64 v[176:177], v[248:249], 0, s[14:15]
	s_mov_b32 m0, s3
	v_readfirstlane_b32 s3, v172
	global_load_lds_dwordx4 v[176:177], off
	v_lshl_add_u64 v[176:177], v[250:251], 0, s[14:15]
	s_mov_b32 m0, s3
	s_nop 0
	global_load_lds_dwordx4 v[176:177], off
	s_waitcnt vmcnt(6)
	s_barrier
	s_setprio 1
	v_mfma_f32_16x16x32_bf16 v[28:31], v[192:195], v[224:227], v[28:31]
	v_mfma_f32_16x16x32_bf16 v[24:27], v[192:195], v[232:235], v[24:27]
	v_mfma_f32_16x16x32_bf16 v[20:23], v[200:203], v[224:227], v[20:23]
	v_mfma_f32_16x16x32_bf16 v[16:19], v[200:203], v[232:235], v[16:19]
	v_mfma_f32_16x16x32_bf16 v[12:15], v[208:211], v[224:227], v[12:15]
	v_mfma_f32_16x16x32_bf16 v[8:11], v[208:211], v[232:235], v[8:11]
	v_mfma_f32_16x16x32_bf16 v[4:7], v[216:219], v[224:227], v[4:7]
	v_mfma_f32_16x16x32_bf16 v[0:3], v[216:219], v[232:235], v[0:3]
	v_mfma_f32_16x16x32_bf16 v[28:31], v[196:199], v[228:231], v[28:31]
	v_mfma_f32_16x16x32_bf16 v[24:27], v[196:199], v[236:239], v[24:27]
	v_mfma_f32_16x16x32_bf16 v[20:23], v[204:207], v[228:231], v[20:23]
	v_mfma_f32_16x16x32_bf16 v[16:19], v[204:207], v[236:239], v[16:19]
	v_mfma_f32_16x16x32_bf16 v[12:15], v[212:215], v[228:231], v[12:15]
	v_mfma_f32_16x16x32_bf16 v[8:11], v[212:215], v[236:239], v[8:11]
	v_mfma_f32_16x16x32_bf16 v[4:7], v[220:223], v[228:231], v[4:7]
	v_mfma_f32_16x16x32_bf16 v[0:3], v[220:223], v[236:239], v[0:3]
	s_setprio 0
	s_add_i32 s1, s1, 2
	s_add_u32 s28, s28, 0x100
	s_addc_u32 s29, s29, 0
	s_cmp_lt_u32 s1, 12
	s_barrier
	s_cbranch_scc1 .LBB0_457
	s_add_u32 s26, s34, s26
	s_addc_u32 s27, s35, s27
	v_lshl_add_u64 v[208:209], s[26:27], 0, v[128:129]
	v_readfirstlane_b32 s1, v173
	v_lshl_add_u64 v[208:209], v[208:209], 0, s[18:19]
	s_mov_b32 m0, s1
	ds_read_b128 v[132:135], v164
	ds_read_b128 v[136:139], v164 offset:1024
	ds_read_b128 v[140:143], v164 offset:2048
	ds_read_b128 v[144:147], v164 offset:3072
	ds_read_b128 v[176:179], v159
	ds_read_b128 v[180:183], v159 offset:1024
	ds_read_b128 v[184:187], v158
	ds_read_b128 v[188:191], v158 offset:1024
	ds_read_b128 v[192:195], v157
	ds_read_b128 v[196:199], v157 offset:1024
	ds_read_b128 v[200:203], v156
	ds_read_b128 v[204:207], v156 offset:1024
	global_load_lds_dwordx4 v[208:209], off
	v_lshl_add_u64 v[208:209], s[26:27], 0, v[130:131]
	v_readfirstlane_b32 s1, v174
	v_lshl_add_u64 v[208:209], v[208:209], 0, s[18:19]
	s_mov_b32 m0, s1
	s_nop 0
	global_load_lds_dwordx4 v[208:209], off
	s_barrier
	s_waitcnt lgkmcnt(0)
	s_setprio 1
	s_waitcnt lgkmcnt(0)
	v_mfma_f32_16x16x32_bf16 v[124:127], v[176:179], v[132:135], v[124:127]
	v_mfma_f32_16x16x32_bf16 v[120:123], v[176:179], v[140:143], v[120:123]
	v_mfma_f32_16x16x32_bf16 v[116:119], v[184:187], v[132:135], v[116:119]
	v_mfma_f32_16x16x32_bf16 v[112:115], v[184:187], v[140:143], v[112:115]
	v_mfma_f32_16x16x32_bf16 v[100:103], v[200:203], v[132:135], v[100:103]
	v_mfma_f32_16x16x32_bf16 v[96:99], v[200:203], v[140:143], v[96:99]
	v_mfma_f32_16x16x32_bf16 v[124:127], v[180:183], v[136:139], v[124:127]
	v_mfma_f32_16x16x32_bf16 v[120:123], v[180:183], v[144:147], v[120:123]
	v_mfma_f32_16x16x32_bf16 v[116:119], v[188:191], v[136:139], v[116:119]
	v_mfma_f32_16x16x32_bf16 v[112:115], v[188:191], v[144:147], v[112:115]
	v_mfma_f32_16x16x32_bf16 v[108:111], v[192:195], v[132:135], v[108:111]
	v_mfma_f32_16x16x32_bf16 v[104:107], v[192:195], v[140:143], v[104:107]
	v_mfma_f32_16x16x32_bf16 v[100:103], v[204:207], v[136:139], v[100:103]
	v_mfma_f32_16x16x32_bf16 v[96:99], v[204:207], v[144:147], v[96:99]
	v_mfma_f32_16x16x32_bf16 v[208:211], v[196:199], v[136:139], v[108:111]
	v_mfma_f32_16x16x32_bf16 v[212:215], v[196:199], v[144:147], v[104:107]
	s_setprio 0
	s_barrier
	s_nop 1
	ds_read_b128 v[104:107], v163
	ds_read_b128 v[108:111], v163 offset:1024
	ds_read_b128 v[216:219], v163 offset:2048
	ds_read_b128 v[220:223], v163 offset:3072
	s_barrier
; #define LDA(dst, b, h) for (int m = 0; m < 4; ++m) for (int k = 0; k < 2; ++k) \
;     dst[m][k] = *reinterpret_cast<const bf16x8*>((char*)SA(b, h) + lds_byte(wr * 64 + m * 16 + fr, k * 32 + fq * 8))
; #define LDB(dst, b, h) for (int n = 0; n < 2; ++n) for (int k = 0; k < 2; ++k) \
;     dst[n][k] = *reinterpret_cast<const bf16x8*>((char*)SB(b, h) + lds_byte(wc * 32 + n * 16 + fr, k * 32 + fq * 8))
; #define MMA(ai, bj, At, Bq) do { __builtin_amdgcn_s_setprio(1); \
;     for (int m = 0; m < 4; ++m) for (int n = 0; n < 2; ++n) for (int k = 0; k < 2; ++k) \
;       acc[ai][bj][m][n] = __builtin_amdgcn_mfma_f32_16x16x32_bf16(At[m][k], Bq[n][k], acc[ai][bj][m][n], 0, 0, 0); \
;     __builtin_amdgcn_s_setprio(0); } while (0)
; #define WAIT_V(n) asm volatile("s_waitcnt vmcnt(" #n ")" ::: "memory")
; #define WAIT_L(n) asm volatile("s_waitcnt lgkmcnt(" #n ")" ::: "memory")
; #define BAR __builtin_amdgcn_s_barrier()
; template <class Epi>
; __device__ __forceinline__ void gemm_tile(const u16* __restrict__ A, const u16* __restrict__ Bt, int K,
;                                           int brow, int bcol, bool first, bool has_next, int nbrow, int nbcol, Epi epi) {
;     ...
;     BAR; WAIT_L(0); MMA(0, 0, At, B0); BAR;
;     LDB(B1, 0, 1); BAR; WAIT_L(0); MMA(0, 1, At, B1); BAR;
;     LDA(At, 0, 1); WAIT_V(4); BAR; WAIT_L(0); MMA(1, 0, At, B0); MMA(1, 1, At, B1); BAR; }
;   { LDB(B0, 1, 0); LDA(At, 1, 0); WAIT_V(2); BAR; WAIT_L(0); MMA(0, 0, At, B0); BAR;
	s_waitcnt lgkmcnt(0)
	s_setprio 1
	s_waitcnt lgkmcnt(0)
	v_mfma_f32_16x16x32_bf16 v[84:87], v[184:187], v[104:107], v[84:87]
	v_mfma_f32_16x16x32_bf16 v[80:83], v[184:187], v[216:219], v[80:83]
	v_mfma_f32_16x16x32_bf16 v[68:71], v[200:203], v[104:107], v[68:71]
	v_mfma_f32_16x16x32_bf16 v[64:67], v[200:203], v[216:219], v[64:67]
	v_mfma_f32_16x16x32_bf16 v[92:95], v[176:179], v[104:107], v[92:95]
	v_mfma_f32_16x16x32_bf16 v[88:91], v[176:179], v[216:219], v[88:91]
	v_mfma_f32_16x16x32_bf16 v[84:87], v[188:191], v[108:111], v[84:87]
	v_mfma_f32_16x16x32_bf16 v[80:83], v[188:191], v[220:223], v[80:83]
	v_mfma_f32_16x16x32_bf16 v[76:79], v[192:195], v[104:107], v[76:79]
	v_mfma_f32_16x16x32_bf16 v[72:75], v[192:195], v[216:219], v[72:75]
	v_mfma_f32_16x16x32_bf16 v[68:71], v[204:207], v[108:111], v[68:71]
	v_mfma_f32_16x16x32_bf16 v[64:67], v[204:207], v[220:223], v[64:67]
	v_mfma_f32_16x16x32_bf16 v[224:227], v[180:183], v[108:111], v[92:95]
	v_mfma_f32_16x16x32_bf16 v[174:177], v[180:183], v[220:223], v[88:91]
	v_mfma_f32_16x16x32_bf16 v[178:181], v[196:199], v[108:111], v[76:79]
	v_mfma_f32_16x16x32_bf16 v[182:185], v[196:199], v[220:223], v[72:75]
	s_setprio 0
	s_barrier
	s_nop 0
	ds_read_b128 v[72:75], v159 offset:16384
	ds_read_b128 v[76:79], v159 offset:17408
	ds_read_b128 v[88:91], v158 offset:16384
	ds_read_b128 v[92:95], v158 offset:17408
	ds_read_b128 v[186:189], v157 offset:16384
	ds_read_b128 v[190:193], v157 offset:17408
	ds_read_b128 v[194:197], v156 offset:16384
	ds_read_b128 v[198:201], v156 offset:17408
	s_waitcnt vmcnt(4)
	s_barrier
	s_waitcnt lgkmcnt(0)
	s_setprio 1
	s_waitcnt lgkmcnt(0)
	v_mfma_f32_16x16x32_bf16 v[60:63], v[72:75], v[132:135], v[60:63]
	v_mfma_f32_16x16x32_bf16 v[56:59], v[72:75], v[140:143], v[56:59]
	v_mfma_f32_16x16x32_bf16 v[52:55], v[88:91], v[132:135], v[52:55]
	v_mfma_f32_16x16x32_bf16 v[48:51], v[88:91], v[140:143], v[48:51]
	v_mfma_f32_16x16x32_bf16 v[36:39], v[194:197], v[132:135], v[36:39]
	v_mfma_f32_16x16x32_bf16 v[32:35], v[194:197], v[140:143], v[32:35]
	v_mfma_f32_16x16x32_bf16 v[60:63], v[76:79], v[136:139], v[60:63]
	v_mfma_f32_16x16x32_bf16 v[56:59], v[76:79], v[144:147], v[56:59]
	v_mfma_f32_16x16x32_bf16 v[52:55], v[92:95], v[136:139], v[52:55]
	v_mfma_f32_16x16x32_bf16 v[48:51], v[92:95], v[144:147], v[48:51]
	v_mfma_f32_16x16x32_bf16 v[44:47], v[186:189], v[132:135], v[44:47]
	v_mfma_f32_16x16x32_bf16 v[40:43], v[186:189], v[140:143], v[40:43]
	v_mfma_f32_16x16x32_bf16 v[36:39], v[198:201], v[136:139], v[36:39]
	v_mfma_f32_16x16x32_bf16 v[32:35], v[198:201], v[144:147], v[32:35]
	v_mfma_f32_16x16x32_bf16 v[202:205], v[190:193], v[136:139], v[44:47]
	v_mfma_f32_16x16x32_bf16 v[228:231], v[190:193], v[144:147], v[40:43]
	s_setprio 0
	s_setprio 1
	v_mfma_f32_16x16x32_bf16 v[20:23], v[88:91], v[104:107], v[20:23]
	v_mfma_f32_16x16x32_bf16 v[16:19], v[88:91], v[216:219], v[16:19]
	v_mfma_f32_16x16x32_bf16 v[4:7], v[194:197], v[104:107], v[4:7]
	v_mfma_f32_16x16x32_bf16 v[0:3], v[194:197], v[216:219], v[0:3]
	v_mfma_f32_16x16x32_bf16 v[28:31], v[72:75], v[104:107], v[28:31]
	v_mfma_f32_16x16x32_bf16 v[24:27], v[72:75], v[216:219], v[24:27]
	v_mfma_f32_16x16x32_bf16 v[20:23], v[92:95], v[108:111], v[20:23]
	v_mfma_f32_16x16x32_bf16 v[16:19], v[92:95], v[220:223], v[16:19]
	v_mfma_f32_16x16x32_bf16 v[12:15], v[186:189], v[104:107], v[12:15]
	v_mfma_f32_16x16x32_bf16 v[8:11], v[186:189], v[216:219], v[8:11]
	v_mfma_f32_16x16x32_bf16 v[4:7], v[198:201], v[108:111], v[4:7]
	v_mfma_f32_16x16x32_bf16 v[0:3], v[198:201], v[220:223], v[0:3]
	v_mfma_f32_16x16x32_bf16 v[132:135], v[76:79], v[108:111], v[28:31]
	v_mfma_f32_16x16x32_bf16 v[136:139], v[76:79], v[220:223], v[24:27]
	v_mfma_f32_16x16x32_bf16 v[140:143], v[190:193], v[108:111], v[12:15]
	v_mfma_f32_16x16x32_bf16 v[144:147], v[190:193], v[220:223], v[8:11]
	s_setprio 0
	s_barrier
	s_nop 0
	ds_read_b128 v[8:11], v162
	ds_read_b128 v[12:15], v162 offset:1024
	ds_read_b128 v[186:189], v162 offset:2048
	ds_read_b128 v[190:193], v162 offset:3072
	ds_read_b128 v[24:27], v159 offset:32768
	ds_read_b128 v[28:31], v159 offset:33792
	ds_read_b128 v[40:43], v158 offset:32768
	ds_read_b128 v[44:47], v158 offset:33792
	ds_read_b128 v[194:197], v157 offset:32768
	ds_read_b128 v[198:201], v157 offset:33792
	ds_read_b128 v[216:219], v156 offset:32768
	ds_read_b128 v[220:223], v156 offset:33792
	s_waitcnt vmcnt(2)
	s_barrier
; #define LDA(dst, b, h) for (int m = 0; m < 4; ++m) for (int k = 0; k < 2; ++k) \
;     dst[m][k] = *reinterpret_cast<const bf16x8*>((char*)SA(b, h) + lds_byte(wr * 64 + m * 16 + fr, k * 32 + fq * 8))
; #define LDB(dst, b, h) for (int n = 0; n < 2; ++n) for (int k = 0; k < 2; ++k) \
;     dst[n][k] = *reinterpret_cast<const bf16x8*>((char*)SB(b, h) + lds_byte(wc * 32 + n * 16 + fr, k * 32 + fq * 8))
; #define MMA(ai, bj, At, Bq) do { __builtin_amdgcn_s_setprio(1); \
;     for (int m = 0; m < 4; ++m) for (int n = 0; n < 2; ++n) for (int k = 0; k < 2; ++k) \
;       acc[ai][bj][m][n] = __builtin_amdgcn_mfma_f32_16x16x32_bf16(At[m][k], Bq[n][k], acc[ai][bj][m][n], 0, 0, 0); \
;     __builtin_amdgcn_s_setprio(0); } while (0)
; #define WAIT_V(n) asm volatile("s_waitcnt vmcnt(" #n ")" ::: "memory")
; #define WAIT_L(n) asm volatile("s_waitcnt lgkmcnt(" #n ")" ::: "memory")
; #define BAR __builtin_amdgcn_s_barrier()
; template <class Epi>
; __device__ __forceinline__ void gemm_tile(const u16* __restrict__ A, const u16* __restrict__ Bt, int K,
;                                           int brow, int bcol, bool first, bool has_next, int nbrow, int nbcol, Epi epi) {
;     ...
;   { LDB(B0, 1, 0); LDA(At, 1, 0); WAIT_V(2); BAR; WAIT_L(0); MMA(0, 0, At, B0); BAR;
;     LDB(B1, 1, 1); WAIT_V(0); BAR; WAIT_L(0); MMA(0, 1, At, B1); BAR;
;     LDA(At, 1, 1); BAR; WAIT_L(0); MMA(1, 0, At, B0); MMA(1, 1, At, B1); BAR; }
;   if (wr == 0) BAR;
	s_waitcnt lgkmcnt(0)
	s_setprio 1
	s_waitcnt lgkmcnt(0)
	v_mfma_f32_16x16x32_bf16 v[72:75], v[24:27], v[8:11], v[124:127]
	v_mfma_f32_16x16x32_bf16 v[124:127], v[28:31], v[12:15], v[72:75]
	v_mfma_f32_16x16x32_bf16 v[72:75], v[24:27], v[186:189], v[120:123]
	v_mfma_f32_16x16x32_bf16 v[120:123], v[28:31], v[190:193], v[72:75]
	v_mfma_f32_16x16x32_bf16 v[72:75], v[40:43], v[8:11], v[116:119]
	v_mfma_f32_16x16x32_bf16 v[108:111], v[44:47], v[12:15], v[72:75]
	v_mfma_f32_16x16x32_bf16 v[72:75], v[40:43], v[186:189], v[112:115]
	v_mfma_f32_16x16x32_bf16 v[104:107], v[44:47], v[190:193], v[72:75]
	v_mfma_f32_16x16x32_bf16 v[72:75], v[194:197], v[8:11], v[208:211]
	v_mfma_f32_16x16x32_bf16 v[92:95], v[198:201], v[12:15], v[72:75]
	v_mfma_f32_16x16x32_bf16 v[72:75], v[194:197], v[186:189], v[212:215]
	v_mfma_f32_16x16x32_bf16 v[88:91], v[198:201], v[190:193], v[72:75]
	v_mfma_f32_16x16x32_bf16 v[72:75], v[216:219], v[8:11], v[100:103]
	v_mfma_f32_16x16x32_bf16 v[76:79], v[220:223], v[12:15], v[72:75]
	v_mfma_f32_16x16x32_bf16 v[72:75], v[216:219], v[186:189], v[96:99]
	v_mfma_f32_16x16x32_bf16 v[72:75], v[220:223], v[190:193], v[72:75]
	s_setprio 0
	s_barrier
	ds_read_b128 v[206:209], v161
	ds_read_b128 v[210:213], v161 offset:1024
	ds_read_b128 v[232:235], v161 offset:2048
	ds_read_b128 v[236:239], v161 offset:3072
	s_waitcnt vmcnt(0)
	s_barrier
	s_waitcnt lgkmcnt(0)
	s_setprio 1
	s_waitcnt lgkmcnt(0)
	v_mfma_f32_16x16x32_bf16 v[96:99], v[24:27], v[206:209], v[224:227]
	v_mfma_f32_16x16x32_bf16 v[24:27], v[24:27], v[232:235], v[174:177]
	v_mfma_f32_16x16x32_bf16 v[112:115], v[28:31], v[236:239], v[24:27]
	v_mfma_f32_16x16x32_bf16 v[24:27], v[40:43], v[206:209], v[84:87]
	v_mfma_f32_16x16x32_bf16 v[100:103], v[44:47], v[210:213], v[24:27]
	v_mfma_f32_16x16x32_bf16 v[24:27], v[40:43], v[232:235], v[80:83]
	v_mfma_f32_16x16x32_bf16 v[116:119], v[28:31], v[210:213], v[96:99]
	v_mfma_f32_16x16x32_bf16 v[96:99], v[44:47], v[236:239], v[24:27]
	v_mfma_f32_16x16x32_bf16 v[24:27], v[194:197], v[206:209], v[178:181]
	v_mfma_f32_16x16x32_bf16 v[84:87], v[198:201], v[210:213], v[24:27]
	v_mfma_f32_16x16x32_bf16 v[24:27], v[194:197], v[232:235], v[182:185]
	v_mfma_f32_16x16x32_bf16 v[80:83], v[198:201], v[236:239], v[24:27]
	v_mfma_f32_16x16x32_bf16 v[24:27], v[216:219], v[206:209], v[68:71]
	v_mfma_f32_16x16x32_bf16 v[68:71], v[220:223], v[210:213], v[24:27]
	v_mfma_f32_16x16x32_bf16 v[24:27], v[216:219], v[232:235], v[64:67]
	v_mfma_f32_16x16x32_bf16 v[64:67], v[220:223], v[236:239], v[24:27]
	s_setprio 0
	s_barrier
	ds_read_b128 v[174:177], v159 offset:49152
	ds_read_b128 v[178:181], v159 offset:50176
	ds_read_b128 v[182:185], v158 offset:49152
	ds_read_b128 v[194:197], v158 offset:50176
	ds_read_b128 v[198:201], v157 offset:49152
	ds_read_b128 v[214:217], v157 offset:50176
	ds_read_b128 v[218:221], v156 offset:49152
	ds_read_b128 v[156:159], v156 offset:50176
	s_barrier
	s_waitcnt lgkmcnt(0)
	s_setprio 1
	s_waitcnt lgkmcnt(0)
	v_mfma_f32_16x16x32_bf16 v[24:27], v[174:177], v[8:11], v[60:63]
	v_mfma_f32_16x16x32_bf16 v[60:63], v[178:181], v[12:15], v[24:27]
	v_mfma_f32_16x16x32_bf16 v[24:27], v[174:177], v[186:189], v[56:59]
	v_mfma_f32_16x16x32_bf16 v[56:59], v[178:181], v[190:193], v[24:27]
	v_mfma_f32_16x16x32_bf16 v[24:27], v[182:185], v[8:11], v[52:55]
	v_mfma_f32_16x16x32_bf16 v[44:47], v[194:197], v[12:15], v[24:27]
	v_mfma_f32_16x16x32_bf16 v[24:27], v[182:185], v[186:189], v[48:51]
	v_mfma_f32_16x16x32_bf16 v[40:43], v[194:197], v[190:193], v[24:27]
	v_mfma_f32_16x16x32_bf16 v[24:27], v[198:201], v[8:11], v[202:205]
	v_mfma_f32_16x16x32_bf16 v[8:11], v[218:221], v[8:11], v[36:39]
	v_mfma_f32_16x16x32_bf16 v[28:31], v[214:217], v[12:15], v[24:27]
	v_mfma_f32_16x16x32_bf16 v[24:27], v[198:201], v[186:189], v[228:231]
	v_mfma_f32_16x16x32_bf16 v[12:15], v[156:159], v[12:15], v[8:11]
	v_mfma_f32_16x16x32_bf16 v[8:11], v[218:221], v[186:189], v[32:35]
	v_mfma_f32_16x16x32_bf16 v[24:27], v[214:217], v[190:193], v[24:27]
	v_mfma_f32_16x16x32_bf16 v[8:11], v[156:159], v[190:193], v[8:11]
	s_setprio 0
	s_setprio 1
	v_mfma_f32_16x16x32_bf16 v[32:35], v[174:177], v[206:209], v[132:135]
	v_mfma_f32_16x16x32_bf16 v[52:55], v[178:181], v[210:213], v[32:35]
	v_mfma_f32_16x16x32_bf16 v[32:35], v[174:177], v[232:235], v[136:139]
	v_mfma_f32_16x16x32_bf16 v[16:19], v[182:185], v[232:235], v[16:19]
	v_mfma_f32_16x16x32_bf16 v[48:51], v[178:181], v[236:239], v[32:35]
	v_mfma_f32_16x16x32_bf16 v[20:23], v[182:185], v[206:209], v[20:23]
	v_mfma_f32_16x16x32_bf16 v[32:35], v[194:197], v[236:239], v[16:19]
	v_mfma_f32_16x16x32_bf16 v[16:19], v[198:201], v[206:209], v[140:143]
	v_mfma_f32_16x16x32_bf16 v[36:39], v[194:197], v[210:213], v[20:23]
	v_mfma_f32_16x16x32_bf16 v[20:23], v[214:217], v[210:213], v[16:19]
	v_mfma_f32_16x16x32_bf16 v[16:19], v[198:201], v[232:235], v[144:147]
	v_mfma_f32_16x16x32_bf16 v[4:7], v[218:221], v[206:209], v[4:7]
	v_mfma_f32_16x16x32_bf16 v[0:3], v[218:221], v[232:235], v[0:3]
	v_mfma_f32_16x16x32_bf16 v[16:19], v[214:217], v[236:239], v[16:19]
	v_mfma_f32_16x16x32_bf16 v[4:7], v[156:159], v[210:213], v[4:7]
	v_mfma_f32_16x16x32_bf16 v[0:3], v[156:159], v[236:239], v[0:3]
	s_setprio 0
	v_cmp_gt_u32_e32 vcc, s62, v148
	s_barrier
	s_and_saveexec_b64 s[26:27], vcc
	s_cbranch_execz .LBB0_460
	s_barrier

; #define LDA(dst, b, h) for (int m = 0; m < 4; ++m) for (int k = 0; k < 2; ++k) \
;     dst[m][k] = *reinterpret_cast<const bf16x8*>((char*)SA(b, h) + lds_byte(wr * 64 + m * 16 + fr, k * 32 + fq * 8))
; #define LDB(dst, b, h) for (int n = 0; n < 2; ++n) for (int k = 0; k < 2; ++k) \
;     dst[n][k] = *reinterpret_cast<const bf16x8*>((char*)SB(b, h) + lds_byte(wc * 32 + n * 16 + fr, k * 32 + fq * 8))
; #define MMA(ai, bj, At, Bq) do { __builtin_amdgcn_s_setprio(1); \
;     for (int m = 0; m < 4; ++m) for (int n = 0; n < 2; ++n) for (int k = 0; k < 2; ++k) \
;       acc[ai][bj][m][n] = __builtin_amdgcn_mfma_f32_16x16x32_bf16(At[m][k], Bq[n][k], acc[ai][bj][m][n], 0, 0, 0); \
;     __builtin_amdgcn_s_setprio(0); } while (0)
; #define WAIT_L(n) asm volatile("s_waitcnt lgkmcnt(" #n ")" ::: "memory")
; #define BAR __builtin_amdgcn_s_barrier()
; #define SCHED __builtin_amdgcn_sched_barrier(0)
; template <class Epi>
; __device__ __forceinline__ void gemm_tile(const u16* __restrict__ A, const u16* __restrict__ Bt, int K,
;                                           int brow, int bcol, bool first, bool has_next, int nbrow, int nbcol, Epi epi) {
;     ...
;     LDB(B0, 0, 0); SCHED; LDA(At, 0, 0); STAGE(SA(1, 1), A, brow + HALF, t + 1);
;     WAIT_L(8); BAR; WAIT_L(0); MMA(0, 0, At, B0); BAR; SCHED;
;     LDB(B1, 0, 1); STAGE(SB(0, 0), Bt, bcol, t + 2);
;     BAR; WAIT_L(0); MMA(0, 1, At, B1); BAR;
;     LDA(At, 0, 1); STAGE(SA(0, 0), A, brow, t + 2);
;     BAR; WAIT_L(0); MMA(1, 0, At, B0); BAR; SCHED;
.LBB0_592:
	ds_read_b128 v[166:169], v164
	ds_read_b128 v[176:179], v164 offset:1024
	ds_read_b128 v[180:183], v164 offset:2048
	ds_read_b128 v[184:187], v164 offset:3072
	v_add_u32_e32 v173, 0xc000, v153
	v_lshl_add_u64 v[170:171], s[40:41], 0, v[144:145]
	v_readfirstlane_b32 s3, v173
	v_lshl_add_u64 v[174:175], v[170:171], 0, s[12:13]
	s_mov_b32 m0, s3
	ds_read_b128 v[188:191], v159
	ds_read_b128 v[192:195], v159 offset:1024
	ds_read_b128 v[196:199], v158
	ds_read_b128 v[200:203], v158 offset:1024
	ds_read_b128 v[204:207], v157
	ds_read_b128 v[208:211], v157 offset:1024
	ds_read_b128 v[212:215], v156
	ds_read_b128 v[216:219], v156 offset:1024
	global_load_lds_dwordx4 v[174:175], off
	v_add_u32_e32 v174, 0xe000, v153
	v_lshl_add_u64 v[236:237], s[40:41], 0, v[146:147]
	v_readfirstlane_b32 s3, v174
	v_lshl_add_u64 v[220:221], v[236:237], 0, s[12:13]
	s_mov_b32 m0, s3
	s_nop 0
	global_load_lds_dwordx4 v[220:221], off
	s_waitcnt lgkmcnt(8)
	s_barrier
	s_waitcnt lgkmcnt(0)
	s_setprio 1
	v_mfma_f32_16x16x32_bf16 v[124:127], v[188:191], v[166:169], v[124:127]
	v_mfma_f32_16x16x32_bf16 v[120:123], v[188:191], v[180:183], v[120:123]
	v_mfma_f32_16x16x32_bf16 v[116:119], v[196:199], v[166:169], v[116:119]
	v_mfma_f32_16x16x32_bf16 v[112:115], v[196:199], v[180:183], v[112:115]
	v_mfma_f32_16x16x32_bf16 v[108:111], v[204:207], v[166:169], v[108:111]
	v_mfma_f32_16x16x32_bf16 v[104:107], v[204:207], v[180:183], v[104:107]
	v_mfma_f32_16x16x32_bf16 v[100:103], v[212:215], v[166:169], v[100:103]
	v_mfma_f32_16x16x32_bf16 v[96:99], v[212:215], v[180:183], v[96:99]
	v_mfma_f32_16x16x32_bf16 v[124:127], v[192:195], v[176:179], v[124:127]
	v_mfma_f32_16x16x32_bf16 v[120:123], v[192:195], v[184:187], v[120:123]
	v_mfma_f32_16x16x32_bf16 v[116:119], v[200:203], v[176:179], v[116:119]
	v_mfma_f32_16x16x32_bf16 v[112:115], v[200:203], v[184:187], v[112:115]
	v_mfma_f32_16x16x32_bf16 v[108:111], v[208:211], v[176:179], v[108:111]
	v_mfma_f32_16x16x32_bf16 v[104:107], v[208:211], v[184:187], v[104:107]
	v_mfma_f32_16x16x32_bf16 v[100:103], v[216:219], v[176:179], v[100:103]
	v_mfma_f32_16x16x32_bf16 v[96:99], v[216:219], v[184:187], v[96:99]
	s_setprio 0
	s_barrier
	v_lshl_add_u64 v[240:241], s[40:41], 0, v[132:133]
	v_readfirstlane_b32 s3, v154
	v_add_u32_e32 v165, 0x2000, v154
	v_lshl_add_u64 v[238:239], v[240:241], 0, s[14:15]
	s_mov_b32 m0, s3
	v_lshl_add_u64 v[242:243], s[40:41], 0, v[134:135]
	v_readfirstlane_b32 s3, v165
	ds_read_b128 v[220:223], v163
	ds_read_b128 v[224:227], v163 offset:1024
	ds_read_b128 v[228:231], v163 offset:2048
	ds_read_b128 v[232:235], v163 offset:3072
	global_load_lds_dwordx4 v[238:239], off
	v_lshl_add_u64 v[238:239], v[242:243], 0, s[14:15]
	s_mov_b32 m0, s3
	s_nop 0
	global_load_lds_dwordx4 v[238:239], off
	s_barrier
	s_waitcnt lgkmcnt(0)
	s_setprio 1
	v_mfma_f32_16x16x32_bf16 v[92:95], v[188:191], v[220:223], v[92:95]
	v_mfma_f32_16x16x32_bf16 v[88:91], v[188:191], v[228:231], v[88:91]
	v_mfma_f32_16x16x32_bf16 v[84:87], v[196:199], v[220:223], v[84:87]
	v_mfma_f32_16x16x32_bf16 v[80:83], v[196:199], v[228:231], v[80:83]
	v_mfma_f32_16x16x32_bf16 v[76:79], v[204:207], v[220:223], v[76:79]
	v_mfma_f32_16x16x32_bf16 v[72:75], v[204:207], v[228:231], v[72:75]
	v_mfma_f32_16x16x32_bf16 v[68:71], v[212:215], v[220:223], v[68:71]
	v_mfma_f32_16x16x32_bf16 v[64:67], v[212:215], v[228:231], v[64:67]
	v_mfma_f32_16x16x32_bf16 v[92:95], v[192:195], v[224:227], v[92:95]
	v_mfma_f32_16x16x32_bf16 v[88:91], v[192:195], v[232:235], v[88:91]
	v_mfma_f32_16x16x32_bf16 v[84:87], v[200:203], v[224:227], v[84:87]
	v_mfma_f32_16x16x32_bf16 v[80:83], v[200:203], v[232:235], v[80:83]
	v_mfma_f32_16x16x32_bf16 v[76:79], v[208:211], v[224:227], v[76:79]
	v_mfma_f32_16x16x32_bf16 v[72:75], v[208:211], v[232:235], v[72:75]
	v_mfma_f32_16x16x32_bf16 v[68:71], v[216:219], v[224:227], v[68:71]
	v_mfma_f32_16x16x32_bf16 v[64:67], v[216:219], v[232:235], v[64:67]
	s_setprio 0
	v_lshl_add_u64 v[244:245], s[40:41], 0, v[136:137]
	v_readfirstlane_b32 s3, v153
	v_lshl_add_u64 v[238:239], v[244:245], 0, s[16:17]
	s_mov_b32 m0, s3
	v_lshl_add_u64 v[246:247], s[40:41], 0, v[138:139]
	v_readfirstlane_b32 s3, v152
	s_barrier
	ds_read_b128 v[188:191], v159 offset:16384
	ds_read_b128 v[192:195], v159 offset:17408
	ds_read_b128 v[196:199], v158 offset:16384
	ds_read_b128 v[200:203], v158 offset:17408
	ds_read_b128 v[204:207], v157 offset:16384
	ds_read_b128 v[208:211], v157 offset:17408
	ds_read_b128 v[212:215], v156 offset:16384
	ds_read_b128 v[216:219], v156 offset:17408
	global_load_lds_dwordx4 v[238:239], off
	v_lshl_add_u64 v[238:239], v[246:247], 0, s[16:17]
	s_mov_b32 m0, s3
	s_nop 0
	global_load_lds_dwordx4 v[238:239], off
	s_barrier
	s_waitcnt lgkmcnt(0)
	s_setprio 1
	v_mfma_f32_16x16x32_bf16 v[60:63], v[188:191], v[166:169], v[60:63]
	v_mfma_f32_16x16x32_bf16 v[56:59], v[188:191], v[180:183], v[56:59]
	v_mfma_f32_16x16x32_bf16 v[52:55], v[196:199], v[166:169], v[52:55]
	v_mfma_f32_16x16x32_bf16 v[48:51], v[196:199], v[180:183], v[48:51]
	v_mfma_f32_16x16x32_bf16 v[44:47], v[204:207], v[166:169], v[44:47]
	v_mfma_f32_16x16x32_bf16 v[40:43], v[204:207], v[180:183], v[40:43]
	v_mfma_f32_16x16x32_bf16 v[36:39], v[212:215], v[166:169], v[36:39]
	v_mfma_f32_16x16x32_bf16 v[32:35], v[212:215], v[180:183], v[32:35]
	v_mfma_f32_16x16x32_bf16 v[60:63], v[192:195], v[176:179], v[60:63]
	v_mfma_f32_16x16x32_bf16 v[56:59], v[192:195], v[184:187], v[56:59]
	v_mfma_f32_16x16x32_bf16 v[52:55], v[200:203], v[176:179], v[52:55]
	v_mfma_f32_16x16x32_bf16 v[48:51], v[200:203], v[184:187], v[48:51]
	v_mfma_f32_16x16x32_bf16 v[44:47], v[208:211], v[176:179], v[44:47]
	v_mfma_f32_16x16x32_bf16 v[40:43], v[208:211], v[184:187], v[40:43]
	v_mfma_f32_16x16x32_bf16 v[36:39], v[216:219], v[176:179], v[36:39]
	v_mfma_f32_16x16x32_bf16 v[32:35], v[216:219], v[184:187], v[32:35]
	s_setprio 0
	s_barrier
; #define LDA(dst, b, h) for (int m = 0; m < 4; ++m) for (int k = 0; k < 2; ++k) \
;     dst[m][k] = *reinterpret_cast<const bf16x8*>((char*)SA(b, h) + lds_byte(wr * 64 + m * 16 + fr, k * 32 + fq * 8))
; #define LDB(dst, b, h) for (int n = 0; n < 2; ++n) for (int k = 0; k < 2; ++k) \
;     dst[n][k] = *reinterpret_cast<const bf16x8*>((char*)SB(b, h) + lds_byte(wc * 32 + n * 16 + fr, k * 32 + fq * 8))
; #define MMA(ai, bj, At, Bq) do { __builtin_amdgcn_s_setprio(1); \
;     for (int m = 0; m < 4; ++m) for (int n = 0; n < 2; ++n) for (int k = 0; k < 2; ++k) \
;       acc[ai][bj][m][n] = __builtin_amdgcn_mfma_f32_16x16x32_bf16(At[m][k], Bq[n][k], acc[ai][bj][m][n], 0, 0, 0); \
;     __builtin_amdgcn_s_setprio(0); } while (0)
; #define WAIT_V(n) asm volatile("s_waitcnt vmcnt(" #n ")" ::: "memory")
; #define WAIT_L(n) asm volatile("s_waitcnt lgkmcnt(" #n ")" ::: "memory")
; #define BAR __builtin_amdgcn_s_barrier()
; #define SCHED __builtin_amdgcn_sched_barrier(0)
; template <class Epi>
; __device__ __forceinline__ void gemm_tile(const u16* __restrict__ A, const u16* __restrict__ Bt, int K,
;                                           int brow, int bcol, bool first, bool has_next, int nbrow, int nbcol, Epi epi) {
;     ...
;     STAGE(SB(0, 1), Bt, bcol + HALF, t + 2);
;     WAIT_V(6); BAR; MMA(1, 1, At, B1); BAR;
;     LDB(B0, 1, 0); SCHED; LDA(At, 1, 0); STAGE(SA(0, 1), A, brow + HALF, t + 2);
;     WAIT_L(8); BAR; WAIT_L(0); MMA(0, 0, At, B0); BAR; SCHED;
;     LDB(B1, 1, 1); STAGE(SB(1, 0), Bt, bcol, t + 3);
;     BAR; WAIT_L(0); MMA(0, 1, At, B1); BAR;
	v_lshl_add_u64 v[248:249], s[40:41], 0, v[140:141]
	v_readfirstlane_b32 s3, v151
	v_lshl_add_u64 v[166:167], v[248:249], 0, s[14:15]
	s_mov_b32 m0, s3
	v_lshl_add_u64 v[250:251], s[40:41], 0, v[142:143]
	global_load_lds_dwordx4 v[166:167], off
	v_add_u32_e32 v166, 0x2000, v151
	v_lshl_add_u64 v[168:169], v[250:251], 0, s[14:15]
	v_readfirstlane_b32 s3, v166
	s_mov_b32 m0, s3
	s_nop 0
	global_load_lds_dwordx4 v[168:169], off
	s_waitcnt vmcnt(6)
	s_barrier
	s_setprio 1
	v_mfma_f32_16x16x32_bf16 v[28:31], v[188:191], v[220:223], v[28:31]
	v_mfma_f32_16x16x32_bf16 v[24:27], v[188:191], v[228:231], v[24:27]
	v_mfma_f32_16x16x32_bf16 v[20:23], v[196:199], v[220:223], v[20:23]
	v_mfma_f32_16x16x32_bf16 v[16:19], v[196:199], v[228:231], v[16:19]
	v_mfma_f32_16x16x32_bf16 v[12:15], v[204:207], v[220:223], v[12:15]
	v_mfma_f32_16x16x32_bf16 v[8:11], v[204:207], v[228:231], v[8:11]
	v_mfma_f32_16x16x32_bf16 v[4:7], v[212:215], v[220:223], v[4:7]
	v_mfma_f32_16x16x32_bf16 v[0:3], v[212:215], v[228:231], v[0:3]
	v_mfma_f32_16x16x32_bf16 v[28:31], v[192:195], v[224:227], v[28:31]
	v_mfma_f32_16x16x32_bf16 v[24:27], v[192:195], v[232:235], v[24:27]
	v_mfma_f32_16x16x32_bf16 v[20:23], v[200:203], v[224:227], v[20:23]
	v_mfma_f32_16x16x32_bf16 v[16:19], v[200:203], v[232:235], v[16:19]
	v_mfma_f32_16x16x32_bf16 v[12:15], v[208:211], v[224:227], v[12:15]
	v_mfma_f32_16x16x32_bf16 v[8:11], v[208:211], v[232:235], v[8:11]
	v_mfma_f32_16x16x32_bf16 v[4:7], v[216:219], v[224:227], v[4:7]
	v_mfma_f32_16x16x32_bf16 v[0:3], v[216:219], v[232:235], v[0:3]
	s_setprio 0
	s_barrier
	ds_read_b128 v[176:179], v161
	ds_read_b128 v[180:183], v161 offset:1024
	ds_read_b128 v[184:187], v161 offset:2048
	ds_read_b128 v[188:191], v161 offset:3072
	v_readfirstlane_b32 s3, v150
	v_lshl_add_u64 v[168:169], v[170:171], 0, s[16:17]
	s_mov_b32 m0, s3
	v_readfirstlane_b32 s3, v149
	ds_read_b128 v[192:195], v159 offset:32768
	ds_read_b128 v[196:199], v159 offset:33792
	ds_read_b128 v[200:203], v158 offset:32768
	ds_read_b128 v[204:207], v158 offset:33792
	ds_read_b128 v[208:211], v157 offset:32768
	ds_read_b128 v[212:215], v157 offset:33792
	ds_read_b128 v[216:219], v156 offset:32768
	ds_read_b128 v[220:223], v156 offset:33792
	global_load_lds_dwordx4 v[168:169], off
	v_lshl_add_u64 v[168:169], v[236:237], 0, s[16:17]
	s_mov_b32 m0, s3
	s_nop 0
	global_load_lds_dwordx4 v[168:169], off
	s_waitcnt lgkmcnt(8)
	s_barrier
	s_waitcnt lgkmcnt(0)
	s_setprio 1
	v_mfma_f32_16x16x32_bf16 v[124:127], v[192:195], v[176:179], v[124:127]
	v_mfma_f32_16x16x32_bf16 v[120:123], v[192:195], v[184:187], v[120:123]
	v_mfma_f32_16x16x32_bf16 v[116:119], v[200:203], v[176:179], v[116:119]
	v_mfma_f32_16x16x32_bf16 v[112:115], v[200:203], v[184:187], v[112:115]
	v_mfma_f32_16x16x32_bf16 v[108:111], v[208:211], v[176:179], v[108:111]
	v_mfma_f32_16x16x32_bf16 v[104:107], v[208:211], v[184:187], v[104:107]
	v_mfma_f32_16x16x32_bf16 v[100:103], v[216:219], v[176:179], v[100:103]
	v_mfma_f32_16x16x32_bf16 v[96:99], v[216:219], v[184:187], v[96:99]
	v_mfma_f32_16x16x32_bf16 v[124:127], v[196:199], v[180:183], v[124:127]
	v_mfma_f32_16x16x32_bf16 v[120:123], v[196:199], v[188:191], v[120:123]
	v_mfma_f32_16x16x32_bf16 v[116:119], v[204:207], v[180:183], v[116:119]
	v_mfma_f32_16x16x32_bf16 v[112:115], v[204:207], v[188:191], v[112:115]
	v_mfma_f32_16x16x32_bf16 v[108:111], v[212:215], v[180:183], v[108:111]
	v_mfma_f32_16x16x32_bf16 v[104:107], v[212:215], v[188:191], v[104:107]
	v_mfma_f32_16x16x32_bf16 v[100:103], v[220:223], v[180:183], v[100:103]
	v_mfma_f32_16x16x32_bf16 v[96:99], v[220:223], v[188:191], v[96:99]
	s_setprio 0
	s_barrier
	v_add_u32_e32 v167, s84, v155
	v_lshl_add_u64 v[168:169], v[240:241], 0, s[18:19]
	v_readfirstlane_b32 s3, v167
	s_mov_b32 m0, s3
	ds_read_b128 v[224:227], v160
	ds_read_b128 v[228:231], v160 offset:1024
	ds_read_b128 v[232:235], v160 offset:2048
	ds_read_b128 v[236:239], v160 offset:3072
	global_load_lds_dwordx4 v[168:169], off
	v_add_u32_e32 v168, 0x2000, v167
	v_lshl_add_u64 v[170:171], v[242:243], 0, s[18:19]
	v_readfirstlane_b32 s3, v168
	s_mov_b32 m0, s3
	s_nop 0
	global_load_lds_dwordx4 v[170:171], off
	s_barrier
	s_waitcnt lgkmcnt(0)
	s_setprio 1
	v_mfma_f32_16x16x32_bf16 v[92:95], v[192:195], v[224:227], v[92:95]
	v_mfma_f32_16x16x32_bf16 v[88:91], v[192:195], v[232:235], v[88:91]
	v_mfma_f32_16x16x32_bf16 v[84:87], v[200:203], v[224:227], v[84:87]
	v_mfma_f32_16x16x32_bf16 v[80:83], v[200:203], v[232:235], v[80:83]
	v_mfma_f32_16x16x32_bf16 v[76:79], v[208:211], v[224:227], v[76:79]
	v_mfma_f32_16x16x32_bf16 v[72:75], v[208:211], v[232:235], v[72:75]
	v_mfma_f32_16x16x32_bf16 v[68:71], v[216:219], v[224:227], v[68:71]
	v_mfma_f32_16x16x32_bf16 v[64:67], v[216:219], v[232:235], v[64:67]
	v_mfma_f32_16x16x32_bf16 v[92:95], v[196:199], v[228:231], v[92:95]
	v_mfma_f32_16x16x32_bf16 v[88:91], v[196:199], v[236:239], v[88:91]
	v_mfma_f32_16x16x32_bf16 v[84:87], v[204:207], v[228:231], v[84:87]
	v_mfma_f32_16x16x32_bf16 v[80:83], v[204:207], v[236:239], v[80:83]
	v_mfma_f32_16x16x32_bf16 v[76:79], v[212:215], v[228:231], v[76:79]
	v_mfma_f32_16x16x32_bf16 v[72:75], v[212:215], v[236:239], v[72:75]
	v_mfma_f32_16x16x32_bf16 v[68:71], v[220:223], v[228:231], v[68:71]
	v_mfma_f32_16x16x32_bf16 v[64:67], v[220:223], v[236:239], v[64:67]
	s_setprio 0
	v_add_u32_e32 v169, 0x8000, v153
	v_lshl_add_u64 v[170:171], v[244:245], 0, s[20:21]
	v_readfirstlane_b32 s3, v169
	s_mov_b32 m0, s3
	s_barrier
; #define LDA(dst, b, h) for (int m = 0; m < 4; ++m) for (int k = 0; k < 2; ++k) \
;     dst[m][k] = *reinterpret_cast<const bf16x8*>((char*)SA(b, h) + lds_byte(wr * 64 + m * 16 + fr, k * 32 + fq * 8))
; #define LDB(dst, b, h) for (int n = 0; n < 2; ++n) for (int k = 0; k < 2; ++k) \
;     dst[n][k] = *reinterpret_cast<const bf16x8*>((char*)SB(b, h) + lds_byte(wc * 32 + n * 16 + fr, k * 32 + fq * 8))
; #define MMA(ai, bj, At, Bq) do { __builtin_amdgcn_s_setprio(1); \
;     for (int m = 0; m < 4; ++m) for (int n = 0; n < 2; ++n) for (int k = 0; k < 2; ++k) \
;       acc[ai][bj][m][n] = __builtin_amdgcn_mfma_f32_16x16x32_bf16(At[m][k], Bq[n][k], acc[ai][bj][m][n], 0, 0, 0); \
;     __builtin_amdgcn_s_setprio(0); } while (0)
; #define WAIT_V(n) asm volatile("s_waitcnt vmcnt(" #n ")" ::: "memory")
; #define WAIT_L(n) asm volatile("s_waitcnt lgkmcnt(" #n ")" ::: "memory")
; #define BAR __builtin_amdgcn_s_barrier()
; #define SCHED __builtin_amdgcn_sched_barrier(0)
; template <class Epi>
; __device__ __forceinline__ void gemm_tile(const u16* __restrict__ A, const u16* __restrict__ Bt, int K,
;                                           int brow, int bcol, bool first, bool has_next, int nbrow, int nbcol, Epi epi) {
;     ...
;     LDB(B0, 1, 0); SCHED; LDA(At, 1, 0); STAGE(SA(0, 1), A, brow + HALF, t + 2);
;     WAIT_L(8); BAR; WAIT_L(0); MMA(0, 0, At, B0); BAR; SCHED;
;     LDB(B1, 1, 1); STAGE(SB(1, 0), Bt, bcol, t + 3);
;     BAR; WAIT_L(0); MMA(0, 1, At, B1); BAR;
;     LDA(At, 1, 1); STAGE(SA(1, 0), A, brow, t + 3);
;     BAR; WAIT_L(0); MMA(1, 0, At, B0); BAR; SCHED;
;     STAGE(SB(1, 1), Bt, bcol + HALF, t + 3);
;     WAIT_V(6); BAR; MMA(1, 1, At, B1); BAR;
;   }
;   { LDB(B0, 0, 0); LDA(At, 0, 0); STAGE(SA(1, 1), A, brow + HALF, nt - 1);
;     BAR; WAIT_L(0); MMA(0, 0, At, B0); BAR;
	ds_read_b128 v[192:195], v159 offset:49152
	ds_read_b128 v[196:199], v159 offset:50176
	ds_read_b128 v[200:203], v158 offset:49152
	ds_read_b128 v[204:207], v158 offset:50176
	ds_read_b128 v[208:211], v157 offset:49152
	ds_read_b128 v[212:215], v157 offset:50176
	ds_read_b128 v[216:219], v156 offset:49152
	ds_read_b128 v[220:223], v156 offset:50176
	global_load_lds_dwordx4 v[170:171], off
	v_add_u32_e32 v170, 0xa000, v153
	v_lshl_add_u64 v[240:241], v[246:247], 0, s[20:21]
	v_readfirstlane_b32 s3, v170
	s_mov_b32 m0, s3
	s_nop 0
	global_load_lds_dwordx4 v[240:241], off
	s_barrier
	s_waitcnt lgkmcnt(0)
	s_setprio 1
	v_mfma_f32_16x16x32_bf16 v[60:63], v[192:195], v[176:179], v[60:63]
	v_mfma_f32_16x16x32_bf16 v[56:59], v[192:195], v[184:187], v[56:59]
	v_mfma_f32_16x16x32_bf16 v[52:55], v[200:203], v[176:179], v[52:55]
	v_mfma_f32_16x16x32_bf16 v[48:51], v[200:203], v[184:187], v[48:51]
	v_mfma_f32_16x16x32_bf16 v[44:47], v[208:211], v[176:179], v[44:47]
	v_mfma_f32_16x16x32_bf16 v[40:43], v[208:211], v[184:187], v[40:43]
	v_mfma_f32_16x16x32_bf16 v[36:39], v[216:219], v[176:179], v[36:39]
	v_mfma_f32_16x16x32_bf16 v[32:35], v[216:219], v[184:187], v[32:35]
	v_mfma_f32_16x16x32_bf16 v[60:63], v[196:199], v[180:183], v[60:63]
	v_mfma_f32_16x16x32_bf16 v[56:59], v[196:199], v[188:191], v[56:59]
	v_mfma_f32_16x16x32_bf16 v[52:55], v[204:207], v[180:183], v[52:55]
	v_mfma_f32_16x16x32_bf16 v[48:51], v[204:207], v[188:191], v[48:51]
	v_mfma_f32_16x16x32_bf16 v[44:47], v[212:215], v[180:183], v[44:47]
	v_mfma_f32_16x16x32_bf16 v[40:43], v[212:215], v[188:191], v[40:43]
	v_mfma_f32_16x16x32_bf16 v[36:39], v[220:223], v[180:183], v[36:39]
	v_mfma_f32_16x16x32_bf16 v[32:35], v[220:223], v[188:191], v[32:35]
	s_setprio 0
	s_barrier
	v_add_u32_e32 v171, s85, v155
	v_add_u32_e32 v172, 0x2000, v171
	v_readfirstlane_b32 s3, v171
	v_lshl_add_u64 v[176:177], v[248:249], 0, s[18:19]
	s_mov_b32 m0, s3
	v_readfirstlane_b32 s3, v172
	global_load_lds_dwordx4 v[176:177], off
	v_lshl_add_u64 v[176:177], v[250:251], 0, s[18:19]
	s_mov_b32 m0, s3
	s_nop 0
	global_load_lds_dwordx4 v[176:177], off
	s_waitcnt vmcnt(6)
	s_barrier
	s_setprio 1
	v_mfma_f32_16x16x32_bf16 v[28:31], v[192:195], v[224:227], v[28:31]
	v_mfma_f32_16x16x32_bf16 v[24:27], v[192:195], v[232:235], v[24:27]
	v_mfma_f32_16x16x32_bf16 v[20:23], v[200:203], v[224:227], v[20:23]
	v_mfma_f32_16x16x32_bf16 v[16:19], v[200:203], v[232:235], v[16:19]
	v_mfma_f32_16x16x32_bf16 v[12:15], v[208:211], v[224:227], v[12:15]
	v_mfma_f32_16x16x32_bf16 v[8:11], v[208:211], v[232:235], v[8:11]
	v_mfma_f32_16x16x32_bf16 v[4:7], v[216:219], v[224:227], v[4:7]
	v_mfma_f32_16x16x32_bf16 v[0:3], v[216:219], v[232:235], v[0:3]
	v_mfma_f32_16x16x32_bf16 v[28:31], v[196:199], v[228:231], v[28:31]
	v_mfma_f32_16x16x32_bf16 v[24:27], v[196:199], v[236:239], v[24:27]
	v_mfma_f32_16x16x32_bf16 v[20:23], v[204:207], v[228:231], v[20:23]
	v_mfma_f32_16x16x32_bf16 v[16:19], v[204:207], v[236:239], v[16:19]
	v_mfma_f32_16x16x32_bf16 v[12:15], v[212:215], v[228:231], v[12:15]
	v_mfma_f32_16x16x32_bf16 v[8:11], v[212:215], v[236:239], v[8:11]
	v_mfma_f32_16x16x32_bf16 v[4:7], v[220:223], v[228:231], v[4:7]
	v_mfma_f32_16x16x32_bf16 v[0:3], v[220:223], v[236:239], v[0:3]
	s_setprio 0
	s_add_i32 s1, s1, 2
	s_add_u32 s40, s40, 0x100
	s_addc_u32 s41, s41, 0
	s_cmp_lt_u32 s1, 12
	s_barrier
	s_cbranch_scc1 .LBB0_592
	s_add_u32 s36, s6, s36
	s_addc_u32 s37, s7, s37
	v_lshl_add_u64 v[208:209], s[36:37], 0, v[128:129]
	v_readfirstlane_b32 s1, v173
	v_lshl_add_u64 v[208:209], v[208:209], 0, s[22:23]
	s_mov_b32 m0, s1
	ds_read_b128 v[132:135], v164
	ds_read_b128 v[136:139], v164 offset:1024
	ds_read_b128 v[140:143], v164 offset:2048
	ds_read_b128 v[144:147], v164 offset:3072
	ds_read_b128 v[176:179], v159
	ds_read_b128 v[180:183], v159 offset:1024
	ds_read_b128 v[184:187], v158
	ds_read_b128 v[188:191], v158 offset:1024
	ds_read_b128 v[192:195], v157
	ds_read_b128 v[196:199], v157 offset:1024
	ds_read_b128 v[200:203], v156
	ds_read_b128 v[204:207], v156 offset:1024
	global_load_lds_dwordx4 v[208:209], off
	v_lshl_add_u64 v[208:209], s[36:37], 0, v[130:131]
	v_readfirstlane_b32 s1, v174
	v_lshl_add_u64 v[208:209], v[208:209], 0, s[22:23]
	s_mov_b32 m0, s1
	s_nop 0
	global_load_lds_dwordx4 v[208:209], off
	s_barrier
	s_waitcnt lgkmcnt(0)
	s_setprio 1
	s_waitcnt lgkmcnt(0)
	v_mfma_f32_16x16x32_bf16 v[124:127], v[176:179], v[132:135], v[124:127]
	v_mfma_f32_16x16x32_bf16 v[116:119], v[184:187], v[132:135], v[116:119]
	v_mfma_f32_16x16x32_bf16 v[108:111], v[192:195], v[132:135], v[108:111]
	v_mfma_f32_16x16x32_bf16 v[100:103], v[200:203], v[132:135], v[100:103]
	v_mfma_f32_16x16x32_bf16 v[124:127], v[180:183], v[136:139], v[124:127]
	v_mfma_f32_16x16x32_bf16 v[120:123], v[176:179], v[140:143], v[120:123]
	v_mfma_f32_16x16x32_bf16 v[116:119], v[188:191], v[136:139], v[116:119]
	v_mfma_f32_16x16x32_bf16 v[112:115], v[184:187], v[140:143], v[112:115]
	v_mfma_f32_16x16x32_bf16 v[108:111], v[196:199], v[136:139], v[108:111]
	v_mfma_f32_16x16x32_bf16 v[104:107], v[192:195], v[140:143], v[104:107]
	v_mfma_f32_16x16x32_bf16 v[100:103], v[204:207], v[136:139], v[100:103]
	v_mfma_f32_16x16x32_bf16 v[96:99], v[200:203], v[140:143], v[96:99]
	v_mfma_f32_16x16x32_bf16 v[208:211], v[180:183], v[144:147], v[120:123]
	v_mfma_f32_16x16x32_bf16 v[212:215], v[188:191], v[144:147], v[112:115]
	v_mfma_f32_16x16x32_bf16 v[216:219], v[196:199], v[144:147], v[104:107]
	v_mfma_f32_16x16x32_bf16 v[220:223], v[204:207], v[144:147], v[96:99]
	s_setprio 0
	s_barrier
	s_nop 1
	ds_read_b128 v[96:99], v163
	ds_read_b128 v[104:107], v163 offset:1024
	ds_read_b128 v[112:115], v163 offset:2048
	ds_read_b128 v[120:123], v163 offset:3072
	s_barrier
; #define LDA(dst, b, h) for (int m = 0; m < 4; ++m) for (int k = 0; k < 2; ++k) \
;     dst[m][k] = *reinterpret_cast<const bf16x8*>((char*)SA(b, h) + lds_byte(wr * 64 + m * 16 + fr, k * 32 + fq * 8))
; #define LDB(dst, b, h) for (int n = 0; n < 2; ++n) for (int k = 0; k < 2; ++k) \
;     dst[n][k] = *reinterpret_cast<const bf16x8*>((char*)SB(b, h) + lds_byte(wc * 32 + n * 16 + fr, k * 32 + fq * 8))
; #define MMA(ai, bj, At, Bq) do { __builtin_amdgcn_s_setprio(1); \
;     for (int m = 0; m < 4; ++m) for (int n = 0; n < 2; ++n) for (int k = 0; k < 2; ++k) \
;       acc[ai][bj][m][n] = __builtin_amdgcn_mfma_f32_16x16x32_bf16(At[m][k], Bq[n][k], acc[ai][bj][m][n], 0, 0, 0); \
;     __builtin_amdgcn_s_setprio(0); } while (0)
; #define WAIT_V(n) asm volatile("s_waitcnt vmcnt(" #n ")" ::: "memory")
; #define WAIT_L(n) asm volatile("s_waitcnt lgkmcnt(" #n ")" ::: "memory")
; #define BAR __builtin_amdgcn_s_barrier()
; template <class Epi>
; __device__ __forceinline__ void gemm_tile(const u16* __restrict__ A, const u16* __restrict__ Bt, int K,
;                                           int brow, int bcol, bool first, bool has_next, int nbrow, int nbcol, Epi epi) {
;     ...
;     BAR; WAIT_L(0); MMA(0, 0, At, B0); BAR;
;     LDB(B1, 0, 1); BAR; WAIT_L(0); MMA(0, 1, At, B1); BAR;
;     LDA(At, 0, 1); WAIT_V(4); BAR; WAIT_L(0); MMA(1, 0, At, B0); MMA(1, 1, At, B1); BAR; }
;   { LDB(B0, 1, 0); LDA(At, 1, 0); WAIT_V(2); BAR; WAIT_L(0); MMA(0, 0, At, B0); BAR;
	s_waitcnt lgkmcnt(0)
	s_setprio 1
	s_waitcnt lgkmcnt(0)
	v_mfma_f32_16x16x32_bf16 v[92:95], v[176:179], v[96:99], v[92:95]
	v_mfma_f32_16x16x32_bf16 v[84:87], v[184:187], v[96:99], v[84:87]
	v_mfma_f32_16x16x32_bf16 v[76:79], v[192:195], v[96:99], v[76:79]
	v_mfma_f32_16x16x32_bf16 v[68:71], v[200:203], v[96:99], v[68:71]
	v_mfma_f32_16x16x32_bf16 v[92:95], v[180:183], v[104:107], v[92:95]
	v_mfma_f32_16x16x32_bf16 v[88:91], v[176:179], v[112:115], v[88:91]
	v_mfma_f32_16x16x32_bf16 v[84:87], v[188:191], v[104:107], v[84:87]
	v_mfma_f32_16x16x32_bf16 v[80:83], v[184:187], v[112:115], v[80:83]
	v_mfma_f32_16x16x32_bf16 v[76:79], v[196:199], v[104:107], v[76:79]
	v_mfma_f32_16x16x32_bf16 v[72:75], v[192:195], v[112:115], v[72:75]
	v_mfma_f32_16x16x32_bf16 v[68:71], v[204:207], v[104:107], v[68:71]
	v_mfma_f32_16x16x32_bf16 v[64:67], v[200:203], v[112:115], v[64:67]
	v_mfma_f32_16x16x32_bf16 v[174:177], v[180:183], v[120:123], v[88:91]
	v_mfma_f32_16x16x32_bf16 v[178:181], v[188:191], v[120:123], v[80:83]
	v_mfma_f32_16x16x32_bf16 v[182:185], v[196:199], v[120:123], v[72:75]
	v_mfma_f32_16x16x32_bf16 v[186:189], v[204:207], v[120:123], v[64:67]
	s_setprio 0
	s_barrier
	s_nop 1
	ds_read_b128 v[64:67], v159 offset:16384
	ds_read_b128 v[72:75], v159 offset:17408
	ds_read_b128 v[80:83], v158 offset:16384
	ds_read_b128 v[88:91], v158 offset:17408
	ds_read_b128 v[190:193], v157 offset:16384
	ds_read_b128 v[194:197], v157 offset:17408
	ds_read_b128 v[198:201], v156 offset:16384
	ds_read_b128 v[202:205], v156 offset:17408
	s_waitcnt vmcnt(4)
	s_barrier
	s_waitcnt lgkmcnt(0)
	s_setprio 1
	s_waitcnt lgkmcnt(0)
	v_mfma_f32_16x16x32_bf16 v[60:63], v[64:67], v[132:135], v[60:63]
	v_mfma_f32_16x16x32_bf16 v[52:55], v[80:83], v[132:135], v[52:55]
	v_mfma_f32_16x16x32_bf16 v[44:47], v[190:193], v[132:135], v[44:47]
	v_mfma_f32_16x16x32_bf16 v[36:39], v[198:201], v[132:135], v[36:39]
	v_mfma_f32_16x16x32_bf16 v[60:63], v[72:75], v[136:139], v[60:63]
	v_mfma_f32_16x16x32_bf16 v[56:59], v[64:67], v[140:143], v[56:59]
	v_mfma_f32_16x16x32_bf16 v[52:55], v[88:91], v[136:139], v[52:55]
	v_mfma_f32_16x16x32_bf16 v[48:51], v[80:83], v[140:143], v[48:51]
	v_mfma_f32_16x16x32_bf16 v[44:47], v[194:197], v[136:139], v[44:47]
	v_mfma_f32_16x16x32_bf16 v[40:43], v[190:193], v[140:143], v[40:43]
	v_mfma_f32_16x16x32_bf16 v[36:39], v[202:205], v[136:139], v[36:39]
	v_mfma_f32_16x16x32_bf16 v[32:35], v[198:201], v[140:143], v[32:35]
	v_mfma_f32_16x16x32_bf16 v[224:227], v[72:75], v[144:147], v[56:59]
	v_mfma_f32_16x16x32_bf16 v[228:231], v[88:91], v[144:147], v[48:51]
	v_mfma_f32_16x16x32_bf16 v[232:235], v[194:197], v[144:147], v[40:43]
	v_mfma_f32_16x16x32_bf16 v[132:135], v[202:205], v[144:147], v[32:35]
	s_setprio 0
	s_setprio 1
	v_mfma_f32_16x16x32_bf16 v[28:31], v[64:67], v[96:99], v[28:31]
	v_mfma_f32_16x16x32_bf16 v[20:23], v[80:83], v[96:99], v[20:23]
	v_mfma_f32_16x16x32_bf16 v[12:15], v[190:193], v[96:99], v[12:15]
	v_mfma_f32_16x16x32_bf16 v[4:7], v[198:201], v[96:99], v[4:7]
	v_mfma_f32_16x16x32_bf16 v[28:31], v[72:75], v[104:107], v[28:31]
	v_mfma_f32_16x16x32_bf16 v[24:27], v[64:67], v[112:115], v[24:27]
	v_mfma_f32_16x16x32_bf16 v[20:23], v[88:91], v[104:107], v[20:23]
	v_mfma_f32_16x16x32_bf16 v[16:19], v[80:83], v[112:115], v[16:19]
	v_mfma_f32_16x16x32_bf16 v[12:15], v[194:197], v[104:107], v[12:15]
	v_mfma_f32_16x16x32_bf16 v[8:11], v[190:193], v[112:115], v[8:11]
	v_mfma_f32_16x16x32_bf16 v[4:7], v[202:205], v[104:107], v[4:7]
	v_mfma_f32_16x16x32_bf16 v[0:3], v[198:201], v[112:115], v[0:3]
	v_mfma_f32_16x16x32_bf16 v[136:139], v[72:75], v[120:123], v[24:27]
	v_mfma_f32_16x16x32_bf16 v[140:143], v[88:91], v[120:123], v[16:19]
	v_mfma_f32_16x16x32_bf16 v[144:147], v[194:197], v[120:123], v[8:11]
	v_mfma_f32_16x16x32_bf16 v[190:193], v[202:205], v[120:123], v[0:3]
	s_setprio 0
	s_barrier
	s_nop 1
	ds_read_b128 v[0:3], v161
	ds_read_b128 v[8:11], v161 offset:1024
	ds_read_b128 v[194:197], v161 offset:2048
	ds_read_b128 v[198:201], v161 offset:3072
	ds_read_b128 v[16:19], v159 offset:32768
	ds_read_b128 v[24:27], v159 offset:33792
	ds_read_b128 v[32:35], v158 offset:32768
	ds_read_b128 v[40:43], v158 offset:33792
	ds_read_b128 v[48:51], v157 offset:32768
	ds_read_b128 v[56:59], v157 offset:33792
	ds_read_b128 v[202:205], v156 offset:32768
	ds_read_b128 v[236:239], v156 offset:33792
	s_waitcnt vmcnt(2)
	s_barrier
; #define LDA(dst, b, h) for (int m = 0; m < 4; ++m) for (int k = 0; k < 2; ++k) \
;     dst[m][k] = *reinterpret_cast<const bf16x8*>((char*)SA(b, h) + lds_byte(wr * 64 + m * 16 + fr, k * 32 + fq * 8))
; #define LDB(dst, b, h) for (int n = 0; n < 2; ++n) for (int k = 0; k < 2; ++k) \
;     dst[n][k] = *reinterpret_cast<const bf16x8*>((char*)SB(b, h) + lds_byte(wc * 32 + n * 16 + fr, k * 32 + fq * 8))
; #define MMA(ai, bj, At, Bq) do { __builtin_amdgcn_s_setprio(1); \
;     for (int m = 0; m < 4; ++m) for (int n = 0; n < 2; ++n) for (int k = 0; k < 2; ++k) \
;       acc[ai][bj][m][n] = __builtin_amdgcn_mfma_f32_16x16x32_bf16(At[m][k], Bq[n][k], acc[ai][bj][m][n], 0, 0, 0); \
;     __builtin_amdgcn_s_setprio(0); } while (0)
; #define WAIT_V(n) asm volatile("s_waitcnt vmcnt(" #n ")" ::: "memory")
; #define WAIT_L(n) asm volatile("s_waitcnt lgkmcnt(" #n ")" ::: "memory")
; #define BAR __builtin_amdgcn_s_barrier()
; template <class Epi>
; __device__ __forceinline__ void gemm_tile(const u16* __restrict__ A, const u16* __restrict__ Bt, int K,
;                                           int brow, int bcol, bool first, bool has_next, int nbrow, int nbcol, Epi epi) {
;     ...
;   { LDB(B0, 1, 0); LDA(At, 1, 0); WAIT_V(2); BAR; WAIT_L(0); MMA(0, 0, At, B0); BAR;
;     LDB(B1, 1, 1); WAIT_V(0); BAR; WAIT_L(0); MMA(0, 1, At, B1); BAR;
;     LDA(At, 1, 1); BAR; WAIT_L(0); MMA(1, 0, At, B0); MMA(1, 1, At, B1); BAR; }
;   if (wr == 0) BAR;
	s_waitcnt lgkmcnt(0)
	s_setprio 1
	s_waitcnt lgkmcnt(0)
	v_mfma_f32_16x16x32_bf16 v[64:67], v[16:19], v[0:3], v[124:127]
	v_mfma_f32_16x16x32_bf16 v[120:123], v[24:27], v[8:11], v[64:67]
	v_mfma_f32_16x16x32_bf16 v[64:67], v[16:19], v[194:197], v[208:211]
	v_mfma_f32_16x16x32_bf16 v[112:115], v[24:27], v[198:201], v[64:67]
	v_mfma_f32_16x16x32_bf16 v[64:67], v[32:35], v[0:3], v[116:119]
	v_mfma_f32_16x16x32_bf16 v[104:107], v[40:43], v[8:11], v[64:67]
	v_mfma_f32_16x16x32_bf16 v[64:67], v[32:35], v[194:197], v[212:215]
	v_mfma_f32_16x16x32_bf16 v[96:99], v[40:43], v[198:201], v[64:67]
	v_mfma_f32_16x16x32_bf16 v[64:67], v[48:51], v[0:3], v[108:111]
	v_mfma_f32_16x16x32_bf16 v[88:91], v[56:59], v[8:11], v[64:67]
	v_mfma_f32_16x16x32_bf16 v[64:67], v[48:51], v[194:197], v[216:219]
	v_mfma_f32_16x16x32_bf16 v[80:83], v[56:59], v[198:201], v[64:67]
	v_mfma_f32_16x16x32_bf16 v[64:67], v[202:205], v[0:3], v[100:103]
	v_mfma_f32_16x16x32_bf16 v[72:75], v[236:239], v[8:11], v[64:67]
	v_mfma_f32_16x16x32_bf16 v[64:67], v[202:205], v[194:197], v[220:223]
	v_mfma_f32_16x16x32_bf16 v[64:67], v[236:239], v[198:201], v[64:67]
	s_setprio 0
	s_barrier
	ds_read_b128 v[206:209], v160
	ds_read_b128 v[210:213], v160 offset:1024
	ds_read_b128 v[214:217], v160 offset:2048
	ds_read_b128 v[218:221], v160 offset:3072
	s_waitcnt vmcnt(0)
	s_barrier
	s_waitcnt lgkmcnt(0)
	s_setprio 1
	s_waitcnt lgkmcnt(0)
	v_mfma_f32_16x16x32_bf16 v[92:95], v[16:19], v[206:209], v[92:95]
	v_mfma_f32_16x16x32_bf16 v[16:19], v[16:19], v[214:217], v[174:177]
	v_mfma_f32_16x16x32_bf16 v[116:119], v[24:27], v[218:221], v[16:19]
	v_mfma_f32_16x16x32_bf16 v[16:19], v[32:35], v[206:209], v[84:87]
	v_mfma_f32_16x16x32_bf16 v[108:111], v[40:43], v[210:213], v[16:19]
	v_mfma_f32_16x16x32_bf16 v[16:19], v[32:35], v[214:217], v[178:181]
	v_mfma_f32_16x16x32_bf16 v[100:103], v[40:43], v[218:221], v[16:19]
	v_mfma_f32_16x16x32_bf16 v[16:19], v[48:51], v[206:209], v[76:79]
	v_mfma_f32_16x16x32_bf16 v[124:127], v[24:27], v[210:213], v[92:95]
	v_mfma_f32_16x16x32_bf16 v[92:95], v[56:59], v[210:213], v[16:19]
	v_mfma_f32_16x16x32_bf16 v[16:19], v[48:51], v[214:217], v[182:185]
	v_mfma_f32_16x16x32_bf16 v[84:87], v[56:59], v[218:221], v[16:19]
	v_mfma_f32_16x16x32_bf16 v[16:19], v[202:205], v[206:209], v[68:71]
	v_mfma_f32_16x16x32_bf16 v[76:79], v[236:239], v[210:213], v[16:19]
	v_mfma_f32_16x16x32_bf16 v[16:19], v[202:205], v[214:217], v[186:189]
	v_mfma_f32_16x16x32_bf16 v[68:71], v[236:239], v[218:221], v[16:19]
	s_setprio 0
	s_barrier
	ds_read_b128 v[174:177], v159 offset:49152
	ds_read_b128 v[178:181], v159 offset:50176
	ds_read_b128 v[182:185], v158 offset:49152
	ds_read_b128 v[158:161], v158 offset:50176
	ds_read_b128 v[186:189], v157 offset:49152
	ds_read_b128 v[202:205], v157 offset:50176
	ds_read_b128 v[236:239], v156 offset:49152
	ds_read_b128 v[240:243], v156 offset:50176
	s_barrier
	s_waitcnt lgkmcnt(0)
	s_setprio 1
	s_waitcnt lgkmcnt(0)
	v_mfma_f32_16x16x32_bf16 v[16:19], v[174:177], v[0:3], v[60:63]
	v_mfma_f32_16x16x32_bf16 v[56:59], v[178:181], v[8:11], v[16:19]
	v_mfma_f32_16x16x32_bf16 v[16:19], v[174:177], v[194:197], v[224:227]
	v_mfma_f32_16x16x32_bf16 v[48:51], v[178:181], v[198:201], v[16:19]
	v_mfma_f32_16x16x32_bf16 v[16:19], v[182:185], v[0:3], v[52:55]
	v_mfma_f32_16x16x32_bf16 v[40:43], v[158:161], v[8:11], v[16:19]
	v_mfma_f32_16x16x32_bf16 v[16:19], v[182:185], v[194:197], v[228:231]
	v_mfma_f32_16x16x32_bf16 v[32:35], v[158:161], v[198:201], v[16:19]
	v_mfma_f32_16x16x32_bf16 v[16:19], v[186:189], v[0:3], v[44:47]
	v_mfma_f32_16x16x32_bf16 v[0:3], v[236:239], v[0:3], v[36:39]
	v_mfma_f32_16x16x32_bf16 v[24:27], v[202:205], v[8:11], v[16:19]
	v_mfma_f32_16x16x32_bf16 v[16:19], v[186:189], v[194:197], v[232:235]
	v_mfma_f32_16x16x32_bf16 v[8:11], v[240:243], v[8:11], v[0:3]
	v_mfma_f32_16x16x32_bf16 v[0:3], v[236:239], v[194:197], v[132:135]
	v_mfma_f32_16x16x32_bf16 v[16:19], v[202:205], v[198:201], v[16:19]
	v_mfma_f32_16x16x32_bf16 v[0:3], v[240:243], v[198:201], v[0:3]
	s_setprio 0
	s_setprio 1
	v_mfma_f32_16x16x32_bf16 v[28:31], v[174:177], v[206:209], v[28:31]
	v_mfma_f32_16x16x32_bf16 v[60:63], v[178:181], v[210:213], v[28:31]
	v_mfma_f32_16x16x32_bf16 v[28:31], v[174:177], v[214:217], v[136:139]
	v_mfma_f32_16x16x32_bf16 v[20:23], v[182:185], v[206:209], v[20:23]
	v_mfma_f32_16x16x32_bf16 v[12:15], v[186:189], v[206:209], v[12:15]
	v_mfma_f32_16x16x32_bf16 v[52:55], v[178:181], v[218:221], v[28:31]
	v_mfma_f32_16x16x32_bf16 v[44:47], v[158:161], v[210:213], v[20:23]
	v_mfma_f32_16x16x32_bf16 v[20:23], v[182:185], v[214:217], v[140:143]
	v_mfma_f32_16x16x32_bf16 v[28:31], v[202:205], v[210:213], v[12:15]
	v_mfma_f32_16x16x32_bf16 v[12:15], v[186:189], v[214:217], v[144:147]
	v_mfma_f32_16x16x32_bf16 v[4:7], v[236:239], v[206:209], v[4:7]
	v_mfma_f32_16x16x32_bf16 v[36:39], v[158:161], v[218:221], v[20:23]
	v_mfma_f32_16x16x32_bf16 v[20:23], v[202:205], v[218:221], v[12:15]
	v_mfma_f32_16x16x32_bf16 v[12:15], v[240:243], v[210:213], v[4:7]
	v_mfma_f32_16x16x32_bf16 v[4:7], v[236:239], v[214:217], v[190:193]
	v_mfma_f32_16x16x32_bf16 v[4:7], v[240:243], v[218:221], v[4:7]
	s_setprio 0
	v_cmp_gt_u32_e32 vcc, s61, v148
	s_barrier
	s_and_saveexec_b64 s[36:37], vcc
	s_cbranch_execz .LBB0_595
	s_barrier

; #define LDA(dst, b, h) for (int m = 0; m < 4; ++m) for (int k = 0; k < 2; ++k) \
;     dst[m][k] = *reinterpret_cast<const bf16x8*>((char*)SA(b, h) + lds_byte(wr * 64 + m * 16 + fr, k * 32 + fq * 8))
; #define LDB(dst, b, h) for (int n = 0; n < 2; ++n) for (int k = 0; k < 2; ++k) \
;     dst[n][k] = *reinterpret_cast<const bf16x8*>((char*)SB(b, h) + lds_byte(wc * 32 + n * 16 + fr, k * 32 + fq * 8))
; #define MMA(ai, bj, At, Bq) do { __builtin_amdgcn_s_setprio(1); \
;     for (int m = 0; m < 4; ++m) for (int n = 0; n < 2; ++n) for (int k = 0; k < 2; ++k) \
;       acc[ai][bj][m][n] = __builtin_amdgcn_mfma_f32_16x16x32_bf16(At[m][k], Bq[n][k], acc[ai][bj][m][n], 0, 0, 0); \
;     __builtin_amdgcn_s_setprio(0); } while (0)
; #define WAIT_L(n) asm volatile("s_waitcnt lgkmcnt(" #n ")" ::: "memory")
; #define BAR __builtin_amdgcn_s_barrier()
; #define SCHED __builtin_amdgcn_sched_barrier(0)
; template <class Epi>
; __device__ __forceinline__ void gemm_tile(const u16* __restrict__ A, const u16* __restrict__ Bt, int K,
;                                           int brow, int bcol, bool first, bool has_next, int nbrow, int nbcol, Epi epi) {
;     ...
;     LDB(B0, 0, 0); SCHED; LDA(At, 0, 0); STAGE(SA(1, 1), A, brow + HALF, t + 1);
;     WAIT_L(8); BAR; WAIT_L(0); MMA(0, 0, At, B0); BAR; SCHED;
;     LDB(B1, 0, 1); STAGE(SB(0, 0), Bt, bcol, t + 2);
;     BAR; WAIT_L(0); MMA(0, 1, At, B1); BAR;
;     LDA(At, 0, 1); STAGE(SA(0, 0), A, brow, t + 2);
;     BAR; WAIT_L(0); MMA(1, 0, At, B0); BAR; SCHED;
.LBB0_663:
	ds_read_b128 v[172:175], v169
	ds_read_b128 v[180:183], v169 offset:1024
	ds_read_b128 v[184:187], v169 offset:2048
	ds_read_b128 v[188:191], v169 offset:3072
	v_add_u32_e32 v178, 0xc000, v159
	v_lshl_add_u64 v[240:241], s[18:19], 0, v[148:149]
	v_readfirstlane_b32 s21, v178
	v_add_u32_e32 v179, 0xe000, v159
	v_lshl_add_u64 v[170:171], v[240:241], 0, s[8:9]
	s_mov_b32 m0, s21
	v_lshl_add_u64 v[242:243], s[18:19], 0, v[150:151]
	v_readfirstlane_b32 s21, v179
	ds_read_b128 v[192:195], v165
	ds_read_b128 v[196:199], v165 offset:1024
	ds_read_b128 v[200:203], v164
	ds_read_b128 v[204:207], v164 offset:1024
	ds_read_b128 v[208:211], v163
	ds_read_b128 v[212:215], v163 offset:1024
	ds_read_b128 v[216:219], v162
	ds_read_b128 v[220:223], v162 offset:1024
	global_load_lds_dwordx4 v[170:171], off
	v_lshl_add_u64 v[170:171], v[242:243], 0, s[8:9]
	s_mov_b32 m0, s21
	s_nop 0
	global_load_lds_dwordx4 v[170:171], off
	s_waitcnt lgkmcnt(8)
	s_barrier
	s_waitcnt lgkmcnt(0)
	s_setprio 1
	v_mfma_f32_16x16x32_bf16 v[124:127], v[192:195], v[172:175], v[124:127]
	v_mfma_f32_16x16x32_bf16 v[120:123], v[192:195], v[184:187], v[120:123]
	v_mfma_f32_16x16x32_bf16 v[116:119], v[200:203], v[172:175], v[116:119]
	v_mfma_f32_16x16x32_bf16 v[112:115], v[200:203], v[184:187], v[112:115]
	v_mfma_f32_16x16x32_bf16 v[108:111], v[208:211], v[172:175], v[108:111]
	v_mfma_f32_16x16x32_bf16 v[104:107], v[208:211], v[184:187], v[104:107]
	v_mfma_f32_16x16x32_bf16 v[100:103], v[216:219], v[172:175], v[100:103]
	v_mfma_f32_16x16x32_bf16 v[96:99], v[216:219], v[184:187], v[96:99]
	v_mfma_f32_16x16x32_bf16 v[124:127], v[196:199], v[180:183], v[124:127]
	v_mfma_f32_16x16x32_bf16 v[120:123], v[196:199], v[188:191], v[120:123]
	v_mfma_f32_16x16x32_bf16 v[116:119], v[204:207], v[180:183], v[116:119]
	v_mfma_f32_16x16x32_bf16 v[112:115], v[204:207], v[188:191], v[112:115]
	v_mfma_f32_16x16x32_bf16 v[108:111], v[212:215], v[180:183], v[108:111]
	v_mfma_f32_16x16x32_bf16 v[104:107], v[212:215], v[188:191], v[104:107]
	v_mfma_f32_16x16x32_bf16 v[100:103], v[220:223], v[180:183], v[100:103]
	v_mfma_f32_16x16x32_bf16 v[96:99], v[220:223], v[188:191], v[96:99]
	s_setprio 0
	s_barrier
	v_lshl_add_u64 v[244:245], s[18:19], 0, v[136:137]
	v_readfirstlane_b32 s21, v160
	v_lshl_add_u64 v[170:171], v[244:245], 0, s[10:11]
	s_mov_b32 m0, s21
	ds_read_b128 v[224:227], v168
	ds_read_b128 v[228:231], v168 offset:1024
	ds_read_b128 v[232:235], v168 offset:2048
	ds_read_b128 v[236:239], v168 offset:3072
	global_load_lds_dwordx4 v[170:171], off
	v_add_u32_e32 v170, 0x2000, v160
	v_lshl_add_u64 v[246:247], s[18:19], 0, v[138:139]
	v_readfirstlane_b32 s21, v170
	v_lshl_add_u64 v[176:177], v[246:247], 0, s[10:11]
	s_mov_b32 m0, s21
	s_nop 0
	global_load_lds_dwordx4 v[176:177], off
	s_barrier
	s_waitcnt lgkmcnt(0)
	s_setprio 1
	v_mfma_f32_16x16x32_bf16 v[92:95], v[192:195], v[224:227], v[92:95]
	v_mfma_f32_16x16x32_bf16 v[88:91], v[192:195], v[232:235], v[88:91]
	v_mfma_f32_16x16x32_bf16 v[84:87], v[200:203], v[224:227], v[84:87]
	v_mfma_f32_16x16x32_bf16 v[80:83], v[200:203], v[232:235], v[80:83]
	v_mfma_f32_16x16x32_bf16 v[76:79], v[208:211], v[224:227], v[76:79]
	v_mfma_f32_16x16x32_bf16 v[72:75], v[208:211], v[232:235], v[72:75]
	v_mfma_f32_16x16x32_bf16 v[68:71], v[216:219], v[224:227], v[68:71]
	v_mfma_f32_16x16x32_bf16 v[64:67], v[216:219], v[232:235], v[64:67]
	v_mfma_f32_16x16x32_bf16 v[92:95], v[196:199], v[228:231], v[92:95]
	v_mfma_f32_16x16x32_bf16 v[88:91], v[196:199], v[236:239], v[88:91]
	v_mfma_f32_16x16x32_bf16 v[84:87], v[204:207], v[228:231], v[84:87]
	v_mfma_f32_16x16x32_bf16 v[80:83], v[204:207], v[236:239], v[80:83]
	v_mfma_f32_16x16x32_bf16 v[76:79], v[212:215], v[228:231], v[76:79]
	v_mfma_f32_16x16x32_bf16 v[72:75], v[212:215], v[236:239], v[72:75]
	v_mfma_f32_16x16x32_bf16 v[68:71], v[220:223], v[228:231], v[68:71]
	v_mfma_f32_16x16x32_bf16 v[64:67], v[220:223], v[236:239], v[64:67]
	s_setprio 0
	v_lshl_add_u64 v[248:249], s[18:19], 0, v[140:141]
	v_readfirstlane_b32 s21, v159
	v_lshl_add_u64 v[176:177], v[248:249], 0, s[12:13]
	s_mov_b32 m0, s21
	v_lshl_add_u64 v[250:251], s[18:19], 0, v[142:143]
	v_readfirstlane_b32 s21, v158
	s_barrier
	ds_read_b128 v[192:195], v165 offset:16384
	ds_read_b128 v[196:199], v165 offset:17408
	ds_read_b128 v[200:203], v164 offset:16384
	ds_read_b128 v[204:207], v164 offset:17408
	ds_read_b128 v[208:211], v163 offset:16384
	ds_read_b128 v[212:215], v163 offset:17408
	ds_read_b128 v[216:219], v162 offset:16384
	ds_read_b128 v[220:223], v162 offset:17408
	global_load_lds_dwordx4 v[176:177], off
	v_lshl_add_u64 v[176:177], v[250:251], 0, s[12:13]
	s_mov_b32 m0, s21
	s_nop 0
	global_load_lds_dwordx4 v[176:177], off
	s_barrier
	s_waitcnt lgkmcnt(0)
	s_setprio 1
	v_mfma_f32_16x16x32_bf16 v[60:63], v[192:195], v[172:175], v[60:63]
	v_mfma_f32_16x16x32_bf16 v[56:59], v[192:195], v[184:187], v[56:59]
	v_mfma_f32_16x16x32_bf16 v[52:55], v[200:203], v[172:175], v[52:55]
	v_mfma_f32_16x16x32_bf16 v[48:51], v[200:203], v[184:187], v[48:51]
	v_mfma_f32_16x16x32_bf16 v[44:47], v[208:211], v[172:175], v[44:47]
	v_mfma_f32_16x16x32_bf16 v[40:43], v[208:211], v[184:187], v[40:43]
	v_mfma_f32_16x16x32_bf16 v[36:39], v[216:219], v[172:175], v[36:39]
	v_mfma_f32_16x16x32_bf16 v[32:35], v[216:219], v[184:187], v[32:35]
	v_mfma_f32_16x16x32_bf16 v[60:63], v[196:199], v[180:183], v[60:63]
	v_mfma_f32_16x16x32_bf16 v[56:59], v[196:199], v[188:191], v[56:59]
	v_mfma_f32_16x16x32_bf16 v[52:55], v[204:207], v[180:183], v[52:55]
	v_mfma_f32_16x16x32_bf16 v[48:51], v[204:207], v[188:191], v[48:51]
	v_mfma_f32_16x16x32_bf16 v[44:47], v[212:215], v[180:183], v[44:47]
	v_mfma_f32_16x16x32_bf16 v[40:43], v[212:215], v[188:191], v[40:43]
	v_mfma_f32_16x16x32_bf16 v[36:39], v[220:223], v[180:183], v[36:39]
	v_mfma_f32_16x16x32_bf16 v[32:35], v[220:223], v[188:191], v[32:35]
	s_setprio 0
	s_barrier
; #define LDA(dst, b, h) for (int m = 0; m < 4; ++m) for (int k = 0; k < 2; ++k) \
;     dst[m][k] = *reinterpret_cast<const bf16x8*>((char*)SA(b, h) + lds_byte(wr * 64 + m * 16 + fr, k * 32 + fq * 8))
; #define LDB(dst, b, h) for (int n = 0; n < 2; ++n) for (int k = 0; k < 2; ++k) \
;     dst[n][k] = *reinterpret_cast<const bf16x8*>((char*)SB(b, h) + lds_byte(wc * 32 + n * 16 + fr, k * 32 + fq * 8))
; #define MMA(ai, bj, At, Bq) do { __builtin_amdgcn_s_setprio(1); \
;     for (int m = 0; m < 4; ++m) for (int n = 0; n < 2; ++n) for (int k = 0; k < 2; ++k) \
;       acc[ai][bj][m][n] = __builtin_amdgcn_mfma_f32_16x16x32_bf16(At[m][k], Bq[n][k], acc[ai][bj][m][n], 0, 0, 0); \
;     __builtin_amdgcn_s_setprio(0); } while (0)
; #define WAIT_V(n) asm volatile("s_waitcnt vmcnt(" #n ")" ::: "memory")
; #define WAIT_L(n) asm volatile("s_waitcnt lgkmcnt(" #n ")" ::: "memory")
; #define BAR __builtin_amdgcn_s_barrier()
; #define SCHED __builtin_amdgcn_sched_barrier(0)
; template <class Epi>
; __device__ __forceinline__ void gemm_tile(const u16* __restrict__ A, const u16* __restrict__ Bt, int K,
;                                           int brow, int bcol, bool first, bool has_next, int nbrow, int nbcol, Epi epi) {
;     ...
;     STAGE(SB(0, 1), Bt, bcol + HALF, t + 2);
;     WAIT_V(6); BAR; MMA(1, 1, At, B1); BAR;
;     LDB(B0, 1, 0); SCHED; LDA(At, 1, 0); STAGE(SA(0, 1), A, brow + HALF, t + 2);
;     WAIT_L(8); BAR; WAIT_L(0); MMA(0, 0, At, B0); BAR; SCHED;
;     LDB(B1, 1, 1); STAGE(SB(1, 0), Bt, bcol, t + 3);
;     BAR; WAIT_L(0); MMA(0, 1, At, B1); BAR;
	v_lshl_add_u64 v[252:253], s[18:19], 0, v[144:145]
	v_readfirstlane_b32 s21, v157
	v_add_u32_e32 v171, 0x2000, v157
	v_lshl_add_u64 v[172:173], v[252:253], 0, s[10:11]
	s_mov_b32 m0, s21
	v_lshl_add_u64 v[152:153], s[18:19], 0, v[146:147]
	v_readfirstlane_b32 s21, v171
	global_load_lds_dwordx4 v[172:173], off
	v_lshl_add_u64 v[172:173], v[152:153], 0, s[10:11]
	s_mov_b32 m0, s21
	s_nop 0
	global_load_lds_dwordx4 v[172:173], off
	s_waitcnt vmcnt(6)
	s_barrier
	s_setprio 1
	v_mfma_f32_16x16x32_bf16 v[28:31], v[192:195], v[224:227], v[28:31]
	v_mfma_f32_16x16x32_bf16 v[24:27], v[192:195], v[232:235], v[24:27]
	v_mfma_f32_16x16x32_bf16 v[20:23], v[200:203], v[224:227], v[20:23]
	v_mfma_f32_16x16x32_bf16 v[16:19], v[200:203], v[232:235], v[16:19]
	v_mfma_f32_16x16x32_bf16 v[12:15], v[208:211], v[224:227], v[12:15]
	v_mfma_f32_16x16x32_bf16 v[8:11], v[208:211], v[232:235], v[8:11]
	v_mfma_f32_16x16x32_bf16 v[4:7], v[216:219], v[224:227], v[4:7]
	v_mfma_f32_16x16x32_bf16 v[0:3], v[216:219], v[232:235], v[0:3]
	v_mfma_f32_16x16x32_bf16 v[28:31], v[196:199], v[228:231], v[28:31]
	v_mfma_f32_16x16x32_bf16 v[24:27], v[196:199], v[236:239], v[24:27]
	v_mfma_f32_16x16x32_bf16 v[20:23], v[204:207], v[228:231], v[20:23]
	v_mfma_f32_16x16x32_bf16 v[16:19], v[204:207], v[236:239], v[16:19]
	v_mfma_f32_16x16x32_bf16 v[12:15], v[212:215], v[228:231], v[12:15]
	v_mfma_f32_16x16x32_bf16 v[8:11], v[212:215], v[236:239], v[8:11]
	v_mfma_f32_16x16x32_bf16 v[4:7], v[220:223], v[228:231], v[4:7]
	v_mfma_f32_16x16x32_bf16 v[0:3], v[220:223], v[236:239], v[0:3]
	s_setprio 0
	s_barrier
	ds_read_b128 v[180:183], v167
	ds_read_b128 v[184:187], v167 offset:1024
	ds_read_b128 v[188:191], v167 offset:2048
	ds_read_b128 v[192:195], v167 offset:3072
	v_readfirstlane_b32 s21, v156
	v_lshl_add_u64 v[172:173], v[240:241], 0, s[12:13]
	s_mov_b32 m0, s21
	v_readfirstlane_b32 s21, v130
	ds_read_b128 v[174:177], v165 offset:32768
	ds_read_b128 v[196:199], v165 offset:33792
	ds_read_b128 v[200:203], v164 offset:32768
	ds_read_b128 v[204:207], v164 offset:33792
	ds_read_b128 v[208:211], v163 offset:32768
	ds_read_b128 v[212:215], v163 offset:33792
	ds_read_b128 v[216:219], v162 offset:32768
	ds_read_b128 v[220:223], v162 offset:33792
	global_load_lds_dwordx4 v[172:173], off
	v_lshl_add_u64 v[172:173], v[242:243], 0, s[12:13]
	s_mov_b32 m0, s21
	s_nop 0
	global_load_lds_dwordx4 v[172:173], off
	s_waitcnt lgkmcnt(8)
	s_barrier
	s_waitcnt lgkmcnt(0)
	s_setprio 1
	v_mfma_f32_16x16x32_bf16 v[124:127], v[174:177], v[180:183], v[124:127]
	v_mfma_f32_16x16x32_bf16 v[120:123], v[174:177], v[188:191], v[120:123]
	v_mfma_f32_16x16x32_bf16 v[116:119], v[200:203], v[180:183], v[116:119]
	v_mfma_f32_16x16x32_bf16 v[112:115], v[200:203], v[188:191], v[112:115]
	v_mfma_f32_16x16x32_bf16 v[108:111], v[208:211], v[180:183], v[108:111]
	v_mfma_f32_16x16x32_bf16 v[104:107], v[208:211], v[188:191], v[104:107]
	v_mfma_f32_16x16x32_bf16 v[100:103], v[216:219], v[180:183], v[100:103]
	v_mfma_f32_16x16x32_bf16 v[96:99], v[216:219], v[188:191], v[96:99]
	v_mfma_f32_16x16x32_bf16 v[124:127], v[196:199], v[184:187], v[124:127]
	v_mfma_f32_16x16x32_bf16 v[120:123], v[196:199], v[192:195], v[120:123]
	v_mfma_f32_16x16x32_bf16 v[116:119], v[204:207], v[184:187], v[116:119]
	v_mfma_f32_16x16x32_bf16 v[112:115], v[204:207], v[192:195], v[112:115]
	v_mfma_f32_16x16x32_bf16 v[108:111], v[212:215], v[184:187], v[108:111]
	v_mfma_f32_16x16x32_bf16 v[104:107], v[212:215], v[192:195], v[104:107]
	v_mfma_f32_16x16x32_bf16 v[100:103], v[220:223], v[184:187], v[100:103]
	v_mfma_f32_16x16x32_bf16 v[96:99], v[220:223], v[192:195], v[96:99]
	s_setprio 0
	s_barrier
	v_add_u32_e32 v172, s84, v161
	v_add_u32_e32 v173, 0x2000, v172
	v_readfirstlane_b32 s21, v172
	v_lshl_add_u64 v[240:241], v[244:245], 0, s[14:15]
	s_mov_b32 m0, s21
	v_readfirstlane_b32 s21, v173
	ds_read_b128 v[224:227], v166
	ds_read_b128 v[228:231], v166 offset:1024
	ds_read_b128 v[232:235], v166 offset:2048
	ds_read_b128 v[236:239], v166 offset:3072
	global_load_lds_dwordx4 v[240:241], off
	v_lshl_add_u64 v[240:241], v[246:247], 0, s[14:15]
	s_mov_b32 m0, s21
	s_nop 0
	global_load_lds_dwordx4 v[240:241], off
	s_barrier
	s_waitcnt lgkmcnt(0)
	s_setprio 1
	v_mfma_f32_16x16x32_bf16 v[92:95], v[174:177], v[224:227], v[92:95]
	v_mfma_f32_16x16x32_bf16 v[88:91], v[174:177], v[232:235], v[88:91]
	v_mfma_f32_16x16x32_bf16 v[84:87], v[200:203], v[224:227], v[84:87]
	v_mfma_f32_16x16x32_bf16 v[80:83], v[200:203], v[232:235], v[80:83]
	v_mfma_f32_16x16x32_bf16 v[76:79], v[208:211], v[224:227], v[76:79]
	v_mfma_f32_16x16x32_bf16 v[72:75], v[208:211], v[232:235], v[72:75]
	v_mfma_f32_16x16x32_bf16 v[68:71], v[216:219], v[224:227], v[68:71]
	v_mfma_f32_16x16x32_bf16 v[64:67], v[216:219], v[232:235], v[64:67]
	v_mfma_f32_16x16x32_bf16 v[92:95], v[196:199], v[228:231], v[92:95]
	v_mfma_f32_16x16x32_bf16 v[88:91], v[196:199], v[236:239], v[88:91]
	v_mfma_f32_16x16x32_bf16 v[84:87], v[204:207], v[228:231], v[84:87]
	v_mfma_f32_16x16x32_bf16 v[80:83], v[204:207], v[236:239], v[80:83]
	v_mfma_f32_16x16x32_bf16 v[76:79], v[212:215], v[228:231], v[76:79]
	v_mfma_f32_16x16x32_bf16 v[72:75], v[212:215], v[236:239], v[72:75]
	v_mfma_f32_16x16x32_bf16 v[68:71], v[220:223], v[228:231], v[68:71]
	v_mfma_f32_16x16x32_bf16 v[64:67], v[220:223], v[236:239], v[64:67]
	s_setprio 0
	v_add_u32_e32 v174, 0x8000, v159
	v_add_u32_e32 v175, 0xa000, v159
	v_readfirstlane_b32 s21, v174
	v_lshl_add_u64 v[176:177], v[248:249], 0, s[16:17]
	s_mov_b32 m0, s21
	v_readfirstlane_b32 s21, v175
	s_barrier
; #define LDA(dst, b, h) for (int m = 0; m < 4; ++m) for (int k = 0; k < 2; ++k) \
;     dst[m][k] = *reinterpret_cast<const bf16x8*>((char*)SA(b, h) + lds_byte(wr * 64 + m * 16 + fr, k * 32 + fq * 8))
; #define LDB(dst, b, h) for (int n = 0; n < 2; ++n) for (int k = 0; k < 2; ++k) \
;     dst[n][k] = *reinterpret_cast<const bf16x8*>((char*)SB(b, h) + lds_byte(wc * 32 + n * 16 + fr, k * 32 + fq * 8))
; #define MMA(ai, bj, At, Bq) do { __builtin_amdgcn_s_setprio(1); \
;     for (int m = 0; m < 4; ++m) for (int n = 0; n < 2; ++n) for (int k = 0; k < 2; ++k) \
;       acc[ai][bj][m][n] = __builtin_amdgcn_mfma_f32_16x16x32_bf16(At[m][k], Bq[n][k], acc[ai][bj][m][n], 0, 0, 0); \
;     __builtin_amdgcn_s_setprio(0); } while (0)
; #define WAIT_V(n) asm volatile("s_waitcnt vmcnt(" #n ")" ::: "memory")
; #define WAIT_L(n) asm volatile("s_waitcnt lgkmcnt(" #n ")" ::: "memory")
; #define BAR __builtin_amdgcn_s_barrier()
; #define SCHED __builtin_amdgcn_sched_barrier(0)
; template <class Epi>
; __device__ __forceinline__ void gemm_tile(const u16* __restrict__ A, const u16* __restrict__ Bt, int K,
;                                           int brow, int bcol, bool first, bool has_next, int nbrow, int nbcol, Epi epi) {
;     ...
;     LDA(At, 1, 1); STAGE(SA(1, 0), A, brow, t + 3);
;     BAR; WAIT_L(0); MMA(1, 0, At, B0); BAR; SCHED;
;     STAGE(SB(1, 1), Bt, bcol + HALF, t + 3);
;     WAIT_V(6); BAR; MMA(1, 1, At, B1); BAR;
;   }
;   { LDB(B0, 0, 0); LDA(At, 0, 0); STAGE(SA(1, 1), A, brow + HALF, nt - 1);
;     BAR; WAIT_L(0); MMA(0, 0, At, B0); BAR;
	ds_read_b128 v[196:199], v165 offset:49152
	ds_read_b128 v[200:203], v165 offset:50176
	ds_read_b128 v[204:207], v164 offset:49152
	ds_read_b128 v[208:211], v164 offset:50176
	ds_read_b128 v[212:215], v163 offset:49152
	ds_read_b128 v[216:219], v163 offset:50176
	ds_read_b128 v[220:223], v162 offset:49152
	ds_read_b128 v[240:243], v162 offset:50176
	global_load_lds_dwordx4 v[176:177], off
	v_lshl_add_u64 v[176:177], v[250:251], 0, s[16:17]
	s_mov_b32 m0, s21
	s_nop 0
	global_load_lds_dwordx4 v[176:177], off
	s_barrier
	s_waitcnt lgkmcnt(0)
	s_setprio 1
	v_mfma_f32_16x16x32_bf16 v[60:63], v[196:199], v[180:183], v[60:63]
	v_mfma_f32_16x16x32_bf16 v[56:59], v[196:199], v[188:191], v[56:59]
	v_mfma_f32_16x16x32_bf16 v[52:55], v[204:207], v[180:183], v[52:55]
	v_mfma_f32_16x16x32_bf16 v[48:51], v[204:207], v[188:191], v[48:51]
	v_mfma_f32_16x16x32_bf16 v[44:47], v[212:215], v[180:183], v[44:47]
	v_mfma_f32_16x16x32_bf16 v[40:43], v[212:215], v[188:191], v[40:43]
	v_mfma_f32_16x16x32_bf16 v[36:39], v[220:223], v[180:183], v[36:39]
	v_mfma_f32_16x16x32_bf16 v[32:35], v[220:223], v[188:191], v[32:35]
	v_mfma_f32_16x16x32_bf16 v[60:63], v[200:203], v[184:187], v[60:63]
	v_mfma_f32_16x16x32_bf16 v[56:59], v[200:203], v[192:195], v[56:59]
	v_mfma_f32_16x16x32_bf16 v[52:55], v[208:211], v[184:187], v[52:55]
	v_mfma_f32_16x16x32_bf16 v[48:51], v[208:211], v[192:195], v[48:51]
	v_mfma_f32_16x16x32_bf16 v[44:47], v[216:219], v[184:187], v[44:47]
	v_mfma_f32_16x16x32_bf16 v[40:43], v[216:219], v[192:195], v[40:43]
	v_mfma_f32_16x16x32_bf16 v[36:39], v[240:243], v[184:187], v[36:39]
	v_mfma_f32_16x16x32_bf16 v[32:35], v[240:243], v[192:195], v[32:35]
	s_setprio 0
	s_barrier
	v_add_u32_e32 v176, s85, v161
	v_add_u32_e32 v177, 0x2000, v176
	v_readfirstlane_b32 s21, v176
	v_lshl_add_u64 v[180:181], v[252:253], 0, s[14:15]
	s_mov_b32 m0, s21
	v_readfirstlane_b32 s21, v177
	global_load_lds_dwordx4 v[180:181], off
	v_lshl_add_u64 v[152:153], v[152:153], 0, s[14:15]
	s_mov_b32 m0, s21
	s_nop 0
	global_load_lds_dwordx4 v[152:153], off
	s_waitcnt vmcnt(6)
	s_barrier
	s_setprio 1
	v_mfma_f32_16x16x32_bf16 v[28:31], v[196:199], v[224:227], v[28:31]
	v_mfma_f32_16x16x32_bf16 v[24:27], v[196:199], v[232:235], v[24:27]
	v_mfma_f32_16x16x32_bf16 v[20:23], v[204:207], v[224:227], v[20:23]
	v_mfma_f32_16x16x32_bf16 v[16:19], v[204:207], v[232:235], v[16:19]
	v_mfma_f32_16x16x32_bf16 v[12:15], v[212:215], v[224:227], v[12:15]
	v_mfma_f32_16x16x32_bf16 v[8:11], v[212:215], v[232:235], v[8:11]
	v_mfma_f32_16x16x32_bf16 v[4:7], v[220:223], v[224:227], v[4:7]
	v_mfma_f32_16x16x32_bf16 v[0:3], v[220:223], v[232:235], v[0:3]
	v_mfma_f32_16x16x32_bf16 v[28:31], v[200:203], v[228:231], v[28:31]
	v_mfma_f32_16x16x32_bf16 v[24:27], v[200:203], v[236:239], v[24:27]
	v_mfma_f32_16x16x32_bf16 v[20:23], v[208:211], v[228:231], v[20:23]
	v_mfma_f32_16x16x32_bf16 v[16:19], v[208:211], v[236:239], v[16:19]
	v_mfma_f32_16x16x32_bf16 v[12:15], v[216:219], v[228:231], v[12:15]
	v_mfma_f32_16x16x32_bf16 v[8:11], v[216:219], v[236:239], v[8:11]
	v_mfma_f32_16x16x32_bf16 v[4:7], v[240:243], v[228:231], v[4:7]
	v_mfma_f32_16x16x32_bf16 v[0:3], v[240:243], v[236:239], v[0:3]
	s_setprio 0
	s_add_i32 s20, s20, 2
	s_add_u32 s18, s18, 0x100
	s_addc_u32 s19, s19, 0
	s_cmp_lt_u32 s20, 40
	s_barrier
	s_cbranch_scc1 .LBB0_663
	s_add_u32 s2, s34, s2
	s_addc_u32 s3, s35, s3
	s_add_u32 s2, s2, 0x1580
	s_addc_u32 s3, s3, 0
	v_readfirstlane_b32 s18, v178
	v_lshl_add_u64 v[152:153], s[2:3], 0, v[132:133]
	s_mov_b32 m0, s18
	ds_read_b128 v[136:139], v169
	ds_read_b128 v[140:143], v169 offset:1024
	ds_read_b128 v[144:147], v169 offset:2048
	ds_read_b128 v[148:151], v169 offset:3072
	ds_read_b128 v[180:183], v165
	ds_read_b128 v[184:187], v165 offset:1024
	ds_read_b128 v[188:191], v164
	ds_read_b128 v[192:195], v164 offset:1024
	ds_read_b128 v[196:199], v163
	ds_read_b128 v[200:203], v163 offset:1024
	ds_read_b128 v[204:207], v162
	ds_read_b128 v[208:211], v162 offset:1024
	global_load_lds_dwordx4 v[152:153], off
	v_lshl_add_u64 v[152:153], s[2:3], 0, v[134:135]
	v_readfirstlane_b32 s2, v179
	s_mov_b32 m0, s2
	s_nop 0
	global_load_lds_dwordx4 v[152:153], off
	s_barrier
	s_waitcnt lgkmcnt(0)
	s_setprio 1
	s_waitcnt lgkmcnt(0)
	v_mfma_f32_16x16x32_bf16 v[124:127], v[180:183], v[136:139], v[124:127]
	v_mfma_f32_16x16x32_bf16 v[120:123], v[180:183], v[144:147], v[120:123]
	v_mfma_f32_16x16x32_bf16 v[108:111], v[196:199], v[136:139], v[108:111]
	v_mfma_f32_16x16x32_bf16 v[104:107], v[196:199], v[144:147], v[104:107]
	v_mfma_f32_16x16x32_bf16 v[124:127], v[184:187], v[140:143], v[124:127]
	v_mfma_f32_16x16x32_bf16 v[120:123], v[184:187], v[148:151], v[120:123]
	v_mfma_f32_16x16x32_bf16 v[116:119], v[188:191], v[136:139], v[116:119]
	v_mfma_f32_16x16x32_bf16 v[112:115], v[188:191], v[144:147], v[112:115]
	v_mfma_f32_16x16x32_bf16 v[108:111], v[200:203], v[140:143], v[108:111]
	v_mfma_f32_16x16x32_bf16 v[104:107], v[200:203], v[148:151], v[104:107]
	v_mfma_f32_16x16x32_bf16 v[100:103], v[204:207], v[136:139], v[100:103]
	v_mfma_f32_16x16x32_bf16 v[96:99], v[204:207], v[144:147], v[96:99]
	v_mfma_f32_16x16x32_bf16 v[212:215], v[192:195], v[140:143], v[116:119]
	v_mfma_f32_16x16x32_bf16 v[216:219], v[192:195], v[148:151], v[112:115]
	v_mfma_f32_16x16x32_bf16 v[220:223], v[208:211], v[140:143], v[100:103]
	v_mfma_f32_16x16x32_bf16 v[224:227], v[208:211], v[148:151], v[96:99]
	s_setprio 0
	s_barrier
	s_nop 1
	ds_read_b128 v[96:99], v168
	ds_read_b128 v[100:103], v168 offset:1024
	ds_read_b128 v[112:115], v168 offset:2048
	ds_read_b128 v[116:119], v168 offset:3072
	s_barrier
; #define LDA(dst, b, h) for (int m = 0; m < 4; ++m) for (int k = 0; k < 2; ++k) \
;     dst[m][k] = *reinterpret_cast<const bf16x8*>((char*)SA(b, h) + lds_byte(wr * 64 + m * 16 + fr, k * 32 + fq * 8))
; #define LDB(dst, b, h) for (int n = 0; n < 2; ++n) for (int k = 0; k < 2; ++k) \
;     dst[n][k] = *reinterpret_cast<const bf16x8*>((char*)SB(b, h) + lds_byte(wc * 32 + n * 16 + fr, k * 32 + fq * 8))
; #define MMA(ai, bj, At, Bq) do { __builtin_amdgcn_s_setprio(1); \
;     for (int m = 0; m < 4; ++m) for (int n = 0; n < 2; ++n) for (int k = 0; k < 2; ++k) \
;       acc[ai][bj][m][n] = __builtin_amdgcn_mfma_f32_16x16x32_bf16(At[m][k], Bq[n][k], acc[ai][bj][m][n], 0, 0, 0); \
;     __builtin_amdgcn_s_setprio(0); } while (0)
; #define WAIT_V(n) asm volatile("s_waitcnt vmcnt(" #n ")" ::: "memory")
; #define WAIT_L(n) asm volatile("s_waitcnt lgkmcnt(" #n ")" ::: "memory")
; #define BAR __builtin_amdgcn_s_barrier()
; template <class Epi>
; __device__ __forceinline__ void gemm_tile(const u16* __restrict__ A, const u16* __restrict__ Bt, int K,
;                                           int brow, int bcol, bool first, bool has_next, int nbrow, int nbcol, Epi epi) {
;     ...
;     BAR; WAIT_L(0); MMA(0, 0, At, B0); BAR;
;     LDB(B1, 0, 1); BAR; WAIT_L(0); MMA(0, 1, At, B1); BAR;
;     LDA(At, 0, 1); WAIT_V(4); BAR; WAIT_L(0); MMA(1, 0, At, B0); MMA(1, 1, At, B1); BAR; }
;   { LDB(B0, 1, 0); LDA(At, 1, 0); WAIT_V(2); BAR; WAIT_L(0); MMA(0, 0, At, B0); BAR;
	s_waitcnt lgkmcnt(0)
	s_setprio 1
	s_waitcnt lgkmcnt(0)
	v_mfma_f32_16x16x32_bf16 v[92:95], v[180:183], v[96:99], v[92:95]
	v_mfma_f32_16x16x32_bf16 v[88:91], v[180:183], v[112:115], v[88:91]
	v_mfma_f32_16x16x32_bf16 v[76:79], v[196:199], v[96:99], v[76:79]
	v_mfma_f32_16x16x32_bf16 v[72:75], v[196:199], v[112:115], v[72:75]
	v_mfma_f32_16x16x32_bf16 v[92:95], v[184:187], v[100:103], v[92:95]
	v_mfma_f32_16x16x32_bf16 v[88:91], v[184:187], v[116:119], v[88:91]
	v_mfma_f32_16x16x32_bf16 v[84:87], v[188:191], v[96:99], v[84:87]
	v_mfma_f32_16x16x32_bf16 v[80:83], v[188:191], v[112:115], v[80:83]
	v_mfma_f32_16x16x32_bf16 v[76:79], v[200:203], v[100:103], v[76:79]
	v_mfma_f32_16x16x32_bf16 v[72:75], v[200:203], v[116:119], v[72:75]
	v_mfma_f32_16x16x32_bf16 v[68:71], v[204:207], v[96:99], v[68:71]
	v_mfma_f32_16x16x32_bf16 v[64:67], v[204:207], v[112:115], v[64:67]
	v_mfma_f32_16x16x32_bf16 v[178:181], v[192:195], v[100:103], v[84:87]
	v_mfma_f32_16x16x32_bf16 v[182:185], v[192:195], v[116:119], v[80:83]
	v_mfma_f32_16x16x32_bf16 v[186:189], v[208:211], v[100:103], v[68:71]
	v_mfma_f32_16x16x32_bf16 v[190:193], v[208:211], v[116:119], v[64:67]
	s_setprio 0
	s_barrier
	s_nop 1
	ds_read_b128 v[64:67], v165 offset:16384
	ds_read_b128 v[68:71], v165 offset:17408
	ds_read_b128 v[80:83], v164 offset:16384
	ds_read_b128 v[84:87], v164 offset:17408
	ds_read_b128 v[194:197], v163 offset:16384
	ds_read_b128 v[198:201], v163 offset:17408
	ds_read_b128 v[202:205], v162 offset:16384
	ds_read_b128 v[206:209], v162 offset:17408
	s_waitcnt vmcnt(4)
	s_barrier
	s_waitcnt lgkmcnt(0)
	s_setprio 1
	s_waitcnt lgkmcnt(0)
	v_mfma_f32_16x16x32_bf16 v[60:63], v[64:67], v[136:139], v[60:63]
	v_mfma_f32_16x16x32_bf16 v[56:59], v[64:67], v[144:147], v[56:59]
	v_mfma_f32_16x16x32_bf16 v[44:47], v[194:197], v[136:139], v[44:47]
	v_mfma_f32_16x16x32_bf16 v[40:43], v[194:197], v[144:147], v[40:43]
	v_mfma_f32_16x16x32_bf16 v[60:63], v[68:71], v[140:143], v[60:63]
	v_mfma_f32_16x16x32_bf16 v[56:59], v[68:71], v[148:151], v[56:59]
	v_mfma_f32_16x16x32_bf16 v[52:55], v[80:83], v[136:139], v[52:55]
	v_mfma_f32_16x16x32_bf16 v[48:51], v[80:83], v[144:147], v[48:51]
	v_mfma_f32_16x16x32_bf16 v[44:47], v[198:201], v[140:143], v[44:47]
	v_mfma_f32_16x16x32_bf16 v[40:43], v[198:201], v[148:151], v[40:43]
	v_mfma_f32_16x16x32_bf16 v[36:39], v[202:205], v[136:139], v[36:39]
	v_mfma_f32_16x16x32_bf16 v[32:35], v[202:205], v[144:147], v[32:35]
	v_mfma_f32_16x16x32_bf16 v[228:231], v[84:87], v[140:143], v[52:55]
	v_mfma_f32_16x16x32_bf16 v[232:235], v[84:87], v[148:151], v[48:51]
	v_mfma_f32_16x16x32_bf16 v[136:139], v[206:209], v[140:143], v[36:39]
	v_mfma_f32_16x16x32_bf16 v[140:143], v[206:209], v[148:151], v[32:35]
	s_setprio 0
	s_setprio 1
	v_mfma_f32_16x16x32_bf16 v[28:31], v[64:67], v[96:99], v[28:31]
	v_mfma_f32_16x16x32_bf16 v[24:27], v[64:67], v[112:115], v[24:27]
	v_mfma_f32_16x16x32_bf16 v[12:15], v[194:197], v[96:99], v[12:15]
	v_mfma_f32_16x16x32_bf16 v[8:11], v[194:197], v[112:115], v[8:11]
	v_mfma_f32_16x16x32_bf16 v[28:31], v[68:71], v[100:103], v[28:31]
	v_mfma_f32_16x16x32_bf16 v[24:27], v[68:71], v[116:119], v[24:27]
	v_mfma_f32_16x16x32_bf16 v[20:23], v[80:83], v[96:99], v[20:23]
	v_mfma_f32_16x16x32_bf16 v[16:19], v[80:83], v[112:115], v[16:19]
	v_mfma_f32_16x16x32_bf16 v[12:15], v[198:201], v[100:103], v[12:15]
	v_mfma_f32_16x16x32_bf16 v[8:11], v[198:201], v[116:119], v[8:11]
	v_mfma_f32_16x16x32_bf16 v[4:7], v[202:205], v[96:99], v[4:7]
	v_mfma_f32_16x16x32_bf16 v[0:3], v[202:205], v[112:115], v[0:3]
	v_mfma_f32_16x16x32_bf16 v[144:147], v[84:87], v[100:103], v[20:23]
	v_mfma_f32_16x16x32_bf16 v[148:151], v[84:87], v[116:119], v[16:19]
	v_mfma_f32_16x16x32_bf16 v[194:197], v[206:209], v[100:103], v[4:7]
	v_mfma_f32_16x16x32_bf16 v[198:201], v[206:209], v[116:119], v[0:3]
	s_setprio 0
	s_barrier
	s_nop 1
	ds_read_b128 v[0:3], v167
	ds_read_b128 v[4:7], v167 offset:1024
	ds_read_b128 v[202:205], v167 offset:2048
	ds_read_b128 v[206:209], v167 offset:3072
	ds_read_b128 v[16:19], v165 offset:32768
	ds_read_b128 v[20:23], v165 offset:33792
	ds_read_b128 v[32:35], v164 offset:32768
	ds_read_b128 v[36:39], v164 offset:33792
	ds_read_b128 v[48:51], v163 offset:32768
	ds_read_b128 v[52:55], v163 offset:33792
	ds_read_b128 v[236:239], v162 offset:32768
	ds_read_b128 v[240:243], v162 offset:33792
	s_waitcnt vmcnt(2)
	s_barrier
; #define LDA(dst, b, h) for (int m = 0; m < 4; ++m) for (int k = 0; k < 2; ++k) \
;     dst[m][k] = *reinterpret_cast<const bf16x8*>((char*)SA(b, h) + lds_byte(wr * 64 + m * 16 + fr, k * 32 + fq * 8))
; #define LDB(dst, b, h) for (int n = 0; n < 2; ++n) for (int k = 0; k < 2; ++k) \
;     dst[n][k] = *reinterpret_cast<const bf16x8*>((char*)SB(b, h) + lds_byte(wc * 32 + n * 16 + fr, k * 32 + fq * 8))
; #define MMA(ai, bj, At, Bq) do { __builtin_amdgcn_s_setprio(1); \
;     for (int m = 0; m < 4; ++m) for (int n = 0; n < 2; ++n) for (int k = 0; k < 2; ++k) \
;       acc[ai][bj][m][n] = __builtin_amdgcn_mfma_f32_16x16x32_bf16(At[m][k], Bq[n][k], acc[ai][bj][m][n], 0, 0, 0); \
;     __builtin_amdgcn_s_setprio(0); } while (0)
; #define WAIT_V(n) asm volatile("s_waitcnt vmcnt(" #n ")" ::: "memory")
; #define WAIT_L(n) asm volatile("s_waitcnt lgkmcnt(" #n ")" ::: "memory")
; #define BAR __builtin_amdgcn_s_barrier()
; template <class Epi>
; __device__ __forceinline__ void gemm_tile(const u16* __restrict__ A, const u16* __restrict__ Bt, int K,
;                                           int brow, int bcol, bool first, bool has_next, int nbrow, int nbcol, Epi epi) {
;     ...
;   { LDB(B0, 1, 0); LDA(At, 1, 0); WAIT_V(2); BAR; WAIT_L(0); MMA(0, 0, At, B0); BAR;
;     LDB(B1, 1, 1); WAIT_V(0); BAR; WAIT_L(0); MMA(0, 1, At, B1); BAR;
;     LDA(At, 1, 1); BAR; WAIT_L(0); MMA(1, 0, At, B0); MMA(1, 1, At, B1); BAR; }
;   if (wr == 0) BAR;
	s_waitcnt lgkmcnt(0)
	s_setprio 1
	s_waitcnt lgkmcnt(0)
	v_mfma_f32_16x16x32_bf16 v[64:67], v[16:19], v[0:3], v[124:127]
	v_mfma_f32_16x16x32_bf16 v[112:115], v[20:23], v[4:7], v[64:67]
	v_mfma_f32_16x16x32_bf16 v[64:67], v[16:19], v[202:205], v[120:123]
	v_mfma_f32_16x16x32_bf16 v[116:119], v[20:23], v[206:209], v[64:67]
	v_mfma_f32_16x16x32_bf16 v[64:67], v[32:35], v[0:3], v[212:215]
	v_mfma_f32_16x16x32_bf16 v[96:99], v[36:39], v[4:7], v[64:67]
	v_mfma_f32_16x16x32_bf16 v[64:67], v[32:35], v[202:205], v[216:219]
	v_mfma_f32_16x16x32_bf16 v[100:103], v[36:39], v[206:209], v[64:67]
	v_mfma_f32_16x16x32_bf16 v[64:67], v[48:51], v[0:3], v[108:111]
	v_mfma_f32_16x16x32_bf16 v[80:83], v[52:55], v[4:7], v[64:67]
	v_mfma_f32_16x16x32_bf16 v[64:67], v[48:51], v[202:205], v[104:107]
	v_mfma_f32_16x16x32_bf16 v[84:87], v[52:55], v[206:209], v[64:67]
	v_mfma_f32_16x16x32_bf16 v[64:67], v[236:239], v[0:3], v[220:223]
	v_mfma_f32_16x16x32_bf16 v[68:71], v[236:239], v[202:205], v[224:227]
	v_mfma_f32_16x16x32_bf16 v[64:67], v[240:243], v[4:7], v[64:67]
	v_mfma_f32_16x16x32_bf16 v[68:71], v[240:243], v[206:209], v[68:71]
	s_setprio 0
	s_barrier
	ds_read_b128 v[210:213], v166
	ds_read_b128 v[214:217], v166 offset:1024
	ds_read_b128 v[218:221], v166 offset:2048
	ds_read_b128 v[166:169], v166 offset:3072
	s_waitcnt vmcnt(0)
	s_barrier
	s_waitcnt lgkmcnt(0)
	s_setprio 1
	s_waitcnt lgkmcnt(0)
	v_mfma_f32_16x16x32_bf16 v[92:95], v[16:19], v[210:213], v[92:95]
	v_mfma_f32_16x16x32_bf16 v[16:19], v[16:19], v[218:221], v[88:91]
	v_mfma_f32_16x16x32_bf16 v[120:123], v[20:23], v[166:169], v[16:19]
	v_mfma_f32_16x16x32_bf16 v[16:19], v[32:35], v[210:213], v[178:181]
	v_mfma_f32_16x16x32_bf16 v[108:111], v[36:39], v[214:217], v[16:19]
	v_mfma_f32_16x16x32_bf16 v[16:19], v[32:35], v[218:221], v[182:185]
	v_mfma_f32_16x16x32_bf16 v[104:107], v[36:39], v[166:169], v[16:19]
	v_mfma_f32_16x16x32_bf16 v[16:19], v[48:51], v[210:213], v[76:79]
	v_mfma_f32_16x16x32_bf16 v[124:127], v[20:23], v[214:217], v[92:95]
	v_mfma_f32_16x16x32_bf16 v[92:95], v[52:55], v[214:217], v[16:19]
	v_mfma_f32_16x16x32_bf16 v[16:19], v[48:51], v[218:221], v[72:75]
	v_mfma_f32_16x16x32_bf16 v[88:91], v[52:55], v[166:169], v[16:19]
	v_mfma_f32_16x16x32_bf16 v[16:19], v[236:239], v[210:213], v[186:189]
	v_mfma_f32_16x16x32_bf16 v[76:79], v[240:243], v[214:217], v[16:19]
	v_mfma_f32_16x16x32_bf16 v[16:19], v[236:239], v[218:221], v[190:193]
	v_mfma_f32_16x16x32_bf16 v[72:75], v[240:243], v[166:169], v[16:19]
	s_setprio 0
	s_barrier
	ds_read_b128 v[178:181], v165 offset:49152
	ds_read_b128 v[182:185], v165 offset:50176
	ds_read_b128 v[186:189], v164 offset:49152
	ds_read_b128 v[190:193], v164 offset:50176
	ds_read_b128 v[222:225], v163 offset:49152
	ds_read_b128 v[236:239], v163 offset:50176
	ds_read_b128 v[240:243], v162 offset:49152
	ds_read_b128 v[162:165], v162 offset:50176
	s_barrier
	s_waitcnt lgkmcnt(0)
	s_setprio 1
	s_waitcnt lgkmcnt(0)
	v_mfma_f32_16x16x32_bf16 v[16:19], v[178:181], v[0:3], v[60:63]
	v_mfma_f32_16x16x32_bf16 v[48:51], v[182:185], v[4:7], v[16:19]
	v_mfma_f32_16x16x32_bf16 v[16:19], v[178:181], v[202:205], v[56:59]
	v_mfma_f32_16x16x32_bf16 v[52:55], v[182:185], v[206:209], v[16:19]
	v_mfma_f32_16x16x32_bf16 v[16:19], v[186:189], v[0:3], v[228:231]
	v_mfma_f32_16x16x32_bf16 v[32:35], v[190:193], v[4:7], v[16:19]
	v_mfma_f32_16x16x32_bf16 v[16:19], v[186:189], v[202:205], v[232:235]
	v_mfma_f32_16x16x32_bf16 v[36:39], v[190:193], v[206:209], v[16:19]
	v_mfma_f32_16x16x32_bf16 v[16:19], v[222:225], v[0:3], v[44:47]
	v_mfma_f32_16x16x32_bf16 v[0:3], v[240:243], v[0:3], v[136:139]
	v_mfma_f32_16x16x32_bf16 v[16:19], v[236:239], v[4:7], v[16:19]
	v_mfma_f32_16x16x32_bf16 v[20:23], v[222:225], v[202:205], v[40:43]
	v_mfma_f32_16x16x32_bf16 v[0:3], v[162:165], v[4:7], v[0:3]
	v_mfma_f32_16x16x32_bf16 v[4:7], v[240:243], v[202:205], v[140:143]
	v_mfma_f32_16x16x32_bf16 v[20:23], v[236:239], v[206:209], v[20:23]
	v_mfma_f32_16x16x32_bf16 v[4:7], v[162:165], v[206:209], v[4:7]
	s_setprio 0
	s_setprio 1
	v_mfma_f32_16x16x32_bf16 v[24:27], v[178:181], v[218:221], v[24:27]
	v_mfma_f32_16x16x32_bf16 v[56:59], v[182:185], v[166:169], v[24:27]
	v_mfma_f32_16x16x32_bf16 v[24:27], v[186:189], v[210:213], v[144:147]
	v_mfma_f32_16x16x32_bf16 v[44:47], v[190:193], v[214:217], v[24:27]
	v_mfma_f32_16x16x32_bf16 v[24:27], v[186:189], v[218:221], v[148:151]
	v_mfma_f32_16x16x32_bf16 v[8:11], v[222:225], v[218:221], v[8:11]
	v_mfma_f32_16x16x32_bf16 v[28:31], v[178:181], v[210:213], v[28:31]
	v_mfma_f32_16x16x32_bf16 v[40:43], v[190:193], v[166:169], v[24:27]
	v_mfma_f32_16x16x32_bf16 v[12:15], v[222:225], v[210:213], v[12:15]
	v_mfma_f32_16x16x32_bf16 v[24:27], v[236:239], v[166:169], v[8:11]
	v_mfma_f32_16x16x32_bf16 v[8:11], v[240:243], v[210:213], v[194:197]
	v_mfma_f32_16x16x32_bf16 v[60:63], v[182:185], v[214:217], v[28:31]
	v_mfma_f32_16x16x32_bf16 v[28:31], v[236:239], v[214:217], v[12:15]
	v_mfma_f32_16x16x32_bf16 v[12:15], v[162:165], v[214:217], v[8:11]
	v_mfma_f32_16x16x32_bf16 v[8:11], v[240:243], v[218:221], v[198:201]
	v_mfma_f32_16x16x32_bf16 v[8:11], v[162:165], v[166:169], v[8:11]
	s_setprio 0
	v_cmp_gt_u32_e32 vcc, s42, v129
	s_barrier
	s_and_saveexec_b64 s[2:3], vcc
	s_cbranch_execz .LBB0_666
	s_barrier
